# pipelined residual-GEMM epilogue loads, pipelined compress K loop, LDS read hoisting in FoX/NSA attention loops, DPP wave-max in top-k
# speedup vs baseline: 1.0262x; 1.0262x over previous
; __device__ __forceinline__ f32x16 mfma32(bf16x8 a, bf16x8 b, f32x16 c) { return __builtin_amdgcn_mfma_f32_32x32x16_bf16(a, b, c, 0, 0, 0); }
; __device__ __forceinline__ s16x4 tr16(lptr p) { return __builtin_bit_cast(s16x4, __builtin_amdgcn_ds_read_tr16_b64_v4i16((LAS v4i16_t*)p)); }
; template <int MODE> ...
;     ...
;         const lptr Kt = L + A_KT + buf * 9216, Vt = L + A_VT + vcur * 12288;
;         f32x16 s0, s1;
; #pragma unroll
;         for (int s4 = 0; s4 < 4; ++s4) {
;             const bf16x8 a0 = lds_ld<bf16x8>(Kt + n * KP + s4 * 32 + hl * 16);
;             const bf16x8 a1 = lds_ld<bf16x8>(Kt + (32 + n) * KP + s4 * 32 + hl * 16);
;             if (s4 == 0) { s0 = mfma32(a0, qf[0], negm); s1 = mfma32(a1, qf[0], negm); }
;             else { s0 = mfma32(a0, qf[s4], s0); s1 = mfma32(a1, qf[s4], s1); }
;         }
;         const int kbase = 64 * kt + 4 * hl;
;         const bool far = (MODE == MODE_WIN || MODE == MODE_SEL) ? (wtmin - (64 * kt + 63) >= 128) : false;
;         const bool fmask = (MODE == MODE_FOX) ? (64 * kt + 63 > wtmin) : false;
;         const bool clean = (MODE == MODE_WIN) ? (far && (wtmax - 64 * kt < W)) : false;
;         const float mref = (MODE == MODE_CMP2) ? mfix : ((m == -INFINITY) ? 0.f : m);
;         if (MODE == MODE_FOX) {
; #pragma unroll
;             for (int kb = 0; kb < 2; ++kb)
; #pragma unroll
;                 for (int a = 0; a < 4; ++a) {
;                     const f32x4 c4 = lds_ld<f32x4>(L + A_CB + buf * 256 + (32 * kb + 8 * a + 4 * hl) * 4);
; #pragma unroll
;                     for (int e = 0; e < 4; ++e) { const int r = 4 * a + e; if (kb) s1[r] = s1[r] * SC2 + c4[e]; else s0[r] = s0[r] * SC2 + c4[e]; }
;                 }
;             if (__builtin_amdgcn_readfirstlane((int)fmask)) {
;     ...
;             const lptr vb_ = Vt + (4 * hl + q4) * VP + 32 * blk + 8 * p4;
; #pragma unroll
;             for (int c_ = 0; c_ < 2; ++c_)
; #pragma unroll
;                 for (int ks_ = 0; ks_ < 4; ++ks_) {
;                     const s16x4 lo_ = tr16(vb_ + (16 * ks_) * VP + 64 * c_), hi_ = tr16(vb_ + (16 * ks_ + 8) * VP + 64 * c_);
.LBB0_178:
	v_add_u32_e32 v14, v134, v135
	v_add_u32_e32 v0, v136, v135
	v_add_u32_e32 v156, v138, v139
	ds_read_b128 v[170:173], v14 offset:0
	ds_read_b128 v[174:177], v0 offset:0
	ds_read_b128 v[178:181], v14 offset:32
	ds_read_b128 v[182:185], v0 offset:32
	ds_read_b128 v[186:189], v14 offset:64
	ds_read_b128 v[194:197], v0 offset:64
	ds_read_b128 v[198:201], v14 offset:96
	ds_read_b128 v[202:205], v0 offset:96
	s_or_b32 s1, s0, 63
	v_cmp_gt_i32_e32 vcc, s1, v125
	s_waitcnt lgkmcnt(7)
	v_mfma_f32_32x32x16_bf16 v[80:95], v[170:173], v[104:107], v[48:63]
	ds_read_b64_tr_b16 v[206:207], v156 offset:18432
	ds_read_b64_tr_b16 v[208:209], v156 offset:19968
	s_waitcnt lgkmcnt(8)
	v_mfma_f32_32x32x16_bf16 v[64:79], v[174:177], v[104:107], v[48:63]
	ds_read_b64_tr_b16 v[210:211], v156 offset:21504
	ds_read_b64_tr_b16 v[212:213], v156 offset:23040
	s_waitcnt lgkmcnt(9)
	v_mfma_f32_32x32x16_bf16 v[80:95], v[178:181], v[96:99], v[80:95]
	ds_read_b64_tr_b16 v[226:227], v156 offset:24576
	ds_read_b64_tr_b16 v[228:229], v156 offset:26112
	s_waitcnt lgkmcnt(10)
	v_mfma_f32_32x32x16_bf16 v[64:79], v[182:185], v[96:99], v[64:79]
	ds_read_b64_tr_b16 v[230:231], v156 offset:27648
	ds_read_b64_tr_b16 v[232:233], v156 offset:29184
	s_waitcnt lgkmcnt(11)
	v_mfma_f32_32x32x16_bf16 v[80:95], v[186:189], v[100:103], v[80:95]
	ds_read_b64_tr_b16 v[234:235], v156 offset:18496
	ds_read_b64_tr_b16 v[236:237], v156 offset:20032
	s_waitcnt lgkmcnt(12)
	v_mfma_f32_32x32x16_bf16 v[64:79], v[194:197], v[100:103], v[64:79]
	ds_read_b64_tr_b16 v[238:239], v156 offset:21568
	ds_read_b64_tr_b16 v[240:241], v156 offset:23104
	v_cndmask_b32_e64 v0, 0, 1, vcc
	s_nop 0
	v_readfirstlane_b32 s1, v0
	s_bitcmp0_b32 s1, 0
	s_waitcnt lgkmcnt(13)
	v_mfma_f32_32x32x16_bf16 v[80:95], v[198:201], v[108:111], v[80:95]
	ds_read_b64_tr_b16 v[242:243], v156 offset:24640
	ds_read_b64_tr_b16 v[244:245], v156 offset:26176
	s_waitcnt lgkmcnt(14)
	v_mfma_f32_32x32x16_bf16 v[64:79], v[202:205], v[108:111], v[64:79]
	ds_read_b64_tr_b16 v[246:247], v156 offset:27712
	ds_read_b64_tr_b16 v[248:249], v156 offset:29248
	ds_read_b128 v[144:147], v135 offset:43008
	ds_read_b128 v[148:151], v135 offset:43040
	ds_read_b128 v[152:155], v135 offset:43072
	ds_read_b128 v[12:15], v135 offset:43104
	s_waitcnt lgkmcnt(3)
	s_nop 5
	v_pk_fma_f32 v[82:83], v[82:83], s[54:55], v[146:147] op_sel_hi:[1,0,1]
	s_waitcnt lgkmcnt(2)
	v_pk_fma_f32 v[86:87], v[86:87], s[54:55], v[150:151] op_sel_hi:[1,0,1]
	s_waitcnt lgkmcnt(1)
	v_pk_fma_f32 v[88:89], v[88:89], s[54:55], v[152:153] op_sel_hi:[1,0,1]
	s_waitcnt lgkmcnt(0)
	v_pk_fma_f32 v[10:11], v[94:95], s[54:55], v[14:15] op_sel_hi:[1,0,1]
	v_pk_fma_f32 v[12:13], v[92:93], s[54:55], v[12:13] op_sel_hi:[1,0,1]
	v_pk_fma_f32 v[14:15], v[90:91], s[54:55], v[154:155] op_sel_hi:[1,0,1]
	v_pk_fma_f32 v[84:85], v[84:85], s[54:55], v[148:149] op_sel_hi:[1,0,1]
	v_pk_fma_f32 v[80:81], v[80:81], s[54:55], v[144:145] op_sel_hi:[1,0,1]
	ds_read_b128 v[90:93], v135 offset:43136
	ds_read_b128 v[144:147], v135 offset:43168
	ds_read_b128 v[148:151], v135 offset:43200
	ds_read_b128 v[152:155], v135 offset:43232
	s_waitcnt lgkmcnt(3)
	v_pk_fma_f32 v[66:67], v[66:67], s[54:55], v[92:93] op_sel_hi:[1,0,1]
	s_waitcnt lgkmcnt(2)
	v_pk_fma_f32 v[70:71], v[70:71], s[54:55], v[146:147] op_sel_hi:[1,0,1]
	s_waitcnt lgkmcnt(1)
	v_pk_fma_f32 v[74:75], v[74:75], s[54:55], v[150:151] op_sel_hi:[1,0,1]
	s_waitcnt lgkmcnt(0)
	v_pk_fma_f32 v[78:79], v[78:79], s[54:55], v[154:155] op_sel_hi:[1,0,1]
	v_pk_fma_f32 v[76:77], v[76:77], s[54:55], v[152:153] op_sel_hi:[1,0,1]
	v_pk_fma_f32 v[72:73], v[72:73], s[54:55], v[148:149] op_sel_hi:[1,0,1]
	v_pk_fma_f32 v[68:69], v[68:69], s[54:55], v[144:145] op_sel_hi:[1,0,1]
	v_pk_fma_f32 v[64:65], v[64:65], s[54:55], v[90:91] op_sel_hi:[1,0,1]
	s_cbranch_scc1 .LBB0_180
; template <int MODE> ...
;     ...
;             if (__builtin_amdgcn_readfirstlane((int)fmask)) {
; #pragma unroll
;                 for (int r = 0; r < 16; ++r) {
;                     const int key = kbase + 8 * (r >> 2) + (r & 3);
;                     if (key > t) s0[r] = -INFINITY;
;                     if (key + 32 > t) s1[r] = -INFINITY;
;                 }
;             }
	v_or_b32_e32 v0, s0, v137
	v_or_b32_e32 v90, 32, v0
	v_cmp_le_i32_e32 vcc, v90, v126
	v_or_b32_e32 v90, 33, v0
	s_nop 0
	v_cndmask_b32_e32 v64, v220, v64, vcc
	v_cmp_lt_i32_e32 vcc, v0, v126
	s_nop 1
	v_cndmask_b32_e32 v81, v220, v81, vcc
	v_cmp_le_i32_e32 vcc, v0, v126
	s_nop 1
	v_cndmask_b32_e32 v80, v220, v80, vcc
	v_cmp_le_i32_e32 vcc, v90, v126
	v_or_b32_e32 v90, 2, v0
	s_nop 0
	v_cndmask_b32_e32 v65, v220, v65, vcc
	v_cmp_le_i32_e32 vcc, v90, v126
	v_or_b32_e32 v90, 34, v0
	s_nop 0
	v_cndmask_b32_e32 v82, v220, v82, vcc
	v_cmp_le_i32_e32 vcc, v90, v126
	v_or_b32_e32 v90, 3, v0
	s_nop 0
	v_cndmask_b32_e32 v66, v220, v66, vcc
	v_cmp_le_i32_e32 vcc, v90, v126
	v_or_b32_e32 v90, 35, v0
	s_nop 0
	v_cndmask_b32_e32 v83, v220, v83, vcc
	v_cmp_le_i32_e32 vcc, v90, v126
	v_or_b32_e32 v90, 8, v0
	s_nop 0
	v_cndmask_b32_e32 v67, v220, v67, vcc
	v_cmp_le_i32_e32 vcc, v90, v126
	v_or_b32_e32 v90, 40, v0
	s_nop 0
	v_cndmask_b32_e32 v84, v220, v84, vcc
	v_cmp_le_i32_e32 vcc, v90, v126
	v_or_b32_e32 v90, 9, v0
	s_nop 0
	v_cndmask_b32_e32 v68, v220, v68, vcc
	v_cmp_le_i32_e32 vcc, v90, v126
	v_or_b32_e32 v90, 41, v0
	s_nop 0
	v_cndmask_b32_e32 v85, v220, v85, vcc
	v_cmp_le_i32_e32 vcc, v90, v126
	v_or_b32_e32 v90, 10, v0
	s_nop 0
	v_cndmask_b32_e32 v69, v220, v69, vcc
	v_cmp_le_i32_e32 vcc, v90, v126
	v_or_b32_e32 v90, 42, v0
	s_nop 0
	v_cndmask_b32_e32 v86, v220, v86, vcc
	v_cmp_le_i32_e32 vcc, v90, v126
	v_or_b32_e32 v90, 11, v0
	s_nop 0
	v_cndmask_b32_e32 v70, v220, v70, vcc
	v_cmp_le_i32_e32 vcc, v90, v126
	v_or_b32_e32 v90, 43, v0
	s_nop 0
	v_cndmask_b32_e32 v87, v220, v87, vcc
	v_cmp_le_i32_e32 vcc, v90, v126
	v_or_b32_e32 v90, 16, v0
	s_nop 0
	v_cndmask_b32_e32 v71, v220, v71, vcc
	v_cmp_le_i32_e32 vcc, v90, v126
	v_or_b32_e32 v90, 48, v0
	s_nop 0
	v_cndmask_b32_e32 v88, v220, v88, vcc
	v_cmp_le_i32_e32 vcc, v90, v126
	v_or_b32_e32 v90, 17, v0
	s_nop 0
	v_cndmask_b32_e32 v72, v220, v72, vcc
	v_cmp_le_i32_e32 vcc, v90, v126
	v_or_b32_e32 v90, 49, v0
	s_nop 0
	v_cndmask_b32_e32 v89, v220, v89, vcc
	v_cmp_le_i32_e32 vcc, v90, v126
	v_or_b32_e32 v90, 18, v0
	s_nop 0
	v_cndmask_b32_e32 v73, v220, v73, vcc
	v_cmp_le_i32_e32 vcc, v90, v126
	v_or_b32_e32 v90, 50, v0
	s_nop 0
	v_cndmask_b32_e32 v14, v220, v14, vcc
	v_cmp_le_i32_e32 vcc, v90, v126
	v_or_b32_e32 v90, 19, v0
	s_nop 0
	v_cndmask_b32_e32 v74, v220, v74, vcc
	v_cmp_le_i32_e32 vcc, v90, v126
	v_or_b32_e32 v90, 51, v0
	s_nop 0
	v_cndmask_b32_e32 v15, v220, v15, vcc
	v_cmp_le_i32_e32 vcc, v90, v126
	v_or_b32_e32 v90, 24, v0
	s_nop 0
	v_cndmask_b32_e32 v75, v220, v75, vcc
	v_cmp_le_i32_e32 vcc, v90, v126
	v_or_b32_e32 v90, 56, v0
	s_nop 0
	v_cndmask_b32_e32 v12, v220, v12, vcc
	v_cmp_le_i32_e32 vcc, v90, v126
	v_or_b32_e32 v90, 25, v0
	s_nop 0
	v_cndmask_b32_e32 v76, v220, v76, vcc
	v_cmp_le_i32_e32 vcc, v90, v126
	v_or_b32_e32 v90, 57, v0
	s_nop 0
	v_cndmask_b32_e32 v13, v220, v13, vcc
	v_cmp_le_i32_e32 vcc, v90, v126
	v_or_b32_e32 v90, 26, v0
	s_nop 0
	v_cndmask_b32_e32 v77, v220, v77, vcc
	v_cmp_le_i32_e32 vcc, v90, v126
	v_or_b32_e32 v90, 58, v0
	s_nop 0
	v_cndmask_b32_e32 v10, v220, v10, vcc
	v_cmp_le_i32_e32 vcc, v90, v126
	v_or_b32_e32 v90, 27, v0
	v_or_b32_e32 v0, 59, v0
	v_cndmask_b32_e32 v78, v220, v78, vcc
	v_cmp_le_i32_e32 vcc, v90, v126
	s_nop 1
	v_cndmask_b32_e32 v11, v220, v11, vcc
	v_cmp_le_i32_e32 vcc, v0, v126
	s_nop 1
	v_cndmask_b32_e32 v79, v220, v79, vcc

; template <int MODE> ...
;     ...
;             float ps = 0.f;
; #pragma unroll
;             for (int r = 0; r < 16; ++r) { s0[r] = ex2(s0[r]); s1[r] = ex2(s1[r]); ps += s0[r] + s1[r]; }
;             l += ps;
;         } else {
; #pragma unroll
;             for (int r = 0; r < 16; ++r) { s0[r] = ex2(s0[r]) * linv; s1[r] = ex2(s1[r]) * linv; }
;             float quad[8], last[8], recv[8];
; #pragma unroll
;             for (int a = 0; a < 4; ++a) {
;                 quad[a] = (s0[4 * a] + s0[4 * a + 1]) + (s0[4 * a + 2] + s0[4 * a + 3]); last[a] = s0[4 * a + 3];
;                 quad[4 + a] = (s1[4 * a] + s1[4 * a + 1]) + (s1[4 * a + 2] + s1[4 * a + 3]); last[4 + a] = s1[4 * a + 3];
;             }
; #pragma unroll
;             for (int i = 0; i < 8; ++i) recv[i] = half_other(last[i], hl);
; #pragma unroll
;             for (int i = 0; i < 8; ++i) {
;                 const float prev = (i > 0) ? recv[i > 0 ? i - 1 : 0] : carry;
;                 float v = quad[i] + (hl ? recv[i] : prev);
;                 v += __shfl_xor(v, 1); v += __shfl_xor(v, 2);
;                 if ((n & 3) == 0) lds_st<float>(L + score_ofs + (16 * kt + 2 * i + hl) * 4, v);
;             }
;             carry = recv[7];
;         }
;         if (MODE != MODE_CMP1) {
;             bf16x8 pf[4];
; #pragma unroll
;             for (int ks = 0; ks < 4; ++ks) {
;                 const int hb = 8 * (ks & 1); u32x4 w;
;                 if (ks >> 1) { w.x = cvt_pk(s1[hb], s1[hb + 1]); w.y = cvt_pk(s1[hb + 2], s1[hb + 3]); w.z = cvt_pk(s1[hb + 4], s1[hb + 5]); w.w = cvt_pk(s1[hb + 6], s1[hb + 7]); }
;                 else { w.x = cvt_pk(s0[hb], s0[hb + 1]); w.y = cvt_pk(s0[hb + 2], s0[hb + 3]); w.z = cvt_pk(s0[hb + 4], s0[hb + 5]); w.w = cvt_pk(s0[hb + 6], s0[hb + 7]); }
;                 pf[ks] = __builtin_bit_cast(bf16x8, w);
;             }
;             const lptr vb_ = Vt + (4 * hl + q4) * VP + 32 * blk + 8 * p4;
; #pragma unroll
;             for (int c_ = 0; c_ < 2; ++c_)
; #pragma unroll
;                 for (int ks_ = 0; ks_ < 4; ++ks_) {
;                     const s16x4 lo_ = tr16(vb_ + (16 * ks_) * VP + 64 * c_), hi_ = tr16(vb_ + (16 * ks_ + 8) * VP + 64 * c_);
;                     const bf16x8 vf_ = {lo_[0], lo_[1], lo_[2], lo_[3], hi_[0], hi_[1], hi_[2], hi_[3]};
;                     o[c_] = mfma32(vf_, pf[ks_], o[c_]);
;                 }
.LBB0_182:
	v_exp_f32_e32 v143, v80
	v_exp_f32_e32 v144, v64
	v_exp_f32_e32 v0, v81
	v_exp_f32_e32 v90, v65
	v_exp_f32_e32 v145, v66
	v_add_f32_e32 v91, v144, v143
	v_exp_f32_e32 v80, v67
	v_pk_add_f32 v[64:65], v[90:91], v[0:1]
	v_exp_f32_e32 v91, v82
	v_pk_add_f32 v[64:65], v[64:65], v[64:65] op_sel_hi:[0,1]
	v_exp_f32_e32 v64, v83
	v_exp_f32_e32 v82, v69
	v_add_f32_e32 v81, v145, v91
	v_exp_f32_e32 v92, v75
	v_pk_add_f32 v[66:67], v[80:81], v[64:65]
	v_exp_f32_e32 v65, v84
	v_pk_add_f32 v[66:67], v[66:67], v[66:67] op_sel_hi:[0,1]
	v_exp_f32_e32 v81, v68
	v_exp_f32_e32 v66, v85
	v_exp_f32_e32 v84, v71
	v_exp_f32_e32 v94, v77
	v_add_f32_e32 v83, v81, v65
	v_pk_add_f32 v[68:69], v[82:83], v[66:67]
	v_exp_f32_e32 v67, v86
	v_pk_add_f32 v[68:69], v[68:69], v[68:69] op_sel_hi:[0,1]
	v_exp_f32_e32 v83, v70
	v_exp_f32_e32 v68, v87
	v_exp_f32_e32 v86, v73
	v_exp_f32_e32 v78, v78
	v_add_f32_e32 v85, v83, v67
	v_pk_add_f32 v[70:71], v[84:85], v[68:69]
	v_exp_f32_e32 v69, v88
	v_pk_add_f32 v[70:71], v[70:71], v[70:71] op_sel_hi:[0,1]
	v_exp_f32_e32 v85, v72
	v_exp_f32_e32 v70, v89
	v_cvt_pk_bf16_f32 v75, v67, v68
	v_cvt_pk_bf16_f32 v67, v83, v84
	v_add_f32_e32 v87, v85, v69
	v_pk_add_f32 v[72:73], v[86:87], v[70:71]
	v_exp_f32_e32 v71, v14
	v_pk_add_f32 v[88:89], v[72:73], v[72:73] op_sel_hi:[0,1]
	v_exp_f32_e32 v87, v74
	v_exp_f32_e32 v88, v15
	v_cvt_pk_bf16_f32 v72, v143, v0
	v_add_u32_e32 v0, v138, v139
	v_add_f32_e32 v93, v87, v71
	v_pk_add_f32 v[14:15], v[92:93], v[88:89]
	v_exp_f32_e32 v89, v12
	v_pk_add_f32 v[14:15], v[14:15], v[14:15] op_sel_hi:[0,1]
	v_exp_f32_e32 v93, v76
	v_exp_f32_e32 v14, v13
	v_exp_f32_e32 v76, v79
	v_cvt_pk_bf16_f32 v73, v91, v64
	v_add_f32_e32 v95, v93, v89
	v_pk_add_f32 v[12:13], v[94:95], v[14:15]
	v_exp_f32_e32 v15, v10
	v_pk_add_f32 v[12:13], v[12:13], v[12:13] op_sel_hi:[0,1]
	v_exp_f32_e32 v12, v11
	v_cvt_pk_bf16_f32 v74, v65, v66
	v_add_f32_e32 v77, v78, v15
	v_cvt_pk_bf16_f32 v68, v69, v70
	v_pk_add_f32 v[10:11], v[76:77], v[12:13]
	v_cvt_pk_bf16_f32 v13, v78, v76
	s_waitcnt lgkmcnt(0)
	s_waitcnt lgkmcnt(0)
	v_mfma_f32_32x32x16_bf16 v[16:31], v[206:209], v[72:75], v[16:31]
	v_cvt_pk_bf16_f32 v69, v71, v88
	v_cvt_pk_bf16_f32 v70, v89, v14
	v_cvt_pk_bf16_f32 v71, v15, v12
	v_cvt_pk_bf16_f32 v64, v144, v90
	v_cvt_pk_bf16_f32 v65, v145, v80
	v_cvt_pk_bf16_f32 v66, v81, v82
	v_mfma_f32_32x32x16_bf16 v[16:31], v[210:213], v[68:71], v[16:31]
	v_add_f32_e32 v10, v10, v11
	v_add_f32_e32 v140, v140, v10
	v_cvt_pk_bf16_f32 v10, v85, v86
	v_cvt_pk_bf16_f32 v11, v87, v92
	v_cvt_pk_bf16_f32 v12, v93, v94
	v_mfma_f32_32x32x16_bf16 v[16:31], v[226:229], v[64:67], v[16:31]
	s_nop 1
	v_mfma_f32_32x32x16_bf16 v[16:31], v[230:233], v[10:13], v[16:31]
	v_mfma_f32_32x32x16_bf16 v[32:47], v[234:237], v[72:75], v[32:47]
	v_mfma_f32_32x32x16_bf16 v[32:47], v[238:241], v[68:71], v[32:47]
	v_mfma_f32_32x32x16_bf16 v[32:47], v[242:245], v[64:67], v[32:47]
	v_mfma_f32_32x32x16_bf16 v[32:47], v[246:249], v[10:13], v[32:47]
	s_or_b64 exec, exec, s[56:57]
	s_cmp_lt_i32 s7, 0
	s_cbranch_scc1 .LBB0_186

; __device__ __forceinline__ f32x16 mfma32(bf16x8 a, bf16x8 b, f32x16 c) { return __builtin_amdgcn_mfma_f32_32x32x16_bf16(a, b, c, 0, 0, 0); }
; __device__ __forceinline__ s16x4 tr16(lptr p) { return __builtin_bit_cast(s16x4, __builtin_amdgcn_ds_read_tr16_b64_v4i16((LAS v4i16_t*)p)); }
; template <int MODE> ...
;     ...
;         const lptr Kt = L + A_KT + buf * 9216, Vt = L + A_VT + vcur * 12288;
;         f32x16 s0, s1;
; #pragma unroll
;         for (int s4 = 0; s4 < 4; ++s4) {
;             const bf16x8 a0 = lds_ld<bf16x8>(Kt + n * KP + s4 * 32 + hl * 16);
;             const bf16x8 a1 = lds_ld<bf16x8>(Kt + (32 + n) * KP + s4 * 32 + hl * 16);
;             if (s4 == 0) { s0 = mfma32(a0, qf[0], negm); s1 = mfma32(a1, qf[0], negm); }
;             else { s0 = mfma32(a0, qf[s4], s0); s1 = mfma32(a1, qf[s4], s1); }
;         }
;         const int kbase = 64 * kt + 4 * hl;
;         const bool far = (MODE == MODE_WIN || MODE == MODE_SEL) ? (wtmin - (64 * kt + 63) >= 128) : false;
;         const bool fmask = (MODE == MODE_FOX) ? (64 * kt + 63 > wtmin) : false;
;         const bool clean = (MODE == MODE_WIN) ? (far && (wtmax - 64 * kt < W)) : false;
;         const float mref = (MODE == MODE_CMP2) ? mfix : ((m == -INFINITY) ? 0.f : m);
;         if (MODE == MODE_FOX) {
; #pragma unroll
;             for (int kb = 0; kb < 2; ++kb)
; #pragma unroll
;                 for (int a = 0; a < 4; ++a) {
;                     const f32x4 c4 = lds_ld<f32x4>(L + A_CB + buf * 256 + (32 * kb + 8 * a + 4 * hl) * 4);
; #pragma unroll
;                     for (int e = 0; e < 4; ++e) { const int r = 4 * a + e; if (kb) s1[r] = s1[r] * SC2 + c4[e]; else s0[r] = s0[r] * SC2 + c4[e]; }
;                 }
;             if (__builtin_amdgcn_readfirstlane((int)fmask)) {
;     ...
;             const lptr vb_ = Vt + (4 * hl + q4) * VP + 32 * blk + 8 * p4;
; #pragma unroll
;             for (int c_ = 0; c_ < 2; ++c_)
; #pragma unroll
;                 for (int ks_ = 0; ks_ < 4; ++ks_) {
;                     const s16x4 lo_ = tr16(vb_ + (16 * ks_) * VP + 64 * c_), hi_ = tr16(vb_ + (16 * ks_ + 8) * VP + 64 * c_);
.LBB0_194:
	v_add_u32_e32 v14, v134, v135
	v_add_u32_e32 v0, v136, v135
	v_add_u32_e32 v156, v138, v139
	ds_read_b128 v[170:173], v14 offset:9216
	ds_read_b128 v[174:177], v0 offset:9216
	ds_read_b128 v[178:181], v14 offset:9248
	ds_read_b128 v[182:185], v0 offset:9248
	ds_read_b128 v[186:189], v14 offset:9280
	ds_read_b128 v[194:197], v0 offset:9280
	ds_read_b128 v[198:201], v14 offset:9312
	ds_read_b128 v[202:205], v0 offset:9312
	s_or_b32 s1, s0, 63
	v_cmp_gt_i32_e32 vcc, s1, v125
	s_waitcnt lgkmcnt(7)
	v_mfma_f32_32x32x16_bf16 v[80:95], v[170:173], v[104:107], v[48:63]
	ds_read_b64_tr_b16 v[206:207], v156 offset:30720
	ds_read_b64_tr_b16 v[208:209], v156 offset:32256
	s_waitcnt lgkmcnt(8)
	v_mfma_f32_32x32x16_bf16 v[64:79], v[174:177], v[104:107], v[48:63]
	ds_read_b64_tr_b16 v[210:211], v156 offset:33792
	ds_read_b64_tr_b16 v[212:213], v156 offset:35328
	s_waitcnt lgkmcnt(9)
	v_mfma_f32_32x32x16_bf16 v[80:95], v[178:181], v[96:99], v[80:95]
	ds_read_b64_tr_b16 v[226:227], v156 offset:36864
	ds_read_b64_tr_b16 v[228:229], v156 offset:38400
	s_waitcnt lgkmcnt(10)
	v_mfma_f32_32x32x16_bf16 v[64:79], v[182:185], v[96:99], v[64:79]
	ds_read_b64_tr_b16 v[230:231], v156 offset:39936
	ds_read_b64_tr_b16 v[232:233], v156 offset:41472
	s_waitcnt lgkmcnt(11)
	v_mfma_f32_32x32x16_bf16 v[80:95], v[186:189], v[100:103], v[80:95]
	ds_read_b64_tr_b16 v[234:235], v156 offset:30784
	ds_read_b64_tr_b16 v[236:237], v156 offset:32320
	s_waitcnt lgkmcnt(12)
	v_mfma_f32_32x32x16_bf16 v[64:79], v[194:197], v[100:103], v[64:79]
	ds_read_b64_tr_b16 v[238:239], v156 offset:33856
	ds_read_b64_tr_b16 v[240:241], v156 offset:35392
	v_cndmask_b32_e64 v0, 0, 1, vcc
	s_nop 0
	v_readfirstlane_b32 s1, v0
	s_bitcmp0_b32 s1, 0
	s_waitcnt lgkmcnt(13)
	v_mfma_f32_32x32x16_bf16 v[80:95], v[198:201], v[108:111], v[80:95]
	ds_read_b64_tr_b16 v[242:243], v156 offset:36928
	ds_read_b64_tr_b16 v[244:245], v156 offset:38464
	s_waitcnt lgkmcnt(14)
	v_mfma_f32_32x32x16_bf16 v[64:79], v[202:205], v[108:111], v[64:79]
	ds_read_b64_tr_b16 v[246:247], v156 offset:40000
	ds_read_b64_tr_b16 v[248:249], v156 offset:41536
	ds_read_b128 v[144:147], v135 offset:43264
	ds_read_b128 v[148:151], v135 offset:43296
	ds_read_b128 v[152:155], v135 offset:43328
	ds_read_b128 v[12:15], v135 offset:43360
	s_waitcnt lgkmcnt(3)
	s_nop 5
	v_pk_fma_f32 v[82:83], v[82:83], s[54:55], v[146:147] op_sel_hi:[1,0,1]
	s_waitcnt lgkmcnt(2)
	v_pk_fma_f32 v[86:87], v[86:87], s[54:55], v[150:151] op_sel_hi:[1,0,1]
	s_waitcnt lgkmcnt(1)
	v_pk_fma_f32 v[88:89], v[88:89], s[54:55], v[152:153] op_sel_hi:[1,0,1]
	s_waitcnt lgkmcnt(0)
	v_pk_fma_f32 v[10:11], v[94:95], s[54:55], v[14:15] op_sel_hi:[1,0,1]
	v_pk_fma_f32 v[12:13], v[92:93], s[54:55], v[12:13] op_sel_hi:[1,0,1]
	v_pk_fma_f32 v[14:15], v[90:91], s[54:55], v[154:155] op_sel_hi:[1,0,1]
	v_pk_fma_f32 v[84:85], v[84:85], s[54:55], v[148:149] op_sel_hi:[1,0,1]
	v_pk_fma_f32 v[80:81], v[80:81], s[54:55], v[144:145] op_sel_hi:[1,0,1]
	ds_read_b128 v[90:93], v135 offset:43392
	ds_read_b128 v[144:147], v135 offset:43424
	ds_read_b128 v[148:151], v135 offset:43456
	ds_read_b128 v[152:155], v135 offset:43488
	s_waitcnt lgkmcnt(3)
	v_pk_fma_f32 v[66:67], v[66:67], s[54:55], v[92:93] op_sel_hi:[1,0,1]
	s_waitcnt lgkmcnt(2)
	v_pk_fma_f32 v[70:71], v[70:71], s[54:55], v[146:147] op_sel_hi:[1,0,1]
	s_waitcnt lgkmcnt(1)
	v_pk_fma_f32 v[74:75], v[74:75], s[54:55], v[150:151] op_sel_hi:[1,0,1]
	s_waitcnt lgkmcnt(0)
	v_pk_fma_f32 v[78:79], v[78:79], s[54:55], v[154:155] op_sel_hi:[1,0,1]
	v_pk_fma_f32 v[76:77], v[76:77], s[54:55], v[152:153] op_sel_hi:[1,0,1]
	v_pk_fma_f32 v[72:73], v[72:73], s[54:55], v[148:149] op_sel_hi:[1,0,1]
	v_pk_fma_f32 v[68:69], v[68:69], s[54:55], v[144:145] op_sel_hi:[1,0,1]
	v_pk_fma_f32 v[64:65], v[64:65], s[54:55], v[90:91] op_sel_hi:[1,0,1]
	s_cbranch_scc1 .LBB0_196
; template <int MODE> ...
;     ...
;             if (__builtin_amdgcn_readfirstlane((int)fmask)) {
; #pragma unroll
;                 for (int r = 0; r < 16; ++r) {
;                     const int key = kbase + 8 * (r >> 2) + (r & 3);
;                     if (key > t) s0[r] = -INFINITY;
;                     if (key + 32 > t) s1[r] = -INFINITY;
;                 }
;             }
	v_or_b32_e32 v0, s0, v137
	v_or_b32_e32 v90, 32, v0
	v_cmp_le_i32_e32 vcc, v90, v126
	v_or_b32_e32 v90, 33, v0
	s_nop 0
	v_cndmask_b32_e32 v64, v220, v64, vcc
	v_cmp_lt_i32_e32 vcc, v0, v126
	s_nop 1
	v_cndmask_b32_e32 v81, v220, v81, vcc
	v_cmp_le_i32_e32 vcc, v0, v126
	s_nop 1
	v_cndmask_b32_e32 v80, v220, v80, vcc
	v_cmp_le_i32_e32 vcc, v90, v126
	v_or_b32_e32 v90, 2, v0
	s_nop 0
	v_cndmask_b32_e32 v65, v220, v65, vcc
	v_cmp_le_i32_e32 vcc, v90, v126
	v_or_b32_e32 v90, 34, v0
	s_nop 0
	v_cndmask_b32_e32 v82, v220, v82, vcc
	v_cmp_le_i32_e32 vcc, v90, v126
	v_or_b32_e32 v90, 3, v0
	s_nop 0
	v_cndmask_b32_e32 v66, v220, v66, vcc
	v_cmp_le_i32_e32 vcc, v90, v126
	v_or_b32_e32 v90, 35, v0
	s_nop 0
	v_cndmask_b32_e32 v83, v220, v83, vcc
	v_cmp_le_i32_e32 vcc, v90, v126
	v_or_b32_e32 v90, 8, v0
	s_nop 0
	v_cndmask_b32_e32 v67, v220, v67, vcc
	v_cmp_le_i32_e32 vcc, v90, v126
	v_or_b32_e32 v90, 40, v0
	s_nop 0
	v_cndmask_b32_e32 v84, v220, v84, vcc
	v_cmp_le_i32_e32 vcc, v90, v126
	v_or_b32_e32 v90, 9, v0
	s_nop 0
	v_cndmask_b32_e32 v68, v220, v68, vcc
	v_cmp_le_i32_e32 vcc, v90, v126
	v_or_b32_e32 v90, 41, v0
	s_nop 0
	v_cndmask_b32_e32 v85, v220, v85, vcc
	v_cmp_le_i32_e32 vcc, v90, v126
	v_or_b32_e32 v90, 10, v0
	s_nop 0
	v_cndmask_b32_e32 v69, v220, v69, vcc
	v_cmp_le_i32_e32 vcc, v90, v126
	v_or_b32_e32 v90, 42, v0
	s_nop 0
	v_cndmask_b32_e32 v86, v220, v86, vcc
	v_cmp_le_i32_e32 vcc, v90, v126
	v_or_b32_e32 v90, 11, v0
	s_nop 0
	v_cndmask_b32_e32 v70, v220, v70, vcc
	v_cmp_le_i32_e32 vcc, v90, v126
	v_or_b32_e32 v90, 43, v0
	s_nop 0
	v_cndmask_b32_e32 v87, v220, v87, vcc
	v_cmp_le_i32_e32 vcc, v90, v126
	v_or_b32_e32 v90, 16, v0
	s_nop 0
	v_cndmask_b32_e32 v71, v220, v71, vcc
	v_cmp_le_i32_e32 vcc, v90, v126
	v_or_b32_e32 v90, 48, v0
	s_nop 0
	v_cndmask_b32_e32 v88, v220, v88, vcc
	v_cmp_le_i32_e32 vcc, v90, v126
	v_or_b32_e32 v90, 17, v0
	s_nop 0
	v_cndmask_b32_e32 v72, v220, v72, vcc
	v_cmp_le_i32_e32 vcc, v90, v126
	v_or_b32_e32 v90, 49, v0
	s_nop 0
	v_cndmask_b32_e32 v89, v220, v89, vcc
	v_cmp_le_i32_e32 vcc, v90, v126
	v_or_b32_e32 v90, 18, v0
	s_nop 0
	v_cndmask_b32_e32 v73, v220, v73, vcc
	v_cmp_le_i32_e32 vcc, v90, v126
	v_or_b32_e32 v90, 50, v0
	s_nop 0
	v_cndmask_b32_e32 v14, v220, v14, vcc
	v_cmp_le_i32_e32 vcc, v90, v126
	v_or_b32_e32 v90, 19, v0
	s_nop 0
	v_cndmask_b32_e32 v74, v220, v74, vcc
	v_cmp_le_i32_e32 vcc, v90, v126
	v_or_b32_e32 v90, 51, v0
	s_nop 0
	v_cndmask_b32_e32 v15, v220, v15, vcc
	v_cmp_le_i32_e32 vcc, v90, v126
	v_or_b32_e32 v90, 24, v0
	s_nop 0
	v_cndmask_b32_e32 v75, v220, v75, vcc
	v_cmp_le_i32_e32 vcc, v90, v126
	v_or_b32_e32 v90, 56, v0
	s_nop 0
	v_cndmask_b32_e32 v12, v220, v12, vcc
	v_cmp_le_i32_e32 vcc, v90, v126
	v_or_b32_e32 v90, 25, v0
	s_nop 0
	v_cndmask_b32_e32 v76, v220, v76, vcc
	v_cmp_le_i32_e32 vcc, v90, v126
	v_or_b32_e32 v90, 57, v0
	s_nop 0
	v_cndmask_b32_e32 v13, v220, v13, vcc
	v_cmp_le_i32_e32 vcc, v90, v126
	v_or_b32_e32 v90, 26, v0
	s_nop 0
	v_cndmask_b32_e32 v77, v220, v77, vcc
	v_cmp_le_i32_e32 vcc, v90, v126
	v_or_b32_e32 v90, 58, v0
	s_nop 0
	v_cndmask_b32_e32 v10, v220, v10, vcc
	v_cmp_le_i32_e32 vcc, v90, v126
	v_or_b32_e32 v90, 27, v0
	v_or_b32_e32 v0, 59, v0
	v_cndmask_b32_e32 v78, v220, v78, vcc
	v_cmp_le_i32_e32 vcc, v90, v126
	s_nop 1
	v_cndmask_b32_e32 v11, v220, v11, vcc
	v_cmp_le_i32_e32 vcc, v0, v126
	s_nop 1
	v_cndmask_b32_e32 v79, v220, v79, vcc

; template <int MODE> ...
;     ...
;             float ps = 0.f;
; #pragma unroll
;             for (int r = 0; r < 16; ++r) { s0[r] = ex2(s0[r]); s1[r] = ex2(s1[r]); ps += s0[r] + s1[r]; }
;             l += ps;
;         } else {
; #pragma unroll
;             for (int r = 0; r < 16; ++r) { s0[r] = ex2(s0[r]) * linv; s1[r] = ex2(s1[r]) * linv; }
;             float quad[8], last[8], recv[8];
; #pragma unroll
;             for (int a = 0; a < 4; ++a) {
;                 quad[a] = (s0[4 * a] + s0[4 * a + 1]) + (s0[4 * a + 2] + s0[4 * a + 3]); last[a] = s0[4 * a + 3];
;                 quad[4 + a] = (s1[4 * a] + s1[4 * a + 1]) + (s1[4 * a + 2] + s1[4 * a + 3]); last[4 + a] = s1[4 * a + 3];
;             }
; #pragma unroll
;             for (int i = 0; i < 8; ++i) recv[i] = half_other(last[i], hl);
; #pragma unroll
;             for (int i = 0; i < 8; ++i) {
;                 const float prev = (i > 0) ? recv[i > 0 ? i - 1 : 0] : carry;
;                 float v = quad[i] + (hl ? recv[i] : prev);
;                 v += __shfl_xor(v, 1); v += __shfl_xor(v, 2);
;                 if ((n & 3) == 0) lds_st<float>(L + score_ofs + (16 * kt + 2 * i + hl) * 4, v);
;             }
;             carry = recv[7];
;         }
;         if (MODE != MODE_CMP1) {
;             bf16x8 pf[4];
; #pragma unroll
;             for (int ks = 0; ks < 4; ++ks) {
;                 const int hb = 8 * (ks & 1); u32x4 w;
;                 if (ks >> 1) { w.x = cvt_pk(s1[hb], s1[hb + 1]); w.y = cvt_pk(s1[hb + 2], s1[hb + 3]); w.z = cvt_pk(s1[hb + 4], s1[hb + 5]); w.w = cvt_pk(s1[hb + 6], s1[hb + 7]); }
;                 else { w.x = cvt_pk(s0[hb], s0[hb + 1]); w.y = cvt_pk(s0[hb + 2], s0[hb + 3]); w.z = cvt_pk(s0[hb + 4], s0[hb + 5]); w.w = cvt_pk(s0[hb + 6], s0[hb + 7]); }
;                 pf[ks] = __builtin_bit_cast(bf16x8, w);
;             }
;             const lptr vb_ = Vt + (4 * hl + q4) * VP + 32 * blk + 8 * p4;
; #pragma unroll
;             for (int c_ = 0; c_ < 2; ++c_)
; #pragma unroll
;                 for (int ks_ = 0; ks_ < 4; ++ks_) {
;                     const s16x4 lo_ = tr16(vb_ + (16 * ks_) * VP + 64 * c_), hi_ = tr16(vb_ + (16 * ks_ + 8) * VP + 64 * c_);
;                     const bf16x8 vf_ = {lo_[0], lo_[1], lo_[2], lo_[3], hi_[0], hi_[1], hi_[2], hi_[3]};
;                     o[c_] = mfma32(vf_, pf[ks_], o[c_]);
;                 }
.LBB0_198:
	v_exp_f32_e32 v143, v80
	v_exp_f32_e32 v144, v64
	v_exp_f32_e32 v0, v81
	v_exp_f32_e32 v90, v65
	v_exp_f32_e32 v145, v66
	v_add_f32_e32 v91, v144, v143
	v_exp_f32_e32 v80, v67
	v_pk_add_f32 v[64:65], v[90:91], v[0:1]
	v_exp_f32_e32 v91, v82
	v_pk_add_f32 v[64:65], v[64:65], v[64:65] op_sel_hi:[0,1]
	v_exp_f32_e32 v64, v83
	v_exp_f32_e32 v82, v69
	v_add_f32_e32 v81, v145, v91
	v_exp_f32_e32 v92, v75
	v_pk_add_f32 v[66:67], v[80:81], v[64:65]
	v_exp_f32_e32 v65, v84
	v_pk_add_f32 v[66:67], v[66:67], v[66:67] op_sel_hi:[0,1]
	v_exp_f32_e32 v81, v68
	v_exp_f32_e32 v66, v85
	v_exp_f32_e32 v84, v71
	v_exp_f32_e32 v94, v77
	v_add_f32_e32 v83, v81, v65
	v_pk_add_f32 v[68:69], v[82:83], v[66:67]
	v_exp_f32_e32 v67, v86
	v_pk_add_f32 v[68:69], v[68:69], v[68:69] op_sel_hi:[0,1]
	v_exp_f32_e32 v83, v70
	v_exp_f32_e32 v68, v87
	v_exp_f32_e32 v86, v73
	v_exp_f32_e32 v78, v78
	v_add_f32_e32 v85, v83, v67
	v_pk_add_f32 v[70:71], v[84:85], v[68:69]
	v_exp_f32_e32 v69, v88
	v_pk_add_f32 v[70:71], v[70:71], v[70:71] op_sel_hi:[0,1]
	v_exp_f32_e32 v85, v72
	v_exp_f32_e32 v70, v89
	v_cvt_pk_bf16_f32 v75, v67, v68
	v_cvt_pk_bf16_f32 v67, v83, v84
	v_add_f32_e32 v87, v85, v69
	v_pk_add_f32 v[72:73], v[86:87], v[70:71]
	v_exp_f32_e32 v71, v14
	v_pk_add_f32 v[88:89], v[72:73], v[72:73] op_sel_hi:[0,1]
	v_exp_f32_e32 v87, v74
	v_exp_f32_e32 v88, v15
	v_cvt_pk_bf16_f32 v72, v143, v0
	v_add_u32_e32 v0, v138, v139
	v_add_f32_e32 v93, v87, v71
	v_pk_add_f32 v[14:15], v[92:93], v[88:89]
	v_exp_f32_e32 v89, v12
	v_pk_add_f32 v[14:15], v[14:15], v[14:15] op_sel_hi:[0,1]
	v_exp_f32_e32 v93, v76
	v_exp_f32_e32 v14, v13
	v_exp_f32_e32 v76, v79
	v_cvt_pk_bf16_f32 v73, v91, v64
	v_add_f32_e32 v95, v93, v89
	v_pk_add_f32 v[12:13], v[94:95], v[14:15]
	v_exp_f32_e32 v15, v10
	v_pk_add_f32 v[12:13], v[12:13], v[12:13] op_sel_hi:[0,1]
	v_exp_f32_e32 v12, v11
	v_cvt_pk_bf16_f32 v74, v65, v66
	v_add_f32_e32 v77, v78, v15
	v_cvt_pk_bf16_f32 v68, v69, v70
	v_pk_add_f32 v[10:11], v[76:77], v[12:13]
	v_cvt_pk_bf16_f32 v13, v78, v76
	s_waitcnt lgkmcnt(0)
	s_waitcnt lgkmcnt(0)
	v_mfma_f32_32x32x16_bf16 v[16:31], v[206:209], v[72:75], v[16:31]
	v_cvt_pk_bf16_f32 v69, v71, v88
	v_cvt_pk_bf16_f32 v70, v89, v14
	v_cvt_pk_bf16_f32 v71, v15, v12
	v_cvt_pk_bf16_f32 v64, v144, v90
	v_cvt_pk_bf16_f32 v65, v145, v80
	v_cvt_pk_bf16_f32 v66, v81, v82
	v_mfma_f32_32x32x16_bf16 v[16:31], v[210:213], v[68:71], v[16:31]
	v_add_f32_e32 v10, v10, v11
	v_add_f32_e32 v140, v140, v10
	v_cvt_pk_bf16_f32 v10, v85, v86
	v_cvt_pk_bf16_f32 v11, v87, v92
	v_cvt_pk_bf16_f32 v12, v93, v94
	v_mfma_f32_32x32x16_bf16 v[16:31], v[226:229], v[64:67], v[16:31]
	s_nop 1
	v_mfma_f32_32x32x16_bf16 v[16:31], v[230:233], v[10:13], v[16:31]
	v_mfma_f32_32x32x16_bf16 v[32:47], v[234:237], v[72:75], v[32:47]
	v_mfma_f32_32x32x16_bf16 v[32:47], v[238:241], v[68:71], v[32:47]
	v_mfma_f32_32x32x16_bf16 v[32:47], v[242:245], v[64:67], v[32:47]
	v_mfma_f32_32x32x16_bf16 v[32:47], v[246:249], v[10:13], v[32:47]
	s_or_b64 exec, exec, s[58:59]
	s_andn2_b64 vcc, exec, s[50:51]
	s_cbranch_vccnz .LBB0_171

; __device__ __forceinline__ f32x16 mfma32(bf16x8 a, bf16x8 b, f32x16 c) { return __builtin_amdgcn_mfma_f32_32x32x16_bf16(a, b, c, 0, 0, 0); }
; __device__ __forceinline__ void compress_phase(lptr L, const Params& P, int l) {
;     ...
; #pragma unroll 2
;         for (int p = 0; p < 32; ++p) {
;             int tok = tok0 + p; tok = tok > SEQ - 1 ? SEQ - 1 : tok;
;             const bf16_t* ar = Zb + (size_t)tok * ZLD; const bf16_t* br = B1 + p * 64;
; #pragma unroll
;             for (int s = 0; s < 4; ++s) acc = mfma32(*(const bf16x8*)(ar + 16 * s), *(const bf16x8*)(br + 16 * s), acc);
;         }
.LBB0_203:
	s_mov_b64 s[26:27], 0x100
	v_add_u32_e32 v27, s2, v29
	v_min_u32_e32 v0, 0xfff, v27
	v_mul_u32_u24_e32 v0, 0xe20, v0
	v_lshlrev_b32_e32 v0, 1, v0
	v_lshl_add_u64 v[96:97], v[62:63], 0, v[0:1]
	global_load_dwordx4 v[98:101], v[96:97], off
	global_load_dwordx4 v[102:105], v[96:97], off offset:32
	global_load_dwordx4 v[106:109], v[96:97], off offset:64
	global_load_dwordx4 v[110:113], v[96:97], off offset:96
	global_load_dwordx4 v[130:133], v[64:65], off offset:-128
	global_load_dwordx4 v[134:137], v[64:65], off offset:-96
	global_load_dwordx4 v[138:141], v[64:65], off offset:-64
	global_load_dwordx4 v[142:145], v[64:65], off offset:-32
	v_add_u32_e32 v27, s2, v29
	v_add_u32_e32 v27, 1, v27
	v_min_u32_e32 v0, 0xfff, v27
	v_mul_u32_u24_e32 v0, 0xe20, v0
	v_lshlrev_b32_e32 v0, 1, v0
	v_lshl_add_u64 v[96:97], v[62:63], 0, v[0:1]
	global_load_dwordx4 v[114:117], v[96:97], off
	global_load_dwordx4 v[118:121], v[96:97], off offset:32
	global_load_dwordx4 v[122:125], v[96:97], off offset:64
	global_load_dwordx4 v[126:129], v[96:97], off offset:96
	global_load_dwordx4 v[146:149], v[64:65], off
	global_load_dwordx4 v[150:153], v[64:65], off offset:32
	global_load_dwordx4 v[154:157], v[64:65], off offset:64
	global_load_dwordx4 v[158:161], v[64:65], off offset:96
	v_lshl_add_u64 v[64:65], v[64:65], 0, s[26:27]
.Lcmp_loop:
	v_add_u32_e32 v27, s2, v29
	v_add_u32_e32 v27, 2, v27
	v_min_u32_e32 v0, 0xfff, v27
	v_mul_u32_u24_e32 v0, 0xe20, v0
	v_lshlrev_b32_e32 v0, 1, v0
	v_lshl_add_u64 v[96:97], v[62:63], 0, v[0:1]
	global_load_dwordx4 v[170:173], v[96:97], off
	global_load_dwordx4 v[174:177], v[96:97], off offset:32
	global_load_dwordx4 v[178:181], v[96:97], off offset:64
	global_load_dwordx4 v[182:185], v[96:97], off offset:96
	global_load_dwordx4 v[206:209], v[64:65], off offset:-128
	global_load_dwordx4 v[210:213], v[64:65], off offset:-96
	global_load_dwordx4 v[226:229], v[64:65], off offset:-64
	global_load_dwordx4 v[230:233], v[64:65], off offset:-32
	v_add_u32_e32 v27, s2, v29
	v_add_u32_e32 v27, 3, v27
	v_min_u32_e32 v0, 0xfff, v27
	v_mul_u32_u24_e32 v0, 0xe20, v0
	v_lshlrev_b32_e32 v0, 1, v0
	v_lshl_add_u64 v[96:97], v[62:63], 0, v[0:1]
	global_load_dwordx4 v[186:189], v[96:97], off
	global_load_dwordx4 v[194:197], v[96:97], off offset:32
	global_load_dwordx4 v[198:201], v[96:97], off offset:64
	global_load_dwordx4 v[202:205], v[96:97], off offset:96
	global_load_dwordx4 v[234:237], v[64:65], off
	global_load_dwordx4 v[238:241], v[64:65], off offset:32
	global_load_dwordx4 v[242:245], v[64:65], off offset:64
	global_load_dwordx4 v[246:249], v[64:65], off offset:96
	v_lshl_add_u64 v[64:65], v[64:65], 0, s[26:27]
	s_waitcnt vmcnt(16)
	v_mfma_f32_32x32x16_bf16 v[2:17], v[98:101], v[130:133], v[2:17]
	v_mfma_f32_32x32x16_bf16 v[2:17], v[102:105], v[134:137], v[2:17]
	v_mfma_f32_32x32x16_bf16 v[2:17], v[106:109], v[138:141], v[2:17]
	v_mfma_f32_32x32x16_bf16 v[2:17], v[110:113], v[142:145], v[2:17]
	v_mfma_f32_32x32x16_bf16 v[2:17], v[114:117], v[146:149], v[2:17]
	v_mfma_f32_32x32x16_bf16 v[2:17], v[118:121], v[150:153], v[2:17]
	v_mfma_f32_32x32x16_bf16 v[2:17], v[122:125], v[154:157], v[2:17]
	v_mfma_f32_32x32x16_bf16 v[2:17], v[126:129], v[158:161], v[2:17]
	s_add_i32 s2, s2, 4
	s_cmp_eq_u32 s2, 32
	s_cbranch_scc1 .Lcmp_tail
	v_add_u32_e32 v27, s2, v29
	v_min_u32_e32 v0, 0xfff, v27
	v_mul_u32_u24_e32 v0, 0xe20, v0
	v_lshlrev_b32_e32 v0, 1, v0
	v_lshl_add_u64 v[96:97], v[62:63], 0, v[0:1]
	global_load_dwordx4 v[98:101], v[96:97], off
	global_load_dwordx4 v[102:105], v[96:97], off offset:32
	global_load_dwordx4 v[106:109], v[96:97], off offset:64
	global_load_dwordx4 v[110:113], v[96:97], off offset:96
	global_load_dwordx4 v[130:133], v[64:65], off offset:-128
	global_load_dwordx4 v[134:137], v[64:65], off offset:-96
	global_load_dwordx4 v[138:141], v[64:65], off offset:-64
	global_load_dwordx4 v[142:145], v[64:65], off offset:-32
	v_add_u32_e32 v27, s2, v29
	v_add_u32_e32 v27, 1, v27
	v_min_u32_e32 v0, 0xfff, v27
	v_mul_u32_u24_e32 v0, 0xe20, v0
	v_lshlrev_b32_e32 v0, 1, v0
	v_lshl_add_u64 v[96:97], v[62:63], 0, v[0:1]
	global_load_dwordx4 v[114:117], v[96:97], off
	global_load_dwordx4 v[118:121], v[96:97], off offset:32
	global_load_dwordx4 v[122:125], v[96:97], off offset:64
	global_load_dwordx4 v[126:129], v[96:97], off offset:96
	global_load_dwordx4 v[146:149], v[64:65], off
	global_load_dwordx4 v[150:153], v[64:65], off offset:32
	global_load_dwordx4 v[154:157], v[64:65], off offset:64
	global_load_dwordx4 v[158:161], v[64:65], off offset:96
	v_lshl_add_u64 v[64:65], v[64:65], 0, s[26:27]
	s_waitcnt vmcnt(16)
	v_mfma_f32_32x32x16_bf16 v[2:17], v[170:173], v[206:209], v[2:17]
	v_mfma_f32_32x32x16_bf16 v[2:17], v[174:177], v[210:213], v[2:17]
	v_mfma_f32_32x32x16_bf16 v[2:17], v[178:181], v[226:229], v[2:17]
	v_mfma_f32_32x32x16_bf16 v[2:17], v[182:185], v[230:233], v[2:17]
	v_mfma_f32_32x32x16_bf16 v[2:17], v[186:189], v[234:237], v[2:17]
	v_mfma_f32_32x32x16_bf16 v[2:17], v[194:197], v[238:241], v[2:17]
	v_mfma_f32_32x32x16_bf16 v[2:17], v[198:201], v[242:245], v[2:17]
	v_mfma_f32_32x32x16_bf16 v[2:17], v[202:205], v[246:249], v[2:17]
	s_branch .Lcmp_loop
; __device__ __forceinline__ unsigned cvt_pk(float lo, float hi) { f32x2_t v = {lo, hi}; bf16x2_t b = __builtin_convertvector(v, bf16x2_t); return __builtin_bit_cast(unsigned, b); }
; __device__ __forceinline__ void compress_phase(lptr L, const Params& P, int l) {
;     ...
;         float peb = 0.f;
;         { const float* pp = (const float*)(ws + W_PEB) + src * 32 * 256 + 32 * wave + n;
; #pragma unroll 8
;           for (int q = 0; q < 32; ++q) peb += pp[q * 256]; }
; #pragma unroll
;         for (int r = 0; r < 16; ++r) {
;             const int row = 8 * (r >> 2) + 4 * hl + (r & 3);
;             const float hv = gelu_tanh(acc[r] + peb);
;             lds_st<bf16_t>(L + (row * HP + 32 * wave + n) * 2, (bf16_t)(cvt_pk(hv, 0.f) & 0xffffu));
;         }
.Lcmp_tail:
	s_lshl_b32 s2, s0, 13
	s_ashr_i32 s3, s2, 31
	v_lshl_add_u64 v[62:63], s[2:3], 2, v[24:25]
	v_add_co_u32_e32 v88, vcc, 0x3590000, v62
	s_mov_b64 s[26:27], 0x1000
	s_nop 0
	v_addc_co_u32_e32 v89, vcc, 0, v63, vcc
	global_load_dword v98, v[88:89], off
	global_load_dword v99, v[88:89], off offset:1024
	global_load_dword v100, v[88:89], off offset:2048
	global_load_dword v101, v[88:89], off offset:3072
	v_lshl_add_u64 v[88:89], v[88:89], 0, s[26:27]
	global_load_dword v102, v[88:89], off
	global_load_dword v103, v[88:89], off offset:1024
	global_load_dword v104, v[88:89], off offset:2048
	global_load_dword v105, v[88:89], off offset:3072
	v_lshl_add_u64 v[88:89], v[88:89], 0, s[26:27]
	global_load_dword v106, v[88:89], off
	global_load_dword v107, v[88:89], off offset:1024
	global_load_dword v108, v[88:89], off offset:2048
	global_load_dword v109, v[88:89], off offset:3072
	v_lshl_add_u64 v[88:89], v[88:89], 0, s[26:27]
	global_load_dword v110, v[88:89], off
	global_load_dword v111, v[88:89], off offset:1024
	global_load_dword v112, v[88:89], off offset:2048
	global_load_dword v113, v[88:89], off offset:3072
	v_lshl_add_u64 v[88:89], v[88:89], 0, s[26:27]
	global_load_dword v114, v[88:89], off
	global_load_dword v115, v[88:89], off offset:1024
	global_load_dword v116, v[88:89], off offset:2048
	global_load_dword v117, v[88:89], off offset:3072
	v_lshl_add_u64 v[88:89], v[88:89], 0, s[26:27]
	global_load_dword v118, v[88:89], off
	global_load_dword v119, v[88:89], off offset:1024
	global_load_dword v120, v[88:89], off offset:2048
	global_load_dword v121, v[88:89], off offset:3072
	v_lshl_add_u64 v[88:89], v[88:89], 0, s[26:27]
	global_load_dword v122, v[88:89], off
	global_load_dword v123, v[88:89], off offset:1024
	global_load_dword v124, v[88:89], off offset:2048
	global_load_dword v125, v[88:89], off offset:3072
	v_lshl_add_u64 v[88:89], v[88:89], 0, s[26:27]
	global_load_dword v126, v[88:89], off
	global_load_dword v127, v[88:89], off offset:1024
	global_load_dword v128, v[88:89], off offset:2048
	global_load_dword v129, v[88:89], off offset:3072
	s_waitcnt vmcnt(32)
	v_mfma_f32_32x32x16_bf16 v[2:17], v[170:173], v[206:209], v[2:17]
	v_mfma_f32_32x32x16_bf16 v[2:17], v[174:177], v[210:213], v[2:17]
	v_mfma_f32_32x32x16_bf16 v[2:17], v[178:181], v[226:229], v[2:17]
	v_mfma_f32_32x32x16_bf16 v[2:17], v[182:185], v[230:233], v[2:17]
	v_mfma_f32_32x32x16_bf16 v[2:17], v[186:189], v[234:237], v[2:17]
	v_mfma_f32_32x32x16_bf16 v[2:17], v[194:197], v[238:241], v[2:17]
	v_mfma_f32_32x32x16_bf16 v[2:17], v[198:201], v[242:245], v[2:17]
	v_mfma_f32_32x32x16_bf16 v[2:17], v[202:205], v[246:249], v[2:17]
	v_mov_b32_e32 v0, 0
	s_waitcnt vmcnt(0)
	v_add_f32_e32 v0, v0, v98
	v_add_f32_e32 v0, v0, v99
	v_add_f32_e32 v0, v0, v100
	v_add_f32_e32 v0, v0, v101
	v_add_f32_e32 v0, v0, v102
	v_add_f32_e32 v0, v0, v103
	v_add_f32_e32 v0, v0, v104
	v_add_f32_e32 v0, v0, v105
	v_add_f32_e32 v0, v0, v106
	v_add_f32_e32 v0, v0, v107
	v_add_f32_e32 v0, v0, v108
	v_add_f32_e32 v0, v0, v109
	v_add_f32_e32 v0, v0, v110
	v_add_f32_e32 v0, v0, v111
	v_add_f32_e32 v0, v0, v112
	v_add_f32_e32 v0, v0, v113
	v_add_f32_e32 v0, v0, v114
	v_add_f32_e32 v0, v0, v115
	v_add_f32_e32 v0, v0, v116
	v_add_f32_e32 v0, v0, v117
	v_add_f32_e32 v0, v0, v118
	v_add_f32_e32 v0, v0, v119
	v_add_f32_e32 v0, v0, v120
	v_add_f32_e32 v0, v0, v121
	v_add_f32_e32 v0, v0, v122
	v_add_f32_e32 v0, v0, v123
	v_add_f32_e32 v0, v0, v124
	v_add_f32_e32 v0, v0, v125
	v_add_f32_e32 v0, v0, v126
	v_add_f32_e32 v0, v0, v127
	v_add_f32_e32 v0, v0, v128
	v_add_f32_e32 v0, v0, v129
	v_add_f32_e32 v2, v2, v0
	v_mul_f32_e32 v27, 0x3d372713, v2
	v_mul_f32_e32 v27, v2, v27
	v_fma_f32 v27, v2, v27, v2
	v_mul_f32_e32 v27, 0x3f4c422a, v27
	v_mul_f32_e32 v27, 0x4038aa3b, v27
	v_exp_f32_e32 v27, v27
	v_mul_f32_e32 v2, 0.5, v2
	v_add_f32_e32 v27, 1.0, v27
	v_rcp_f32_e32 v27, v27
	s_nop 0
	v_fma_f32 v27, v27, -2.0, 2.0
	v_mul_f32_e32 v2, v2, v27
	v_cvt_pk_bf16_f32 v2, v2, s0
	ds_write_b16 v69, v2
	v_add_f32_e32 v2, v3, v0
	v_mul_f32_e32 v3, 0x3d372713, v2
	v_mul_f32_e32 v3, v2, v3
	v_fma_f32 v3, v2, v3, v2
	v_mul_f32_e32 v3, 0x3f4c422a, v3
	v_mul_f32_e32 v3, 0x4038aa3b, v3
	v_exp_f32_e32 v3, v3
	v_mul_f32_e32 v2, 0.5, v2
	v_add_f32_e32 v3, 1.0, v3
	v_rcp_f32_e32 v3, v3
	s_nop 0
	v_fma_f32 v3, v3, -2.0, 2.0
	v_mul_f32_e32 v2, v2, v3
	v_cvt_pk_bf16_f32 v2, v2, s0
	ds_write_b16 v70, v2
	v_add_f32_e32 v2, v4, v0
	v_mul_f32_e32 v3, 0x3d372713, v2
	v_mul_f32_e32 v3, v2, v3
	v_fma_f32 v3, v2, v3, v2
	v_mul_f32_e32 v3, 0x3f4c422a, v3
	v_mul_f32_e32 v3, 0x4038aa3b, v3
	v_exp_f32_e32 v3, v3
	v_mul_f32_e32 v2, 0.5, v2
	v_add_f32_e32 v3, 1.0, v3
	v_rcp_f32_e32 v3, v3
	s_nop 0
	v_fma_f32 v3, v3, -2.0, 2.0
	v_mul_f32_e32 v2, v2, v3
	v_cvt_pk_bf16_f32 v2, v2, s0
	ds_write_b16 v71, v2
	v_add_f32_e32 v2, v5, v0
	v_mul_f32_e32 v3, 0x3d372713, v2
	v_mul_f32_e32 v3, v2, v3
	v_fma_f32 v3, v2, v3, v2
	v_mul_f32_e32 v3, 0x3f4c422a, v3
	v_mul_f32_e32 v3, 0x4038aa3b, v3
	v_exp_f32_e32 v3, v3
	v_mul_f32_e32 v2, 0.5, v2
	v_add_f32_e32 v3, 1.0, v3
	v_rcp_f32_e32 v3, v3
	s_nop 0
	v_fma_f32 v3, v3, -2.0, 2.0
	v_mul_f32_e32 v2, v2, v3
	v_cvt_pk_bf16_f32 v2, v2, s0
	ds_write_b16 v72, v2
	v_add_f32_e32 v2, v6, v0
	v_mul_f32_e32 v3, 0x3d372713, v2
	v_mul_f32_e32 v3, v2, v3
	v_fma_f32 v3, v2, v3, v2
	v_mul_f32_e32 v3, 0x3f4c422a, v3
	v_mul_f32_e32 v3, 0x4038aa3b, v3
	v_exp_f32_e32 v3, v3
	v_mul_f32_e32 v2, 0.5, v2
	v_add_f32_e32 v3, 1.0, v3
	v_rcp_f32_e32 v3, v3
	s_nop 0
	v_fma_f32 v3, v3, -2.0, 2.0
	v_mul_f32_e32 v2, v2, v3
	v_cvt_pk_bf16_f32 v2, v2, s0
	ds_write_b16 v73, v2
	v_add_f32_e32 v2, v7, v0
	v_mul_f32_e32 v3, 0x3d372713, v2
; __device__ __forceinline__ unsigned cvt_pk(float lo, float hi) { f32x2_t v = {lo, hi}; bf16x2_t b = __builtin_convertvector(v, bf16x2_t); return __builtin_bit_cast(unsigned, b); }
; __device__ __forceinline__ void compress_phase(lptr L, const Params& P, int l) {
;     ...
;         for (int r = 0; r < 16; ++r) {
;             const int row = 8 * (r >> 2) + 4 * hl + (r & 3);
;             const float hv = gelu_tanh(acc[r] + peb);
;             lds_st<bf16_t>(L + (row * HP + 32 * wave + n) * 2, (bf16_t)(cvt_pk(hv, 0.f) & 0xffffu));
;         }
;         __syncthreads();
;         if (wave < 2) {
	v_mul_f32_e32 v3, v2, v3
	v_fma_f32 v3, v2, v3, v2
	v_mul_f32_e32 v3, 0x3f4c422a, v3
	v_mul_f32_e32 v3, 0x4038aa3b, v3
	v_exp_f32_e32 v3, v3
	v_mul_f32_e32 v2, 0.5, v2
	v_add_f32_e32 v3, 1.0, v3
	v_rcp_f32_e32 v3, v3
	s_nop 0
	v_fma_f32 v3, v3, -2.0, 2.0
	v_mul_f32_e32 v2, v2, v3
	v_cvt_pk_bf16_f32 v2, v2, s0
	ds_write_b16 v74, v2
	v_add_f32_e32 v2, v8, v0
	v_mul_f32_e32 v3, 0x3d372713, v2
	v_mul_f32_e32 v3, v2, v3
	v_fma_f32 v3, v2, v3, v2
	v_mul_f32_e32 v3, 0x3f4c422a, v3
	v_mul_f32_e32 v3, 0x4038aa3b, v3
	v_exp_f32_e32 v3, v3
	v_mul_f32_e32 v2, 0.5, v2
	v_add_f32_e32 v3, 1.0, v3
	v_rcp_f32_e32 v3, v3
	s_nop 0
	v_fma_f32 v3, v3, -2.0, 2.0
	v_mul_f32_e32 v2, v2, v3
	v_cvt_pk_bf16_f32 v2, v2, s0
	ds_write_b16 v75, v2
	v_add_f32_e32 v2, v9, v0
	v_mul_f32_e32 v3, 0x3d372713, v2
	v_mul_f32_e32 v3, v2, v3
	v_fma_f32 v3, v2, v3, v2
	v_mul_f32_e32 v3, 0x3f4c422a, v3
	v_mul_f32_e32 v3, 0x4038aa3b, v3
	v_exp_f32_e32 v3, v3
	v_mul_f32_e32 v2, 0.5, v2
	v_add_f32_e32 v3, 1.0, v3
	v_rcp_f32_e32 v3, v3
	s_nop 0
	v_fma_f32 v3, v3, -2.0, 2.0
	v_mul_f32_e32 v2, v2, v3
	v_cvt_pk_bf16_f32 v2, v2, s0
	ds_write_b16 v76, v2
	v_add_f32_e32 v2, v10, v0
	v_mul_f32_e32 v3, 0x3d372713, v2
	v_mul_f32_e32 v3, v2, v3
	v_fma_f32 v3, v2, v3, v2
	v_mul_f32_e32 v3, 0x3f4c422a, v3
	v_mul_f32_e32 v3, 0x4038aa3b, v3
	v_exp_f32_e32 v3, v3
	v_mul_f32_e32 v2, 0.5, v2
	v_add_f32_e32 v3, 1.0, v3
	v_rcp_f32_e32 v3, v3
	s_nop 0
	v_fma_f32 v3, v3, -2.0, 2.0
	v_mul_f32_e32 v2, v2, v3
	v_cvt_pk_bf16_f32 v2, v2, s0
	ds_write_b16 v77, v2
	v_add_f32_e32 v2, v11, v0
	v_mul_f32_e32 v3, 0x3d372713, v2
	v_mul_f32_e32 v3, v2, v3
	v_fma_f32 v3, v2, v3, v2
	v_mul_f32_e32 v3, 0x3f4c422a, v3
	v_mul_f32_e32 v3, 0x4038aa3b, v3
	v_exp_f32_e32 v3, v3
	v_mul_f32_e32 v2, 0.5, v2
	v_add_f32_e32 v3, 1.0, v3
	v_rcp_f32_e32 v3, v3
	s_nop 0
	v_fma_f32 v3, v3, -2.0, 2.0
	v_mul_f32_e32 v2, v2, v3
	v_cvt_pk_bf16_f32 v2, v2, s0
	ds_write_b16 v78, v2
	v_add_f32_e32 v2, v12, v0
	v_mul_f32_e32 v3, 0x3d372713, v2
	v_mul_f32_e32 v3, v2, v3
	v_fma_f32 v3, v2, v3, v2
	v_mul_f32_e32 v3, 0x3f4c422a, v3
	v_mul_f32_e32 v3, 0x4038aa3b, v3
	v_exp_f32_e32 v3, v3
	v_mul_f32_e32 v2, 0.5, v2
	v_add_f32_e32 v3, 1.0, v3
	v_rcp_f32_e32 v3, v3
	s_nop 0
	v_fma_f32 v3, v3, -2.0, 2.0
	v_mul_f32_e32 v2, v2, v3
	v_cvt_pk_bf16_f32 v2, v2, s0
	ds_write_b16 v79, v2
	v_add_f32_e32 v2, v13, v0
	v_mul_f32_e32 v3, 0x3d372713, v2
	v_mul_f32_e32 v3, v2, v3
	v_fma_f32 v3, v2, v3, v2
	v_mul_f32_e32 v3, 0x3f4c422a, v3
	v_mul_f32_e32 v3, 0x4038aa3b, v3
	v_exp_f32_e32 v3, v3
	v_mul_f32_e32 v2, 0.5, v2
	v_add_f32_e32 v3, 1.0, v3
	v_rcp_f32_e32 v3, v3
	s_nop 0
	v_fma_f32 v3, v3, -2.0, 2.0
	v_mul_f32_e32 v2, v2, v3
	v_cvt_pk_bf16_f32 v2, v2, s0
	ds_write_b16 v80, v2
	v_add_f32_e32 v2, v14, v0
	v_mul_f32_e32 v3, 0x3d372713, v2
	v_mul_f32_e32 v3, v2, v3
	v_fma_f32 v3, v2, v3, v2
	v_mul_f32_e32 v3, 0x3f4c422a, v3
	v_mul_f32_e32 v3, 0x4038aa3b, v3
	v_exp_f32_e32 v3, v3
	v_mul_f32_e32 v2, 0.5, v2
	v_add_f32_e32 v3, 1.0, v3
	v_rcp_f32_e32 v3, v3
	s_nop 0
	v_fma_f32 v3, v3, -2.0, 2.0
	v_mul_f32_e32 v2, v2, v3
	v_cvt_pk_bf16_f32 v2, v2, s0
	ds_write_b16 v81, v2
	v_add_f32_e32 v2, v15, v0
	v_mul_f32_e32 v3, 0x3d372713, v2
	v_mul_f32_e32 v3, v2, v3
	v_fma_f32 v3, v2, v3, v2
	v_mul_f32_e32 v3, 0x3f4c422a, v3
	v_mul_f32_e32 v3, 0x4038aa3b, v3
	v_exp_f32_e32 v3, v3
	v_mul_f32_e32 v2, 0.5, v2
	v_add_f32_e32 v3, 1.0, v3
	v_rcp_f32_e32 v3, v3
	s_nop 0
	v_fma_f32 v3, v3, -2.0, 2.0
	v_mul_f32_e32 v2, v2, v3
	v_cvt_pk_bf16_f32 v2, v2, s0
	ds_write_b16 v82, v2
	v_add_f32_e32 v2, v16, v0
	v_mul_f32_e32 v3, 0x3d372713, v2
	v_mul_f32_e32 v3, v2, v3
	v_fma_f32 v3, v2, v3, v2
	v_mul_f32_e32 v3, 0x3f4c422a, v3
	v_mul_f32_e32 v3, 0x4038aa3b, v3
	v_exp_f32_e32 v3, v3
	v_mul_f32_e32 v2, 0.5, v2
	v_add_f32_e32 v0, v17, v0
	v_add_f32_e32 v3, 1.0, v3
	v_rcp_f32_e32 v3, v3
	s_nop 0
	v_fma_f32 v3, v3, -2.0, 2.0
	v_mul_f32_e32 v2, v2, v3
	v_cvt_pk_bf16_f32 v2, v2, s0
	ds_write_b16 v83, v2
	v_mul_f32_e32 v2, 0x3d372713, v0
	v_mul_f32_e32 v2, v0, v2
	v_fma_f32 v2, v0, v2, v0
	v_mul_f32_e32 v2, 0x3f4c422a, v2
	v_mul_f32_e32 v2, 0x4038aa3b, v2
	v_exp_f32_e32 v2, v2
	v_mul_f32_e32 v0, 0.5, v0
	v_add_f32_e32 v2, 1.0, v2
	v_rcp_f32_e32 v2, v2
	s_nop 0
	v_fma_f32 v2, v2, -2.0, 2.0
	v_mul_f32_e32 v0, v0, v2
	v_cvt_pk_bf16_f32 v0, v0, s0
	ds_write_b16 v85, v0
	s_waitcnt lgkmcnt(0)
	s_barrier
	s_and_saveexec_b64 s[2:3], s[38:39]
	s_cbranch_execz .LBB0_201
; __device__ __forceinline__ unsigned cvt_pk(float lo, float hi) { f32x2_t v = {lo, hi}; bf16x2_t b = __builtin_convertvector(v, bf16x2_t); return __builtin_bit_cast(unsigned, b); }
; __device__ __forceinline__ f32x16 mfma32(bf16x8 a, bf16x8 b, f32x16 c) { return __builtin_amdgcn_mfma_f32_32x32x16_bf16(a, b, c, 0, 0, 0); }
; __device__ __forceinline__ void compress_phase(lptr L, const Params& P, int l) {
;     ...
;         if (wave < 2) {
;             const bf16_t* B2 = (const bf16_t*)(ws + W_C2) + (size_t)src * 64 * 256 + (size_t)(32 * wave + n) * 256 + 8 * hl;
;             f32x16 a2 = {};
; #pragma unroll
;             for (int s = 0; s < 16; ++s) a2 = mfma32(lds_ld<bf16x8>(L + (n * HP + 16 * s + 8 * hl) * 2), *(const bf16x8*)(B2 + 16 * s), a2);
;             bf16_t* out = (bf16_t*)(ws + WS_KC) + ((size_t)(src * 16 + bg) * 256 + i0) * 64 + 32 * wave + n;
; #pragma unroll
;             for (int r = 0; r < 16; ++r) {
;                 const int row = 8 * (r >> 2) + 4 * hl + (r & 3);
;                 const float v = (i0 + row < 255) ? a2[r] : 0.f;
;                 out[(size_t)row * 64] = (bf16_t)(cvt_pk(v, 0.f) & 0xffffu);
;             }
;         }
	s_lshl_b64 s[26:27], s[0:1], 15
	v_lshl_add_u64 v[92:93], v[20:21], 0, s[26:27]
	global_load_dwordx4 v[2:5], v[92:93], off
	ds_read_b128 v[6:9], v86
	ds_read_b128 v[62:65], v86 offset:32
	global_load_dwordx4 v[88:91], v[92:93], off offset:32
	s_lshl_b32 s0, s0, 4
	s_or_b32 s0, s0, s7
	s_lshl_b32 s10, s6, 5
	s_ashr_i32 s1, s0, 31
	s_and_b32 s10, s10, 0xe0
	s_lshl_b64 s[0:1], s[0:1], 15
	v_readlane_b32 s7, v253, 35
	s_add_u32 s0, s7, s0
	v_readlane_b32 s7, v253, 36
	s_addc_u32 s1, s7, s1
	s_lshl_b32 s7, s10, 7
	s_add_u32 s0, s0, s7
	s_addc_u32 s1, s1, 0
	v_mov_b32_e32 v29, v1
	v_mov_b32_e32 v31, v1
	v_mov_b32_e32 v33, v1
	v_mov_b32_e32 v35, v1
	v_mov_b32_e32 v37, v1
	v_mov_b32_e32 v39, v1
	v_mov_b32_e32 v41, v1
	v_mov_b32_e32 v43, v1
	v_mov_b32_e32 v45, v1
	v_mov_b32_e32 v47, v1
	v_mov_b32_e32 v49, v1
	v_mov_b32_e32 v51, v1
	v_mov_b32_e32 v53, v1
	v_mov_b32_e32 v55, v1
	v_mov_b32_e32 v57, v1
	v_mov_b32_e32 v59, v1
	v_mov_b32_e32 v61, v1
	s_waitcnt vmcnt(1) lgkmcnt(1)
	v_mfma_f32_32x32x16_bf16 v[2:17], v[6:9], v[2:5], 0
	s_waitcnt vmcnt(0) lgkmcnt(0)
	v_mfma_f32_32x32x16_bf16 v[2:17], v[62:65], v[88:91], v[2:17]
	global_load_dwordx4 v[88:91], v[92:93], off offset:64
	ds_read_b128 v[62:65], v86 offset:64
	s_waitcnt vmcnt(0) lgkmcnt(0)
	v_mfma_f32_32x32x16_bf16 v[2:17], v[62:65], v[88:91], v[2:17]
	global_load_dwordx4 v[88:91], v[92:93], off offset:96
	ds_read_b128 v[62:65], v86 offset:96
	s_waitcnt vmcnt(0) lgkmcnt(0)
	v_mfma_f32_32x32x16_bf16 v[2:17], v[62:65], v[88:91], v[2:17]
	global_load_dwordx4 v[88:91], v[92:93], off offset:128
	ds_read_b128 v[62:65], v86 offset:128
	s_waitcnt vmcnt(0) lgkmcnt(0)
	v_mfma_f32_32x32x16_bf16 v[2:17], v[62:65], v[88:91], v[2:17]
	global_load_dwordx4 v[88:91], v[92:93], off offset:160
	ds_read_b128 v[62:65], v86 offset:160
	s_waitcnt vmcnt(0) lgkmcnt(0)
	v_mfma_f32_32x32x16_bf16 v[2:17], v[62:65], v[88:91], v[2:17]
	global_load_dwordx4 v[88:91], v[92:93], off offset:192
	ds_read_b128 v[62:65], v86 offset:192
	s_waitcnt vmcnt(0) lgkmcnt(0)
	v_mfma_f32_32x32x16_bf16 v[2:17], v[62:65], v[88:91], v[2:17]
	global_load_dwordx4 v[88:91], v[92:93], off offset:224
	ds_read_b128 v[62:65], v86 offset:224
	s_waitcnt vmcnt(0) lgkmcnt(0)
	v_mfma_f32_32x32x16_bf16 v[2:17], v[62:65], v[88:91], v[2:17]
	global_load_dwordx4 v[88:91], v[92:93], off offset:256
	ds_read_b128 v[62:65], v86 offset:256
	s_waitcnt vmcnt(0) lgkmcnt(0)
	v_mfma_f32_32x32x16_bf16 v[2:17], v[62:65], v[88:91], v[2:17]
	global_load_dwordx4 v[88:91], v[92:93], off offset:288
	ds_read_b128 v[62:65], v86 offset:288
	s_waitcnt vmcnt(0) lgkmcnt(0)
	v_mfma_f32_32x32x16_bf16 v[2:17], v[62:65], v[88:91], v[2:17]
	global_load_dwordx4 v[88:91], v[92:93], off offset:320
	ds_read_b128 v[62:65], v86 offset:320
	s_waitcnt vmcnt(0) lgkmcnt(0)
	v_mfma_f32_32x32x16_bf16 v[2:17], v[62:65], v[88:91], v[2:17]
	global_load_dwordx4 v[88:91], v[92:93], off offset:352
	ds_read_b128 v[62:65], v86 offset:352
	s_waitcnt vmcnt(0) lgkmcnt(0)
	v_mfma_f32_32x32x16_bf16 v[2:17], v[62:65], v[88:91], v[2:17]
	global_load_dwordx4 v[88:91], v[92:93], off offset:384
	ds_read_b128 v[62:65], v86 offset:384
	s_waitcnt vmcnt(0) lgkmcnt(0)
	v_mfma_f32_32x32x16_bf16 v[2:17], v[62:65], v[88:91], v[2:17]
	global_load_dwordx4 v[88:91], v[92:93], off offset:416
	ds_read_b128 v[62:65], v86 offset:416
	s_waitcnt vmcnt(0) lgkmcnt(0)
	v_mfma_f32_32x32x16_bf16 v[2:17], v[62:65], v[88:91], v[2:17]
	global_load_dwordx4 v[88:91], v[92:93], off offset:448
	ds_read_b128 v[62:65], v86 offset:448
	s_waitcnt vmcnt(0) lgkmcnt(0)
	v_mfma_f32_32x32x16_bf16 v[2:17], v[62:65], v[88:91], v[2:17]
	global_load_dwordx4 v[88:91], v[92:93], off offset:480
	ds_read_b128 v[62:65], v86 offset:480
	s_waitcnt vmcnt(0) lgkmcnt(0)
	v_mfma_f32_32x32x16_bf16 v[2:17], v[62:65], v[88:91], v[2:17]
	v_lshl_add_u64 v[62:63], v[18:19], 1, s[0:1]
	v_lshl_add_u64 v[62:63], v[62:63], 0, v[28:29]
	v_lshl_add_u64 v[64:65], v[62:63], 0, v[30:31]
	s_nop 8
	v_cvt_pk_bf16_f32 v0, v2, s0
	global_store_short v[64:65], v0, off
	v_cvt_pk_bf16_f32 v0, v3, s0
	v_lshl_add_u64 v[2:3], v[62:63], 0, v[32:33]
	global_store_short v[2:3], v0, off
	v_cvt_pk_bf16_f32 v0, v4, s0
	v_lshl_add_u64 v[2:3], v[62:63], 0, v[34:35]
	global_store_short v[2:3], v0, off
	v_cvt_pk_bf16_f32 v0, v5, s0
	v_lshl_add_u64 v[2:3], v[62:63], 0, v[36:37]
	global_store_short v[2:3], v0, off
	v_cvt_pk_bf16_f32 v0, v6, s0
	v_lshl_add_u64 v[2:3], v[62:63], 0, v[38:39]
	global_store_short v[2:3], v0, off
	v_cvt_pk_bf16_f32 v0, v7, s0
	v_lshl_add_u64 v[2:3], v[62:63], 0, v[40:41]
	global_store_short v[2:3], v0, off
	v_cvt_pk_bf16_f32 v0, v8, s0
	v_lshl_add_u64 v[2:3], v[62:63], 0, v[42:43]
	global_store_short v[2:3], v0, off
	v_cvt_pk_bf16_f32 v0, v9, s0
	v_lshl_add_u64 v[2:3], v[62:63], 0, v[44:45]
	global_store_short v[2:3], v0, off
	v_cvt_pk_bf16_f32 v0, v10, s0
	v_lshl_add_u64 v[2:3], v[62:63], 0, v[46:47]
	global_store_short v[2:3], v0, off
	v_cvt_pk_bf16_f32 v0, v11, s0
	v_lshl_add_u64 v[2:3], v[62:63], 0, v[48:49]
	global_store_short v[2:3], v0, off
	v_cvt_pk_bf16_f32 v0, v12, s0
	v_lshl_add_u64 v[2:3], v[62:63], 0, v[50:51]
	global_store_short v[2:3], v0, off
	v_cvt_pk_bf16_f32 v0, v13, s0
	v_lshl_add_u64 v[2:3], v[62:63], 0, v[52:53]
	global_store_short v[2:3], v0, off
	v_cvt_pk_bf16_f32 v0, v14, s0
	v_lshl_add_u64 v[2:3], v[62:63], 0, v[54:55]
	global_store_short v[2:3], v0, off
	v_cvt_pk_bf16_f32 v0, v15, s0
	v_lshl_add_u64 v[2:3], v[62:63], 0, v[56:57]
	global_store_short v[2:3], v0, off
	v_cvt_pk_bf16_f32 v0, v16, s0
	v_lshl_add_u64 v[2:3], v[62:63], 0, v[58:59]
	global_store_short v[2:3], v0, off
	v_or_b32_e32 v0, s10, v84
	v_cvt_pk_bf16_f32 v2, v17, s0
	s_movk_i32 s0, 0xff
	v_cmp_ne_u32_e32 vcc, s0, v0
	s_nop 1
	v_cndmask_b32_e32 v0, 0, v2, vcc
	v_lshl_add_u64 v[2:3], v[62:63], 0, v[60:61]
	global_store_short v[2:3], v0, off
	s_branch .LBB0_201

; __device__ __forceinline__ float half_max(float x) { auto rr = __builtin_amdgcn_permlane32_swap(__float_as_uint(x), __float_as_uint(x), false, false); return fmaxf(__uint_as_float(rr[0]), __uint_as_float(rr[1])); }
; __device__ __forceinline__ void nsa_unit(lptr L, const Params& P, int b, int g, int qi) {
;     ...
;         unsigned long long picked = 0ull;
; #pragma unroll 1
;         for (int it = 0; it < nfree; ++it) {
;             const float vv = ((picked >> J) & 1ull) ? -INFINITY : v;
;             float mxv = vv;
; #pragma unroll
;             for (int o_ = 1; o_ < 32; o_ <<= 1) mxv = fmaxf(mxv, __shfl_xor(mxv, o_));
;             mxv = half_max(mxv);
;             const unsigned long long cand = __ballot(vv == mxv && vv > -INFINITY);
;             if (cand == 0ull) break;
;             picked |= 1ull << __builtin_ctzll(cand);
.LBB0_298:
	v_and_b32_e32 v5, s47, v3
	v_and_b32_e32 v4, s46, v2
	v_cmp_eq_u64_e64 s[0:1], 0, v[4:5]
	s_and_b64 s[0:1], s[6:7], s[0:1]
	s_waitcnt lgkmcnt(0)
	v_cndmask_b32_e64 v4, v220, v9, s[0:1]
	v_cmp_lg_f32_e64 s[40:41], s16, v4
	v_max_f32_e32 v5, v4, v4
	s_nop 1
	v_max_f32_dpp v5, v5, v5 quad_perm:[1,0,3,2] row_mask:0xf bank_mask:0xf
	s_nop 1
	v_max_f32_dpp v5, v5, v5 quad_perm:[2,3,0,1] row_mask:0xf bank_mask:0xf
	s_nop 1
	v_max_f32_dpp v5, v5, v5 row_half_mirror row_mask:0xf bank_mask:0xf
	s_nop 1
	v_max_f32_dpp v5, v5, v5 row_mirror row_mask:0xf bank_mask:0xf
	s_nop 1
	v_max_f32_dpp v5, v5, v5 row_bcast:15 row_mask:0xa bank_mask:0xf
	s_nop 1
	v_max_f32_dpp v5, v5, v5 row_bcast:31 row_mask:0xc bank_mask:0xf
	s_nop 1
	v_readlane_b32 s48, v5, 63
	s_nop 3
	v_cmp_eq_f32_e64 s[0:1], s48, v4
	s_and_b64 s[0:1], s[40:41], s[0:1]
	s_nop 0
	v_cndmask_b32_e64 v4, 0, 1, s[0:1]
	v_cmp_ne_u32_e64 s[0:1], 0, v4
	s_cmp_eq_u64 s[0:1], 0
	s_cselect_b64 s[40:41], -1, 0
	s_sub_u32 s48, 0, s0
	s_subb_u32 s49, 0, s1
	s_and_b64 s[0:1], s[0:1], s[48:49]
	s_or_b64 s[46:47], s[0:1], s[46:47]
	v_cmp_ge_u32_e64 s[0:1], s18, v0
	s_or_b64 s[0:1], s[40:41], s[0:1]
	s_add_i32 s18, s18, 1
	s_and_b64 s[0:1], exec, s[0:1]
	s_or_b64 s[44:45], s[0:1], s[44:45]
	v_mov_b64_e32 v[4:5], s[46:47]
	s_andn2_b64 exec, exec, s[44:45]
	s_cbranch_execnz .LBB0_298
	s_or_b64 exec, exec, s[44:45]
	v_and_b32_e32 v5, v5, v3
	v_and_b32_e32 v4, v4, v2
	v_cmp_ne_u64_e64 s[0:1], 0, v[4:5]
	s_or_b64 s[0:1], s[0:1], s[42:43]
	s_or_b64 s[0:1], s[0:1], s[38:39]
	v_cndmask_b32_e64 v4, 0, 1, s[0:1]
	v_cmp_ne_u32_e64 s[40:41], 0, v4
	s_and_saveexec_b64 s[0:1], vcc
	s_cbranch_execz .LBB0_296
	v_add_lshl_u32 v4, s13, v234, 3
	v_mov_b64_e32 v[10:11], s[40:41]
	ds_write_b64 v4, v[10:11] offset:59904
	s_branch .LBB0_296

; __device__ __forceinline__ f32x16 mfma32(bf16x8 a, bf16x8 b, f32x16 c) { return __builtin_amdgcn_mfma_f32_32x32x16_bf16(a, b, c, 0, 0, 0); }
; __device__ __forceinline__ s16x4 tr16(lptr p) { return __builtin_bit_cast(s16x4, __builtin_amdgcn_ds_read_tr16_b64_v4i16((LAS v4i16_t*)p)); }
; template <int MODE> ...
;     ...
;     const bool selbit = (MODE == MODE_SEL) ? ((((kt < 32) ? (mlo >> kt) : (mhi >> (kt - 32))) & 1u) != 0u) : true;
;     if (MODE == MODE_SEL) active = __any(selbit) != 0;
;     if (active) {
;         const lptr Kt = L + A_KT + buf * 9216, Vt = L + A_VT + vcur * 12288;
;         f32x16 s0, s1;
; #pragma unroll
;         for (int s4 = 0; s4 < 4; ++s4) {
;             const bf16x8 a0 = lds_ld<bf16x8>(Kt + n * KP + s4 * 32 + hl * 16);
;             const bf16x8 a1 = lds_ld<bf16x8>(Kt + (32 + n) * KP + s4 * 32 + hl * 16);
;             if (s4 == 0) { s0 = mfma32(a0, qf[0], negm); s1 = mfma32(a1, qf[0], negm); }
;             else { s0 = mfma32(a0, qf[s4], s0); s1 = mfma32(a1, qf[s4], s1); }
;         }
;     ...
;             const lptr vb_ = Vt + (4 * hl + q4) * VP + 32 * blk + 8 * p4;
; #pragma unroll
;             for (int c_ = 0; c_ < 2; ++c_)
; #pragma unroll
;                 for (int ks_ = 0; ks_ < 4; ++ks_) {
;                     const s16x4 lo_ = tr16(vb_ + (16 * ks_) * VP + 64 * c_), hi_ = tr16(vb_ + (16 * ks_ + 8) * VP + 64 * c_);
.LBB0_310:
	v_sub_co_u32_e64 v10, vcc, s0, 32
	v_lshrrev_b32_e32 v0, s0, v160
	v_lshrrev_b32_e32 v10, v10, v161
	v_cndmask_b32_e32 v0, v10, v0, vcc
	v_and_b32_e32 v0, 1, v0
	v_cmp_eq_u32_e64 s[38:39], 1, v0
	v_cmp_ne_u32_e32 vcc, 0, v0
	s_cbranch_vccz .LBB0_318
	v_add_u32_e32 v14, v182, v183
	v_add_u32_e32 v212, v186, v187
	ds_read_b128 v[10:13], v14
	ds_read_b128 v[64:67], v14 offset:32
	v_add_u32_e32 v0, v184, v183
	s_lshl_b32 s7, s0, 6
	v_cmp_ge_i32_e32 vcc, s7, v179
	s_waitcnt lgkmcnt(1)
	v_mfma_f32_32x32x16_bf16 v[112:127], v[10:13], v[128:131], v[48:63]
	ds_read_b64_tr_b16 v[196:197], v212 offset:18432
	ds_read_b64_tr_b16 v[198:199], v212 offset:19968
	ds_read_b128 v[10:13], v0
	ds_read_b128 v[68:71], v0 offset:32
	s_waitcnt lgkmcnt(1)
	v_mfma_f32_32x32x16_bf16 v[96:111], v[10:13], v[128:131], v[48:63]
	ds_read_b64_tr_b16 v[200:201], v212 offset:21504
	ds_read_b64_tr_b16 v[202:203], v212 offset:23040
	s_waitcnt lgkmcnt(6)
	v_mfma_f32_32x32x16_bf16 v[112:127], v[64:67], v[132:135], v[112:127]
	ds_read_b64_tr_b16 v[204:205], v212 offset:24576
	ds_read_b64_tr_b16 v[206:207], v212 offset:26112
	ds_read_b128 v[10:13], v0 offset:64
	ds_read_b128 v[64:67], v14 offset:64
	s_waitcnt lgkmcnt(6)
	v_mfma_f32_32x32x16_bf16 v[96:111], v[68:71], v[132:135], v[96:111]
	ds_read_b64_tr_b16 v[208:209], v212 offset:27648
	ds_read_b64_tr_b16 v[210:211], v212 offset:29184
	s_waitcnt lgkmcnt(2)
	v_mfma_f32_32x32x16_bf16 v[112:127], v[64:67], v[136:139], v[112:127]
	ds_read_b64_tr_b16 v[238:239], v212 offset:18496
	ds_read_b64_tr_b16 v[240:241], v212 offset:20032
	s_waitcnt lgkmcnt(5)
	v_mfma_f32_32x32x16_bf16 v[96:111], v[10:13], v[136:139], v[96:111]
	ds_read_b64_tr_b16 v[242:243], v212 offset:21568
	ds_read_b64_tr_b16 v[244:245], v212 offset:23104
	ds_read_b128 v[10:13], v0 offset:96
	ds_read_b128 v[64:67], v14 offset:96
	s_waitcnt lgkmcnt(0)
	v_mfma_f32_32x32x16_bf16 v[112:127], v[64:67], v[140:143], v[112:127]
	ds_read_b64_tr_b16 v[246:247], v212 offset:24640
	ds_read_b64_tr_b16 v[248:249], v212 offset:26176
	s_waitcnt lgkmcnt(3)
	v_mfma_f32_32x32x16_bf16 v[96:111], v[10:13], v[140:143], v[96:111]
	ds_read_b64_tr_b16 v[234:235], v212 offset:27712
	ds_read_b64_tr_b16 v[236:237], v212 offset:29248
	s_and_saveexec_b64 s[0:1], vcc
	s_xor_b64 s[0:1], exec, s[0:1]
	s_cbranch_execz .LBB0_313
; template <int MODE> ...
;     ...
;         } else if (MODE == MODE_WIN || MODE == MODE_SEL) {
;             const int dbase = t - kbase;
;             const lptr tb = L + tabofs + (dbase + TAB0 - 63) * 4;
; #pragma unroll
;             for (int kb = 0; kb < 2; ++kb)
; #pragma unroll
;                 for (int a = 0; a < 4; ++a)
; #pragma unroll
;                     for (int e = 0; e < 4; ++e) {
;                         const int r = 4 * a + e, off = 32 * kb + 8 * a + e; const int d = dbase - off;
;                         const float bsv = far ? tab128 : lds_ld<float>(tb + 4 * (63 - off));
;                         const bool ok = (MODE == MODE_WIN) ? ((unsigned)d < (unsigned)W) : (selbit && d >= 0);
;                         const float sv = kb ? s1[r] : s0[r];
;                         const float x = ok ? sv * SC2 + bsv : -INFINITY;
;                         if (kb) s1[r] = x; else s0[r] = x;
;                     }
	v_or_b32_e32 v0, s7, v185
	v_sub_u32_e32 v0, v229, v0
	v_lshl_add_u32 v10, v0, 2, v230
	ds_read2_b32 v[12:13], v10 offset0:127 offset1:128
	v_cmp_lt_i32_e32 vcc, -1, v0
	s_and_b64 vcc, vcc, s[38:39]
	s_waitcnt lgkmcnt(0)
	s_nop 0
	v_fmamk_f32 v11, v112, 0x3e38aa3b, v13
	v_cndmask_b32_e32 v64, v220, v11, vcc
	v_cmp_lt_i32_e32 vcc, 0, v0
	s_and_b64 vcc, vcc, s[38:39]
	v_fmac_f32_e32 v12, 0x3e38aa3b, v113
	v_cndmask_b32_e32 v65, v220, v12, vcc
	ds_read2_b32 v[12:13], v10 offset0:125 offset1:126
	v_cmp_lt_i32_e32 vcc, 1, v0
	s_and_b64 vcc, vcc, s[38:39]
	s_waitcnt lgkmcnt(0)
	v_fmamk_f32 v11, v114, 0x3e38aa3b, v13
	v_cndmask_b32_e32 v66, v220, v11, vcc
	v_cmp_lt_i32_e32 vcc, 2, v0
	s_and_b64 vcc, vcc, s[38:39]
	v_fmac_f32_e32 v12, 0x3e38aa3b, v115
	v_cndmask_b32_e32 v67, v220, v12, vcc
	ds_read2_b32 v[12:13], v10 offset0:119 offset1:120
	v_cmp_lt_i32_e32 vcc, 7, v0
	s_and_b64 vcc, vcc, s[38:39]
	s_waitcnt lgkmcnt(0)
	v_fmamk_f32 v11, v116, 0x3e38aa3b, v13
	v_cndmask_b32_e32 v68, v220, v11, vcc
	v_cmp_lt_i32_e32 vcc, 8, v0
	s_and_b64 vcc, vcc, s[38:39]
	v_fmac_f32_e32 v12, 0x3e38aa3b, v117
	v_cndmask_b32_e32 v69, v220, v12, vcc
	ds_read2_b32 v[12:13], v10 offset0:117 offset1:118
	v_cmp_lt_i32_e32 vcc, 9, v0
	s_and_b64 vcc, vcc, s[38:39]
	s_waitcnt lgkmcnt(0)
	v_fmamk_f32 v11, v118, 0x3e38aa3b, v13
	v_cndmask_b32_e32 v70, v220, v11, vcc
	v_cmp_lt_i32_e32 vcc, 10, v0
	s_and_b64 vcc, vcc, s[38:39]
	v_fmac_f32_e32 v12, 0x3e38aa3b, v119
	v_cndmask_b32_e32 v71, v220, v12, vcc
	ds_read2_b32 v[12:13], v10 offset0:111 offset1:112
	v_cmp_lt_i32_e32 vcc, 15, v0
	s_and_b64 vcc, vcc, s[38:39]
	s_waitcnt lgkmcnt(0)
	v_fmamk_f32 v11, v120, 0x3e38aa3b, v13
	v_cndmask_b32_e32 v72, v220, v11, vcc
	v_cmp_lt_i32_e32 vcc, 16, v0
	s_and_b64 vcc, vcc, s[38:39]
	v_fmac_f32_e32 v12, 0x3e38aa3b, v121
	v_cndmask_b32_e32 v73, v220, v12, vcc
	ds_read2_b32 v[12:13], v10 offset0:109 offset1:110
	v_cmp_lt_i32_e32 vcc, 17, v0
	s_and_b64 vcc, vcc, s[38:39]
	s_waitcnt lgkmcnt(0)
	v_fmamk_f32 v11, v122, 0x3e38aa3b, v13
	v_cndmask_b32_e32 v74, v220, v11, vcc
	v_cmp_lt_i32_e32 vcc, 18, v0
	s_and_b64 vcc, vcc, s[38:39]
	v_fmac_f32_e32 v12, 0x3e38aa3b, v123
	v_cndmask_b32_e32 v75, v220, v12, vcc
	ds_read2_b32 v[12:13], v10 offset0:103 offset1:104
	v_cmp_lt_i32_e32 vcc, 23, v0
	s_and_b64 vcc, vcc, s[38:39]
	s_waitcnt lgkmcnt(0)
	v_fmamk_f32 v11, v124, 0x3e38aa3b, v13
	v_cndmask_b32_e32 v76, v220, v11, vcc
	v_cmp_lt_i32_e32 vcc, 24, v0
	s_and_b64 vcc, vcc, s[38:39]
	v_fmac_f32_e32 v12, 0x3e38aa3b, v125
	v_cndmask_b32_e32 v77, v220, v12, vcc
	ds_read2_b32 v[12:13], v10 offset0:101 offset1:102
	v_cmp_lt_i32_e32 vcc, 25, v0
	s_and_b64 vcc, vcc, s[38:39]
	s_waitcnt lgkmcnt(0)
	v_fmamk_f32 v11, v126, 0x3e38aa3b, v13
	v_cndmask_b32_e32 v78, v220, v11, vcc
	v_cmp_lt_i32_e32 vcc, 26, v0
	s_and_b64 vcc, vcc, s[38:39]
	v_fmac_f32_e32 v12, 0x3e38aa3b, v127
	v_cndmask_b32_e32 v79, v220, v12, vcc
	ds_read2_b32 v[12:13], v10 offset0:95 offset1:96
	v_cmp_lt_i32_e32 vcc, 31, v0
	s_and_b64 vcc, vcc, s[38:39]
	s_waitcnt lgkmcnt(0)
	v_fmamk_f32 v11, v96, 0x3e38aa3b, v13
	v_cndmask_b32_e32 v80, v220, v11, vcc
	v_cmp_lt_i32_e32 vcc, 32, v0
	s_and_b64 vcc, vcc, s[38:39]
	v_fmac_f32_e32 v12, 0x3e38aa3b, v97
	v_cndmask_b32_e32 v81, v220, v12, vcc
	ds_read2_b32 v[12:13], v10 offset0:93 offset1:94
	v_cmp_lt_i32_e32 vcc, 33, v0
	s_and_b64 vcc, vcc, s[38:39]
	s_waitcnt lgkmcnt(0)
	v_fmamk_f32 v11, v98, 0x3e38aa3b, v13
	v_cndmask_b32_e32 v82, v220, v11, vcc
	v_cmp_lt_i32_e32 vcc, 34, v0
	s_and_b64 vcc, vcc, s[38:39]
	v_fmac_f32_e32 v12, 0x3e38aa3b, v99
	v_cndmask_b32_e32 v83, v220, v12, vcc
	ds_read2_b32 v[12:13], v10 offset0:87 offset1:88
	v_cmp_lt_i32_e32 vcc, 39, v0
	s_and_b64 vcc, vcc, s[38:39]
	s_waitcnt lgkmcnt(0)
	v_fmamk_f32 v11, v100, 0x3e38aa3b, v13
	v_cndmask_b32_e32 v84, v220, v11, vcc
	v_cmp_lt_i32_e32 vcc, 40, v0
	s_and_b64 vcc, vcc, s[38:39]
	v_fmac_f32_e32 v12, 0x3e38aa3b, v101
	v_cndmask_b32_e32 v85, v220, v12, vcc
	ds_read2_b32 v[12:13], v10 offset0:85 offset1:86
	v_cmp_lt_i32_e32 vcc, 41, v0
	s_and_b64 vcc, vcc, s[38:39]
	s_waitcnt lgkmcnt(0)
	v_fmamk_f32 v11, v102, 0x3e38aa3b, v13
	v_cndmask_b32_e32 v86, v220, v11, vcc
	v_cmp_lt_i32_e32 vcc, 42, v0
	s_and_b64 vcc, vcc, s[38:39]
	v_fmac_f32_e32 v12, 0x3e38aa3b, v103
	v_cndmask_b32_e32 v87, v220, v12, vcc
	ds_read2_b32 v[12:13], v10 offset0:79 offset1:80
	v_cmp_lt_i32_e32 vcc, 47, v0
	s_and_b64 vcc, vcc, s[38:39]
	s_waitcnt lgkmcnt(0)
	v_fmamk_f32 v11, v104, 0x3e38aa3b, v13
	v_cndmask_b32_e32 v88, v220, v11, vcc
	v_cmp_lt_i32_e32 vcc, 48, v0
	s_and_b64 vcc, vcc, s[38:39]
	v_fmac_f32_e32 v12, 0x3e38aa3b, v105
	v_cndmask_b32_e32 v89, v220, v12, vcc
	ds_read2_b32 v[12:13], v10 offset0:77 offset1:78
	v_cmp_lt_i32_e32 vcc, 49, v0
	s_and_b64 vcc, vcc, s[38:39]
	s_waitcnt lgkmcnt(0)
	v_fmamk_f32 v11, v106, 0x3e38aa3b, v13
	v_cndmask_b32_e32 v90, v220, v11, vcc
	v_cmp_lt_i32_e32 vcc, 50, v0
	s_and_b64 vcc, vcc, s[38:39]
	v_fmac_f32_e32 v12, 0x3e38aa3b, v107
	v_cndmask_b32_e32 v91, v220, v12, vcc
	ds_read2_b32 v[12:13], v10 offset0:71 offset1:72
	v_cmp_lt_i32_e32 vcc, 55, v0
	s_and_b64 vcc, vcc, s[38:39]
	s_waitcnt lgkmcnt(0)
	v_fmamk_f32 v11, v108, 0x3e38aa3b, v13
	v_cndmask_b32_e32 v92, v220, v11, vcc
	ds_read2_b32 v[10:11], v10 offset0:69 offset1:70
	v_cmp_lt_i32_e32 vcc, 56, v0
	s_and_b64 vcc, vcc, s[38:39]
	v_fmac_f32_e32 v12, 0x3e38aa3b, v109
	v_cndmask_b32_e32 v93, v220, v12, vcc
	v_cmp_lt_i32_e32 vcc, 57, v0
	s_and_b64 vcc, vcc, s[38:39]
	s_waitcnt lgkmcnt(0)
	v_fmamk_f32 v11, v110, 0x3e38aa3b, v11
	v_cndmask_b32_e32 v94, v220, v11, vcc
	v_cmp_lt_i32_e32 vcc, 58, v0
	s_and_b64 vcc, vcc, s[38:39]
	v_fmac_f32_e32 v10, 0x3e38aa3b, v111
	v_cndmask_b32_e32 v95, v220, v10, vcc

; template <int MODE> ...
;     ...
;             float ps = 0.f;
; #pragma unroll
;             for (int r = 0; r < 16; ++r) { s0[r] = ex2(s0[r]); s1[r] = ex2(s1[r]); ps += s0[r] + s1[r]; }
;             l += ps;
;         } else {
; #pragma unroll
;             for (int r = 0; r < 16; ++r) { s0[r] = ex2(s0[r]) * linv; s1[r] = ex2(s1[r]) * linv; }
;             float quad[8], last[8], recv[8];
; #pragma unroll
;             for (int a = 0; a < 4; ++a) {
;                 quad[a] = (s0[4 * a] + s0[4 * a + 1]) + (s0[4 * a + 2] + s0[4 * a + 3]); last[a] = s0[4 * a + 3];
;                 quad[4 + a] = (s1[4 * a] + s1[4 * a + 1]) + (s1[4 * a + 2] + s1[4 * a + 3]); last[4 + a] = s1[4 * a + 3];
;             }
; #pragma unroll
;             for (int i = 0; i < 8; ++i) recv[i] = half_other(last[i], hl);
; #pragma unroll
;             for (int i = 0; i < 8; ++i) {
;                 const float prev = (i > 0) ? recv[i > 0 ? i - 1 : 0] : carry;
;                 float v = quad[i] + (hl ? recv[i] : prev);
;                 v += __shfl_xor(v, 1); v += __shfl_xor(v, 2);
;                 if ((n & 3) == 0) lds_st<float>(L + score_ofs + (16 * kt + 2 * i + hl) * 4, v);
;             }
;             carry = recv[7];
;         }
;         if (MODE != MODE_CMP1) {
;             bf16x8 pf[4];
; #pragma unroll
;             for (int ks = 0; ks < 4; ++ks) {
;                 const int hb = 8 * (ks & 1); u32x4 w;
;                 if (ks >> 1) { w.x = cvt_pk(s1[hb], s1[hb + 1]); w.y = cvt_pk(s1[hb + 2], s1[hb + 3]); w.z = cvt_pk(s1[hb + 4], s1[hb + 5]); w.w = cvt_pk(s1[hb + 6], s1[hb + 7]); }
;                 else { w.x = cvt_pk(s0[hb], s0[hb + 1]); w.y = cvt_pk(s0[hb + 2], s0[hb + 3]); w.z = cvt_pk(s0[hb + 4], s0[hb + 5]); w.w = cvt_pk(s0[hb + 6], s0[hb + 7]); }
;                 pf[ks] = __builtin_bit_cast(bf16x8, w);
;             }
;             const lptr vb_ = Vt + (4 * hl + q4) * VP + 32 * blk + 8 * p4;
; #pragma unroll
;             for (int c_ = 0; c_ < 2; ++c_)
; #pragma unroll
;                 for (int ks_ = 0; ks_ < 4; ++ks_) {
;                     const s16x4 lo_ = tr16(vb_ + (16 * ks_) * VP + 64 * c_), hi_ = tr16(vb_ + (16 * ks_ + 8) * VP + 64 * c_);
;                     const bf16x8 vf_ = {lo_[0], lo_[1], lo_[2], lo_[3], hi_[0], hi_[1], hi_[2], hi_[3]};
;                     o[c_] = mfma32(vf_, pf[ks_], o[c_]);
;                 }
.LBB0_317:
	v_exp_f32_e32 v98, v64
	v_exp_f32_e32 v99, v80
	v_exp_f32_e32 v0, v65
	v_exp_f32_e32 v10, v81
	v_exp_f32_e32 v100, v82
	v_add_f32_e32 v11, v99, v98
	v_exp_f32_e32 v14, v83
	v_pk_add_f32 v[12:13], v[10:11], v[0:1]
	v_exp_f32_e32 v11, v66
	v_pk_add_f32 v[12:13], v[12:13], v[12:13] op_sel_hi:[0,1]
	v_exp_f32_e32 v12, v67
	v_exp_f32_e32 v66, v85
	v_add_f32_e32 v15, v100, v11
	v_exp_f32_e32 v82, v87
	v_pk_add_f32 v[64:65], v[14:15], v[12:13]
	v_exp_f32_e32 v13, v68
	v_pk_add_f32 v[64:65], v[64:65], v[64:65] op_sel_hi:[0,1]
	v_exp_f32_e32 v15, v84
	v_exp_f32_e32 v64, v69
	v_exp_f32_e32 v72, v72
	v_exp_f32_e32 v96, v91
	v_add_f32_e32 v67, v15, v13
	v_pk_add_f32 v[68:69], v[66:67], v[64:65]
	v_exp_f32_e32 v65, v70
	v_pk_add_f32 v[80:81], v[68:69], v[68:69] op_sel_hi:[0,1]
	v_exp_f32_e32 v67, v86
	v_exp_f32_e32 v80, v71
	v_exp_f32_e32 v86, v89
	v_cvt_pk_bf16_f32 v70, v13, v64
	v_add_f32_e32 v83, v67, v65
	v_pk_add_f32 v[68:69], v[82:83], v[80:81]
	v_exp_f32_e32 v81, v88
	v_pk_add_f32 v[84:85], v[68:69], v[68:69] op_sel_hi:[0,1]
	v_exp_f32_e32 v84, v73
	v_exp_f32_e32 v73, v74
	v_add_f32_e32 v87, v81, v72
	v_exp_f32_e32 v83, v90
	v_pk_add_f32 v[68:69], v[86:87], v[84:85]
	v_exp_f32_e32 v85, v76
	v_pk_add_f32 v[88:89], v[68:69], v[68:69] op_sel_hi:[0,1]
	v_exp_f32_e32 v88, v75
	v_add_f32_e32 v97, v83, v73
	v_exp_f32_e32 v87, v92
	v_exp_f32_e32 v90, v93
	v_pk_add_f32 v[68:69], v[96:97], v[88:89]
	v_exp_f32_e32 v92, v95
	v_pk_add_f32 v[74:75], v[68:69], v[68:69] op_sel_hi:[0,1]
	v_exp_f32_e32 v74, v77
	v_add_f32_e32 v91, v87, v85
	v_cvt_pk_bf16_f32 v71, v65, v80
	v_cvt_pk_bf16_f32 v72, v72, v84
	v_pk_add_f32 v[68:69], v[90:91], v[74:75]
	v_exp_f32_e32 v75, v78
	v_pk_add_f32 v[76:77], v[68:69], v[68:69] op_sel_hi:[0,1]
	v_exp_f32_e32 v78, v94
	v_exp_f32_e32 v76, v79
	v_cvt_pk_bf16_f32 v73, v73, v88
	v_cvt_pk_bf16_f32 v74, v85, v74
	v_add_f32_e32 v93, v78, v75
	v_pk_add_f32 v[68:69], v[92:93], v[76:77]
	v_cvt_pk_bf16_f32 v75, v75, v76
	v_add_f32_e32 v68, v68, v69
	v_add_f32_e32 v178, v178, v68
	v_cvt_pk_bf16_f32 v68, v98, v0
	v_add_u32_e32 v0, v186, v187
	v_cvt_pk_bf16_f32 v13, v78, v92
	v_cvt_pk_bf16_f32 v69, v11, v12
	v_cvt_pk_bf16_f32 v64, v99, v10
	v_cvt_pk_bf16_f32 v65, v100, v14
	s_waitcnt lgkmcnt(0)
	s_waitcnt lgkmcnt(0)
	v_mfma_f32_32x32x16_bf16 v[32:47], v[196:199], v[68:71], v[32:47]
	v_cvt_pk_bf16_f32 v66, v15, v66
	v_cvt_pk_bf16_f32 v67, v67, v82
	v_cvt_pk_bf16_f32 v10, v81, v86
	v_cvt_pk_bf16_f32 v11, v83, v96
	v_cvt_pk_bf16_f32 v12, v87, v90
	v_mfma_f32_32x32x16_bf16 v[32:47], v[200:203], v[72:75], v[32:47]
	v_mfma_f32_32x32x16_bf16 v[32:47], v[204:207], v[64:67], v[32:47]
	v_mfma_f32_32x32x16_bf16 v[32:47], v[208:211], v[10:13], v[32:47]
	v_mfma_f32_32x32x16_bf16 v[16:31], v[238:241], v[68:71], v[16:31]
	v_mfma_f32_32x32x16_bf16 v[16:31], v[242:245], v[72:75], v[16:31]
	v_mfma_f32_32x32x16_bf16 v[16:31], v[246:249], v[64:67], v[16:31]
	v_mfma_f32_32x32x16_bf16 v[16:31], v[234:237], v[10:13], v[16:31]

; __device__ __forceinline__ f32x16 mfma32(bf16x8 a, bf16x8 b, f32x16 c) { return __builtin_amdgcn_mfma_f32_32x32x16_bf16(a, b, c, 0, 0, 0); }
; __device__ __forceinline__ s16x4 tr16(lptr p) { return __builtin_bit_cast(s16x4, __builtin_amdgcn_ds_read_tr16_b64_v4i16((LAS v4i16_t*)p)); }
; template <int MODE> ...
;     ...
;     const bool selbit = (MODE == MODE_SEL) ? ((((kt < 32) ? (mlo >> kt) : (mhi >> (kt - 32))) & 1u) != 0u) : true;
;     if (MODE == MODE_SEL) active = __any(selbit) != 0;
;     if (active) {
;         const lptr Kt = L + A_KT + buf * 9216, Vt = L + A_VT + vcur * 12288;
;         f32x16 s0, s1;
; #pragma unroll
;         for (int s4 = 0; s4 < 4; ++s4) {
;             const bf16x8 a0 = lds_ld<bf16x8>(Kt + n * KP + s4 * 32 + hl * 16);
;             const bf16x8 a1 = lds_ld<bf16x8>(Kt + (32 + n) * KP + s4 * 32 + hl * 16);
;             if (s4 == 0) { s0 = mfma32(a0, qf[0], negm); s1 = mfma32(a1, qf[0], negm); }
;             else { s0 = mfma32(a0, qf[s4], s0); s1 = mfma32(a1, qf[s4], s1); }
;         }
;     ...
;             const lptr vb_ = Vt + (4 * hl + q4) * VP + 32 * blk + 8 * p4;
; #pragma unroll
;             for (int c_ = 0; c_ < 2; ++c_)
; #pragma unroll
;                 for (int ks_ = 0; ks_ < 4; ++ks_) {
;                     const s16x4 lo_ = tr16(vb_ + (16 * ks_) * VP + 64 * c_), hi_ = tr16(vb_ + (16 * ks_ + 8) * VP + 64 * c_);
.LBB0_323:
	v_sub_co_u32_e64 v10, vcc, s18, 32
	v_lshrrev_b32_e32 v0, s18, v160
	v_lshrrev_b32_e32 v10, v10, v161
	v_cndmask_b32_e32 v0, v10, v0, vcc
	v_and_b32_e32 v0, 1, v0
	v_cmp_eq_u32_e64 s[38:39], 1, v0
	v_cmp_ne_u32_e32 vcc, 0, v0
	s_cbranch_vccz .LBB0_331
	v_add_u32_e32 v14, v182, v183
	v_add_u32_e32 v212, v186, v187
	ds_read_b128 v[10:13], v14 offset:9216
	ds_read_b128 v[64:67], v14 offset:9248
	v_add_u32_e32 v0, v184, v183
	s_lshl_b32 s13, s18, 6
	v_cmp_ge_i32_e32 vcc, s13, v179
	s_waitcnt lgkmcnt(1)
	v_mfma_f32_32x32x16_bf16 v[112:127], v[10:13], v[128:131], v[48:63]
	ds_read_b64_tr_b16 v[196:197], v212 offset:30720
	ds_read_b64_tr_b16 v[198:199], v212 offset:32256
	ds_read_b128 v[10:13], v0 offset:9216
	ds_read_b128 v[68:71], v0 offset:9248
	s_waitcnt lgkmcnt(1)
	v_mfma_f32_32x32x16_bf16 v[96:111], v[10:13], v[128:131], v[48:63]
	ds_read_b64_tr_b16 v[200:201], v212 offset:33792
	ds_read_b64_tr_b16 v[202:203], v212 offset:35328
	s_waitcnt lgkmcnt(6)
	v_mfma_f32_32x32x16_bf16 v[112:127], v[64:67], v[132:135], v[112:127]
	ds_read_b64_tr_b16 v[204:205], v212 offset:36864
	ds_read_b64_tr_b16 v[206:207], v212 offset:38400
	ds_read_b128 v[10:13], v0 offset:9280
	ds_read_b128 v[64:67], v14 offset:9280
	s_waitcnt lgkmcnt(6)
	v_mfma_f32_32x32x16_bf16 v[96:111], v[68:71], v[132:135], v[96:111]
	ds_read_b64_tr_b16 v[208:209], v212 offset:39936
	ds_read_b64_tr_b16 v[210:211], v212 offset:41472
	s_waitcnt lgkmcnt(2)
	v_mfma_f32_32x32x16_bf16 v[112:127], v[64:67], v[136:139], v[112:127]
	ds_read_b64_tr_b16 v[238:239], v212 offset:30784
	ds_read_b64_tr_b16 v[240:241], v212 offset:32320
	s_waitcnt lgkmcnt(5)
	v_mfma_f32_32x32x16_bf16 v[96:111], v[10:13], v[136:139], v[96:111]
	ds_read_b64_tr_b16 v[242:243], v212 offset:33856
	ds_read_b64_tr_b16 v[244:245], v212 offset:35392
	ds_read_b128 v[10:13], v0 offset:9312
	ds_read_b128 v[64:67], v14 offset:9312
	s_waitcnt lgkmcnt(0)
	v_mfma_f32_32x32x16_bf16 v[112:127], v[64:67], v[140:143], v[112:127]
	ds_read_b64_tr_b16 v[246:247], v212 offset:36928
	ds_read_b64_tr_b16 v[248:249], v212 offset:38464
	s_waitcnt lgkmcnt(3)
	v_mfma_f32_32x32x16_bf16 v[96:111], v[10:13], v[140:143], v[96:111]
	ds_read_b64_tr_b16 v[234:235], v212 offset:40000
	ds_read_b64_tr_b16 v[236:237], v212 offset:41536
	s_and_saveexec_b64 s[0:1], vcc
	s_xor_b64 s[0:1], exec, s[0:1]
	s_cbranch_execz .LBB0_326
; template <int MODE> ...
;     ...
;         } else if (MODE == MODE_WIN || MODE == MODE_SEL) {
;             const int dbase = t - kbase;
;             const lptr tb = L + tabofs + (dbase + TAB0 - 63) * 4;
; #pragma unroll
;             for (int kb = 0; kb < 2; ++kb)
; #pragma unroll
;                 for (int a = 0; a < 4; ++a)
; #pragma unroll
;                     for (int e = 0; e < 4; ++e) {
;                         const int r = 4 * a + e, off = 32 * kb + 8 * a + e; const int d = dbase - off;
;                         const float bsv = far ? tab128 : lds_ld<float>(tb + 4 * (63 - off));
;                         const bool ok = (MODE == MODE_WIN) ? ((unsigned)d < (unsigned)W) : (selbit && d >= 0);
;                         const float sv = kb ? s1[r] : s0[r];
;                         const float x = ok ? sv * SC2 + bsv : -INFINITY;
;                         if (kb) s1[r] = x; else s0[r] = x;
;                     }
	v_or_b32_e32 v0, s13, v185
	v_sub_u32_e32 v0, v229, v0
	v_lshl_add_u32 v10, v0, 2, v230
	ds_read2_b32 v[12:13], v10 offset0:127 offset1:128
	v_cmp_lt_i32_e32 vcc, -1, v0
	s_and_b64 vcc, vcc, s[38:39]
	s_waitcnt lgkmcnt(0)
	s_nop 0
	v_fmamk_f32 v11, v112, 0x3e38aa3b, v13
	v_cndmask_b32_e32 v64, v220, v11, vcc
	v_cmp_lt_i32_e32 vcc, 0, v0
	s_and_b64 vcc, vcc, s[38:39]
	v_fmac_f32_e32 v12, 0x3e38aa3b, v113
	v_cndmask_b32_e32 v65, v220, v12, vcc
	ds_read2_b32 v[12:13], v10 offset0:125 offset1:126
	v_cmp_lt_i32_e32 vcc, 1, v0
	s_and_b64 vcc, vcc, s[38:39]
	s_waitcnt lgkmcnt(0)
	v_fmamk_f32 v11, v114, 0x3e38aa3b, v13
	v_cndmask_b32_e32 v66, v220, v11, vcc
	v_cmp_lt_i32_e32 vcc, 2, v0
	s_and_b64 vcc, vcc, s[38:39]
	v_fmac_f32_e32 v12, 0x3e38aa3b, v115
	v_cndmask_b32_e32 v67, v220, v12, vcc
	ds_read2_b32 v[12:13], v10 offset0:119 offset1:120
	v_cmp_lt_i32_e32 vcc, 7, v0
	s_and_b64 vcc, vcc, s[38:39]
	s_waitcnt lgkmcnt(0)
	v_fmamk_f32 v11, v116, 0x3e38aa3b, v13
	v_cndmask_b32_e32 v68, v220, v11, vcc
	v_cmp_lt_i32_e32 vcc, 8, v0
	s_and_b64 vcc, vcc, s[38:39]
	v_fmac_f32_e32 v12, 0x3e38aa3b, v117
	v_cndmask_b32_e32 v69, v220, v12, vcc
	ds_read2_b32 v[12:13], v10 offset0:117 offset1:118
	v_cmp_lt_i32_e32 vcc, 9, v0
	s_and_b64 vcc, vcc, s[38:39]
	s_waitcnt lgkmcnt(0)
	v_fmamk_f32 v11, v118, 0x3e38aa3b, v13
	v_cndmask_b32_e32 v70, v220, v11, vcc
	v_cmp_lt_i32_e32 vcc, 10, v0
	s_and_b64 vcc, vcc, s[38:39]
	v_fmac_f32_e32 v12, 0x3e38aa3b, v119
	v_cndmask_b32_e32 v71, v220, v12, vcc
	ds_read2_b32 v[12:13], v10 offset0:111 offset1:112
	v_cmp_lt_i32_e32 vcc, 15, v0
	s_and_b64 vcc, vcc, s[38:39]
	s_waitcnt lgkmcnt(0)
	v_fmamk_f32 v11, v120, 0x3e38aa3b, v13
	v_cndmask_b32_e32 v72, v220, v11, vcc
	v_cmp_lt_i32_e32 vcc, 16, v0
	s_and_b64 vcc, vcc, s[38:39]
	v_fmac_f32_e32 v12, 0x3e38aa3b, v121
	v_cndmask_b32_e32 v73, v220, v12, vcc
	ds_read2_b32 v[12:13], v10 offset0:109 offset1:110
	v_cmp_lt_i32_e32 vcc, 17, v0
	s_and_b64 vcc, vcc, s[38:39]
	s_waitcnt lgkmcnt(0)
	v_fmamk_f32 v11, v122, 0x3e38aa3b, v13
	v_cndmask_b32_e32 v74, v220, v11, vcc
	v_cmp_lt_i32_e32 vcc, 18, v0
	s_and_b64 vcc, vcc, s[38:39]
	v_fmac_f32_e32 v12, 0x3e38aa3b, v123
	v_cndmask_b32_e32 v75, v220, v12, vcc
	ds_read2_b32 v[12:13], v10 offset0:103 offset1:104
	v_cmp_lt_i32_e32 vcc, 23, v0
	s_and_b64 vcc, vcc, s[38:39]
	s_waitcnt lgkmcnt(0)
	v_fmamk_f32 v11, v124, 0x3e38aa3b, v13
	v_cndmask_b32_e32 v76, v220, v11, vcc
	v_cmp_lt_i32_e32 vcc, 24, v0
	s_and_b64 vcc, vcc, s[38:39]
	v_fmac_f32_e32 v12, 0x3e38aa3b, v125
	v_cndmask_b32_e32 v77, v220, v12, vcc
	ds_read2_b32 v[12:13], v10 offset0:101 offset1:102
	v_cmp_lt_i32_e32 vcc, 25, v0
	s_and_b64 vcc, vcc, s[38:39]
	s_waitcnt lgkmcnt(0)
	v_fmamk_f32 v11, v126, 0x3e38aa3b, v13
	v_cndmask_b32_e32 v78, v220, v11, vcc
	v_cmp_lt_i32_e32 vcc, 26, v0
	s_and_b64 vcc, vcc, s[38:39]
	v_fmac_f32_e32 v12, 0x3e38aa3b, v127
	v_cndmask_b32_e32 v79, v220, v12, vcc
	ds_read2_b32 v[12:13], v10 offset0:95 offset1:96
	v_cmp_lt_i32_e32 vcc, 31, v0
	s_and_b64 vcc, vcc, s[38:39]
	s_waitcnt lgkmcnt(0)
	v_fmamk_f32 v11, v96, 0x3e38aa3b, v13
	v_cndmask_b32_e32 v80, v220, v11, vcc
	v_cmp_lt_i32_e32 vcc, 32, v0
	s_and_b64 vcc, vcc, s[38:39]
	v_fmac_f32_e32 v12, 0x3e38aa3b, v97
	v_cndmask_b32_e32 v81, v220, v12, vcc
	ds_read2_b32 v[12:13], v10 offset0:93 offset1:94
	v_cmp_lt_i32_e32 vcc, 33, v0
	s_and_b64 vcc, vcc, s[38:39]
	s_waitcnt lgkmcnt(0)
	v_fmamk_f32 v11, v98, 0x3e38aa3b, v13
	v_cndmask_b32_e32 v82, v220, v11, vcc
	v_cmp_lt_i32_e32 vcc, 34, v0
	s_and_b64 vcc, vcc, s[38:39]
	v_fmac_f32_e32 v12, 0x3e38aa3b, v99
	v_cndmask_b32_e32 v83, v220, v12, vcc
	ds_read2_b32 v[12:13], v10 offset0:87 offset1:88
	v_cmp_lt_i32_e32 vcc, 39, v0
	s_and_b64 vcc, vcc, s[38:39]
	s_waitcnt lgkmcnt(0)
	v_fmamk_f32 v11, v100, 0x3e38aa3b, v13
	v_cndmask_b32_e32 v84, v220, v11, vcc
	v_cmp_lt_i32_e32 vcc, 40, v0
	s_and_b64 vcc, vcc, s[38:39]
	v_fmac_f32_e32 v12, 0x3e38aa3b, v101
	v_cndmask_b32_e32 v85, v220, v12, vcc
	ds_read2_b32 v[12:13], v10 offset0:85 offset1:86
	v_cmp_lt_i32_e32 vcc, 41, v0
	s_and_b64 vcc, vcc, s[38:39]
	s_waitcnt lgkmcnt(0)
	v_fmamk_f32 v11, v102, 0x3e38aa3b, v13
	v_cndmask_b32_e32 v86, v220, v11, vcc
	v_cmp_lt_i32_e32 vcc, 42, v0
	s_and_b64 vcc, vcc, s[38:39]
	v_fmac_f32_e32 v12, 0x3e38aa3b, v103
	v_cndmask_b32_e32 v87, v220, v12, vcc
	ds_read2_b32 v[12:13], v10 offset0:79 offset1:80
	v_cmp_lt_i32_e32 vcc, 47, v0
	s_and_b64 vcc, vcc, s[38:39]
	s_waitcnt lgkmcnt(0)
	v_fmamk_f32 v11, v104, 0x3e38aa3b, v13
	v_cndmask_b32_e32 v88, v220, v11, vcc
	v_cmp_lt_i32_e32 vcc, 48, v0
	s_and_b64 vcc, vcc, s[38:39]
	v_fmac_f32_e32 v12, 0x3e38aa3b, v105
	v_cndmask_b32_e32 v89, v220, v12, vcc
	ds_read2_b32 v[12:13], v10 offset0:77 offset1:78
	v_cmp_lt_i32_e32 vcc, 49, v0
	s_and_b64 vcc, vcc, s[38:39]
	s_waitcnt lgkmcnt(0)
	v_fmamk_f32 v11, v106, 0x3e38aa3b, v13
	v_cndmask_b32_e32 v90, v220, v11, vcc
	v_cmp_lt_i32_e32 vcc, 50, v0
	s_and_b64 vcc, vcc, s[38:39]
	v_fmac_f32_e32 v12, 0x3e38aa3b, v107
	v_cndmask_b32_e32 v91, v220, v12, vcc
	ds_read2_b32 v[12:13], v10 offset0:71 offset1:72
	v_cmp_lt_i32_e32 vcc, 55, v0
	s_and_b64 vcc, vcc, s[38:39]
	s_waitcnt lgkmcnt(0)
	v_fmamk_f32 v11, v108, 0x3e38aa3b, v13
	v_cndmask_b32_e32 v92, v220, v11, vcc
	ds_read2_b32 v[10:11], v10 offset0:69 offset1:70
	v_cmp_lt_i32_e32 vcc, 56, v0
	s_and_b64 vcc, vcc, s[38:39]
	v_fmac_f32_e32 v12, 0x3e38aa3b, v109
	v_cndmask_b32_e32 v93, v220, v12, vcc
	v_cmp_lt_i32_e32 vcc, 57, v0
	s_and_b64 vcc, vcc, s[38:39]
	s_waitcnt lgkmcnt(0)
	v_fmamk_f32 v11, v110, 0x3e38aa3b, v11
	v_cndmask_b32_e32 v94, v220, v11, vcc
	v_cmp_lt_i32_e32 vcc, 58, v0
	s_and_b64 vcc, vcc, s[38:39]
	v_fmac_f32_e32 v10, 0x3e38aa3b, v111
	v_cndmask_b32_e32 v95, v220, v10, vcc

; __device__ __forceinline__ f32x16 mfma32(bf16x8 a, bf16x8 b, f32x16 c) { return __builtin_amdgcn_mfma_f32_32x32x16_bf16(a, b, c, 0, 0, 0); }
; __device__ __forceinline__ s16x4 tr16(lptr p) { return __builtin_bit_cast(s16x4, __builtin_amdgcn_ds_read_tr16_b64_v4i16((LAS v4i16_t*)p)); }
; template <int MODE> ...
;     ...
;         const lptr Kt = L + A_KT + buf * 9216, Vt = L + A_VT + vcur * 12288;
;         f32x16 s0, s1;
; #pragma unroll
;         for (int s4 = 0; s4 < 4; ++s4) {
;             const bf16x8 a0 = lds_ld<bf16x8>(Kt + n * KP + s4 * 32 + hl * 16);
;             const bf16x8 a1 = lds_ld<bf16x8>(Kt + (32 + n) * KP + s4 * 32 + hl * 16);
;             if (s4 == 0) { s0 = mfma32(a0, qf[0], negm); s1 = mfma32(a1, qf[0], negm); }
;             else { s0 = mfma32(a0, qf[s4], s0); s1 = mfma32(a1, qf[s4], s1); }
;         }
;         const int kbase = 64 * kt + 4 * hl;
;         const bool far = (MODE == MODE_WIN || MODE == MODE_SEL) ? (wtmin - (64 * kt + 63) >= 128) : false;
;         const bool fmask = (MODE == MODE_FOX) ? (64 * kt + 63 > wtmin) : false;
;         const bool clean = (MODE == MODE_WIN) ? (far && (wtmax - 64 * kt < W)) : false;
;         const float mref = (MODE == MODE_CMP2) ? mfix : ((m == -INFINITY) ? 0.f : m);
;     ...
;             const lptr vb_ = Vt + (4 * hl + q4) * VP + 32 * blk + 8 * p4;
; #pragma unroll
;             for (int c_ = 0; c_ < 2; ++c_)
; #pragma unroll
;                 for (int ks_ = 0; ks_ < 4; ++ks_) {
;                     const s16x4 lo_ = tr16(vb_ + (16 * ks_) * VP + 64 * c_), hi_ = tr16(vb_ + (16 * ks_ + 8) * VP + 64 * c_);
.LBB0_344:
	ds_read_b128 v[10:13], v191
	ds_read_b128 v[80:83], v191 offset:32
	s_lshl_b32 s6, s0, 6
	v_cmp_ge_i32_e32 vcc, s6, v186
	v_cmp_le_i32_e64 s[0:1], s6, v187
	s_waitcnt lgkmcnt(1)
	v_mfma_f32_32x32x16_bf16 v[112:127], v[10:13], v[128:131], v[48:63]
	ds_read_b64_tr_b16 v[196:197], v192 offset:18432
	ds_read_b64_tr_b16 v[198:199], v192 offset:19968
	ds_read_b128 v[10:13], v190
	ds_read_b128 v[84:87], v190 offset:32
	s_or_b64 s[0:1], vcc, s[0:1]
	s_waitcnt lgkmcnt(1)
	v_mfma_f32_32x32x16_bf16 v[64:79], v[10:13], v[128:131], v[48:63]
	ds_read_b64_tr_b16 v[200:201], v192 offset:21504
	ds_read_b64_tr_b16 v[202:203], v192 offset:23040
	s_waitcnt lgkmcnt(6)
	v_mfma_f32_32x32x16_bf16 v[112:127], v[80:83], v[132:135], v[112:127]
	ds_read_b64_tr_b16 v[204:205], v192 offset:24576
	ds_read_b64_tr_b16 v[206:207], v192 offset:26112
	ds_read_b128 v[10:13], v190 offset:64
	ds_read_b128 v[80:83], v191 offset:64
	s_waitcnt lgkmcnt(6)
	v_mfma_f32_32x32x16_bf16 v[64:79], v[84:87], v[132:135], v[64:79]
	ds_read_b64_tr_b16 v[208:209], v192 offset:27648
	ds_read_b64_tr_b16 v[210:211], v192 offset:29184
	s_waitcnt lgkmcnt(2)
	v_mfma_f32_32x32x16_bf16 v[112:127], v[80:83], v[136:139], v[112:127]
	ds_read_b64_tr_b16 v[238:239], v192 offset:18496
	ds_read_b64_tr_b16 v[240:241], v192 offset:20032
	s_waitcnt lgkmcnt(5)
	v_mfma_f32_32x32x16_bf16 v[64:79], v[10:13], v[136:139], v[64:79]
	ds_read_b64_tr_b16 v[242:243], v192 offset:21568
	ds_read_b64_tr_b16 v[244:245], v192 offset:23104
	ds_read_b128 v[10:13], v190 offset:96
	ds_read_b128 v[80:83], v191 offset:96
	s_waitcnt lgkmcnt(0)
	v_mfma_f32_32x32x16_bf16 v[112:127], v[80:83], v[140:143], v[112:127]
	ds_read_b64_tr_b16 v[246:247], v192 offset:24640
	ds_read_b64_tr_b16 v[248:249], v192 offset:26176
	s_waitcnt lgkmcnt(3)
	v_mfma_f32_32x32x16_bf16 v[64:79], v[10:13], v[140:143], v[64:79]
	ds_read_b64_tr_b16 v[234:235], v192 offset:27712
	ds_read_b64_tr_b16 v[236:237], v192 offset:29248
	s_and_saveexec_b64 s[38:39], s[0:1]
	s_xor_b64 s[0:1], exec, s[38:39]
	s_cbranch_execz .LBB0_379
	v_or_b32_e32 v0, s6, v145
	v_sub_u32_e32 v0, v229, v0
	v_lshlrev_b32_e32 v10, 2, v0
	v_add_u32_e32 v80, v230, v10
	v_mov_b32_e32 v10, v146
	s_and_saveexec_b64 s[6:7], vcc
	s_cbranch_execnz .LBB0_431
	s_or_b64 exec, exec, s[6:7]
	v_mov_b32_e32 v11, v146
	s_and_saveexec_b64 s[6:7], vcc
	s_cbranch_execnz .LBB0_432

; template <int MODE> ...
;     ...
;             float ps = 0.f;
; #pragma unroll
;             for (int r = 0; r < 16; ++r) { s0[r] = ex2(s0[r]); s1[r] = ex2(s1[r]); ps += s0[r] + s1[r]; }
;             l += ps;
;         } else {
; #pragma unroll
;             for (int r = 0; r < 16; ++r) { s0[r] = ex2(s0[r]) * linv; s1[r] = ex2(s1[r]) * linv; }
;             float quad[8], last[8], recv[8];
; #pragma unroll
;             for (int a = 0; a < 4; ++a) {
;                 quad[a] = (s0[4 * a] + s0[4 * a + 1]) + (s0[4 * a + 2] + s0[4 * a + 3]); last[a] = s0[4 * a + 3];
;                 quad[4 + a] = (s1[4 * a] + s1[4 * a + 1]) + (s1[4 * a + 2] + s1[4 * a + 3]); last[4 + a] = s1[4 * a + 3];
;             }
; #pragma unroll
;             for (int i = 0; i < 8; ++i) recv[i] = half_other(last[i], hl);
; #pragma unroll
;             for (int i = 0; i < 8; ++i) {
;                 const float prev = (i > 0) ? recv[i > 0 ? i - 1 : 0] : carry;
;                 float v = quad[i] + (hl ? recv[i] : prev);
;                 v += __shfl_xor(v, 1); v += __shfl_xor(v, 2);
;                 if ((n & 3) == 0) lds_st<float>(L + score_ofs + (16 * kt + 2 * i + hl) * 4, v);
;             }
;             carry = recv[7];
;         }
;         if (MODE != MODE_CMP1) {
;             bf16x8 pf[4];
; #pragma unroll
;             for (int ks = 0; ks < 4; ++ks) {
;                 const int hb = 8 * (ks & 1); u32x4 w;
;                 if (ks >> 1) { w.x = cvt_pk(s1[hb], s1[hb + 1]); w.y = cvt_pk(s1[hb + 2], s1[hb + 3]); w.z = cvt_pk(s1[hb + 4], s1[hb + 5]); w.w = cvt_pk(s1[hb + 6], s1[hb + 7]); }
;                 else { w.x = cvt_pk(s0[hb], s0[hb + 1]); w.y = cvt_pk(s0[hb + 2], s0[hb + 3]); w.z = cvt_pk(s0[hb + 4], s0[hb + 5]); w.w = cvt_pk(s0[hb + 6], s0[hb + 7]); }
;                 pf[ks] = __builtin_bit_cast(bf16x8, w);
;             }
;             const lptr vb_ = Vt + (4 * hl + q4) * VP + 32 * blk + 8 * p4;
; #pragma unroll
;             for (int c_ = 0; c_ < 2; ++c_)
; #pragma unroll
;                 for (int ks_ = 0; ks_ < 4; ++ks_) {
;                     const s16x4 lo_ = tr16(vb_ + (16 * ks_) * VP + 64 * c_), hi_ = tr16(vb_ + (16 * ks_ + 8) * VP + 64 * c_);
;                     const bf16x8 vf_ = {lo_[0], lo_[1], lo_[2], lo_[3], hi_[0], hi_[1], hi_[2], hi_[3]};
;                     o[c_] = mfma32(vf_, pf[ks_], o[c_]);
;                 }
.LBB0_384:
	v_exp_f32_e32 v0, v96
	v_exp_f32_e32 v14, v97
	v_exp_f32_e32 v15, v98
	v_exp_f32_e32 v96, v99
	v_exp_f32_e32 v97, v100
	v_exp_f32_e32 v100, v84
	v_exp_f32_e32 v84, v101
	v_exp_f32_e32 v101, v85
	v_exp_f32_e32 v85, v102
	v_exp_f32_e32 v102, v86
	v_exp_f32_e32 v86, v103
	v_cvt_pk_bf16_f32 v118, v0, v14
	v_cvt_pk_bf16_f32 v119, v15, v96
	v_cvt_pk_bf16_f32 v120, v97, v84
	v_cvt_pk_bf16_f32 v121, v85, v86
	v_exp_f32_e32 v103, v87
	v_exp_f32_e32 v87, v104
	s_waitcnt lgkmcnt(0)
	s_waitcnt lgkmcnt(0)
	v_mfma_f32_32x32x16_bf16 v[32:47], v[196:199], v[118:121], v[32:47]
	v_exp_f32_e32 v104, v88
	v_exp_f32_e32 v88, v105
	v_exp_f32_e32 v105, v89
	v_exp_f32_e32 v89, v106
	v_exp_f32_e32 v106, v90
	v_exp_f32_e32 v90, v107
	v_exp_f32_e32 v107, v91
	v_exp_f32_e32 v91, v108
	v_exp_f32_e32 v108, v92
	v_exp_f32_e32 v92, v109
	v_exp_f32_e32 v109, v93
	v_exp_f32_e32 v93, v110
	v_exp_f32_e32 v110, v94
	v_exp_f32_e32 v94, v111
	v_cvt_pk_bf16_f32 v114, v87, v88
	v_cvt_pk_bf16_f32 v115, v89, v90
	v_cvt_pk_bf16_f32 v116, v91, v92
	v_cvt_pk_bf16_f32 v117, v93, v94
	v_exp_f32_e32 v112, v80
	v_exp_f32_e32 v113, v81
	v_mfma_f32_32x32x16_bf16 v[32:47], v[200:203], v[114:117], v[32:47]
	v_exp_f32_e32 v98, v82
	v_exp_f32_e32 v99, v83
	v_cvt_pk_bf16_f32 v80, v112, v113
	v_cvt_pk_bf16_f32 v82, v100, v101
	v_cvt_pk_bf16_f32 v81, v98, v99
	v_cvt_pk_bf16_f32 v83, v102, v103
	v_exp_f32_e32 v95, v95
	v_cvt_pk_bf16_f32 v10, v104, v105
	v_mfma_f32_32x32x16_bf16 v[32:47], v[204:207], v[80:83], v[32:47]
	v_cvt_pk_bf16_f32 v11, v106, v107
	v_cvt_pk_bf16_f32 v12, v108, v109
	v_cvt_pk_bf16_f32 v13, v110, v95
	s_cmp_lt_i32 s18, 0
	s_nop 1
	v_mfma_f32_32x32x16_bf16 v[32:47], v[208:211], v[10:13], v[32:47]
	v_mfma_f32_32x32x16_bf16 v[16:31], v[238:241], v[118:121], v[16:31]
	v_mfma_f32_32x32x16_bf16 v[16:31], v[242:245], v[114:117], v[16:31]
	v_mfma_f32_32x32x16_bf16 v[16:31], v[246:249], v[80:83], v[16:31]
	v_mfma_f32_32x32x16_bf16 v[16:31], v[234:237], v[10:13], v[16:31]
	s_cbranch_scc1 .LBB0_386
	v_add_u32_e32 v10, v144, v183
	s_waitcnt vmcnt(1)
	ds_write_b128 v189, v[152:155] offset:9216
	s_waitcnt vmcnt(0)
	ds_write_b128 v10, v[156:159] offset:30720

; __device__ __forceinline__ f32x16 mfma32(bf16x8 a, bf16x8 b, f32x16 c) { return __builtin_amdgcn_mfma_f32_32x32x16_bf16(a, b, c, 0, 0, 0); }
; __device__ __forceinline__ s16x4 tr16(lptr p) { return __builtin_bit_cast(s16x4, __builtin_amdgcn_ds_read_tr16_b64_v4i16((LAS v4i16_t*)p)); }
; template <int MODE> ...
;     ...
;         const lptr Kt = L + A_KT + buf * 9216, Vt = L + A_VT + vcur * 12288;
;         f32x16 s0, s1;
; #pragma unroll
;         for (int s4 = 0; s4 < 4; ++s4) {
;             const bf16x8 a0 = lds_ld<bf16x8>(Kt + n * KP + s4 * 32 + hl * 16);
;             const bf16x8 a1 = lds_ld<bf16x8>(Kt + (32 + n) * KP + s4 * 32 + hl * 16);
;             if (s4 == 0) { s0 = mfma32(a0, qf[0], negm); s1 = mfma32(a1, qf[0], negm); }
;             else { s0 = mfma32(a0, qf[s4], s0); s1 = mfma32(a1, qf[s4], s1); }
;         }
;         const int kbase = 64 * kt + 4 * hl;
;         const bool far = (MODE == MODE_WIN || MODE == MODE_SEL) ? (wtmin - (64 * kt + 63) >= 128) : false;
;         const bool fmask = (MODE == MODE_FOX) ? (64 * kt + 63 > wtmin) : false;
;         const bool clean = (MODE == MODE_WIN) ? (far && (wtmax - 64 * kt < W)) : false;
;         const float mref = (MODE == MODE_CMP2) ? mfix : ((m == -INFINITY) ? 0.f : m);
;     ...
;             const lptr vb_ = Vt + (4 * hl + q4) * VP + 32 * blk + 8 * p4;
; #pragma unroll
;             for (int c_ = 0; c_ < 2; ++c_)
; #pragma unroll
;                 for (int ks_ = 0; ks_ < 4; ++ks_) {
;                     const s16x4 lo_ = tr16(vb_ + (16 * ks_) * VP + 64 * c_), hi_ = tr16(vb_ + (16 * ks_ + 8) * VP + 64 * c_);
.LBB0_389:
	ds_read_b128 v[10:13], v191 offset:9216
	ds_read_b128 v[80:83], v191 offset:9248
	s_lshl_b32 s6, s18, 6
	v_cmp_ge_i32_e32 vcc, s6, v186
	v_cmp_le_i32_e64 s[0:1], s6, v187
	s_waitcnt lgkmcnt(1)
	v_mfma_f32_32x32x16_bf16 v[112:127], v[10:13], v[128:131], v[64:79]
	ds_read_b64_tr_b16 v[196:197], v192 offset:30720
	ds_read_b64_tr_b16 v[198:199], v192 offset:32256
	ds_read_b128 v[10:13], v190 offset:9216
	ds_read_b128 v[84:87], v190 offset:9248
	s_or_b64 s[0:1], vcc, s[0:1]
	s_waitcnt lgkmcnt(1)
	v_mfma_f32_32x32x16_bf16 v[64:79], v[10:13], v[128:131], v[64:79]
	ds_read_b64_tr_b16 v[200:201], v192 offset:33792
	ds_read_b64_tr_b16 v[202:203], v192 offset:35328
	s_waitcnt lgkmcnt(6)
	v_mfma_f32_32x32x16_bf16 v[112:127], v[80:83], v[132:135], v[112:127]
	ds_read_b64_tr_b16 v[204:205], v192 offset:36864
	ds_read_b64_tr_b16 v[206:207], v192 offset:38400
	ds_read_b128 v[10:13], v190 offset:9280
	ds_read_b128 v[80:83], v191 offset:9280
	s_waitcnt lgkmcnt(6)
	v_mfma_f32_32x32x16_bf16 v[64:79], v[84:87], v[132:135], v[64:79]
	ds_read_b64_tr_b16 v[208:209], v192 offset:39936
	ds_read_b64_tr_b16 v[210:211], v192 offset:41472
	s_waitcnt lgkmcnt(2)
	v_mfma_f32_32x32x16_bf16 v[112:127], v[80:83], v[136:139], v[112:127]
	ds_read_b64_tr_b16 v[238:239], v192 offset:30784
	ds_read_b64_tr_b16 v[240:241], v192 offset:32320
	s_waitcnt lgkmcnt(5)
	v_mfma_f32_32x32x16_bf16 v[64:79], v[10:13], v[136:139], v[64:79]
	ds_read_b64_tr_b16 v[242:243], v192 offset:33856
	ds_read_b64_tr_b16 v[244:245], v192 offset:35392
	ds_read_b128 v[10:13], v190 offset:9312
	ds_read_b128 v[80:83], v191 offset:9312
	s_waitcnt lgkmcnt(0)
	v_mfma_f32_32x32x16_bf16 v[112:127], v[80:83], v[140:143], v[112:127]
	ds_read_b64_tr_b16 v[246:247], v192 offset:36928
	ds_read_b64_tr_b16 v[248:249], v192 offset:38464
	s_waitcnt lgkmcnt(3)
	v_mfma_f32_32x32x16_bf16 v[64:79], v[10:13], v[140:143], v[64:79]
	ds_read_b64_tr_b16 v[234:235], v192 offset:40000
	ds_read_b64_tr_b16 v[236:237], v192 offset:41536
	s_and_saveexec_b64 s[38:39], s[0:1]
	s_xor_b64 s[0:1], exec, s[38:39]
	s_cbranch_execz .LBB0_424
	v_or_b32_e32 v0, s6, v145
	v_sub_u32_e32 v0, v229, v0
	v_lshlrev_b32_e32 v10, 2, v0
	v_add_u32_e32 v80, v230, v10
	v_mov_b32_e32 v10, v146
	s_and_saveexec_b64 s[6:7], vcc
	s_cbranch_execnz .LBB0_462
	s_or_b64 exec, exec, s[6:7]
	v_mov_b32_e32 v11, v146
	s_and_saveexec_b64 s[6:7], vcc
	s_cbranch_execnz .LBB0_463

; template <int MODE> ...
;     ...
;             float ps = 0.f;
; #pragma unroll
;             for (int r = 0; r < 16; ++r) { s0[r] = ex2(s0[r]); s1[r] = ex2(s1[r]); ps += s0[r] + s1[r]; }
;             l += ps;
;         } else {
; #pragma unroll
;             for (int r = 0; r < 16; ++r) { s0[r] = ex2(s0[r]) * linv; s1[r] = ex2(s1[r]) * linv; }
;             float quad[8], last[8], recv[8];
; #pragma unroll
;             for (int a = 0; a < 4; ++a) {
;                 quad[a] = (s0[4 * a] + s0[4 * a + 1]) + (s0[4 * a + 2] + s0[4 * a + 3]); last[a] = s0[4 * a + 3];
;                 quad[4 + a] = (s1[4 * a] + s1[4 * a + 1]) + (s1[4 * a + 2] + s1[4 * a + 3]); last[4 + a] = s1[4 * a + 3];
;             }
; #pragma unroll
;             for (int i = 0; i < 8; ++i) recv[i] = half_other(last[i], hl);
; #pragma unroll
;             for (int i = 0; i < 8; ++i) {
;                 const float prev = (i > 0) ? recv[i > 0 ? i - 1 : 0] : carry;
;                 float v = quad[i] + (hl ? recv[i] : prev);
;                 v += __shfl_xor(v, 1); v += __shfl_xor(v, 2);
;                 if ((n & 3) == 0) lds_st<float>(L + score_ofs + (16 * kt + 2 * i + hl) * 4, v);
;             }
;             carry = recv[7];
;         }
;         if (MODE != MODE_CMP1) {
;             bf16x8 pf[4];
; #pragma unroll
;             for (int ks = 0; ks < 4; ++ks) {
;                 const int hb = 8 * (ks & 1); u32x4 w;
;                 if (ks >> 1) { w.x = cvt_pk(s1[hb], s1[hb + 1]); w.y = cvt_pk(s1[hb + 2], s1[hb + 3]); w.z = cvt_pk(s1[hb + 4], s1[hb + 5]); w.w = cvt_pk(s1[hb + 6], s1[hb + 7]); }
;                 else { w.x = cvt_pk(s0[hb], s0[hb + 1]); w.y = cvt_pk(s0[hb + 2], s0[hb + 3]); w.z = cvt_pk(s0[hb + 4], s0[hb + 5]); w.w = cvt_pk(s0[hb + 6], s0[hb + 7]); }
;                 pf[ks] = __builtin_bit_cast(bf16x8, w);
;             }
;             const lptr vb_ = Vt + (4 * hl + q4) * VP + 32 * blk + 8 * p4;
; #pragma unroll
;             for (int c_ = 0; c_ < 2; ++c_)
; #pragma unroll
;                 for (int ks_ = 0; ks_ < 4; ++ks_) {
;                     const s16x4 lo_ = tr16(vb_ + (16 * ks_) * VP + 64 * c_), hi_ = tr16(vb_ + (16 * ks_ + 8) * VP + 64 * c_);
;                     const bf16x8 vf_ = {lo_[0], lo_[1], lo_[2], lo_[3], hi_[0], hi_[1], hi_[2], hi_[3]};
;                     o[c_] = mfma32(vf_, pf[ks_], o[c_]);
;                 }
.LBB0_428:
	v_exp_f32_e32 v0, v96
	v_exp_f32_e32 v14, v97
	v_exp_f32_e32 v15, v98
	v_exp_f32_e32 v68, v99
	v_exp_f32_e32 v69, v100
	v_exp_f32_e32 v70, v101
	v_exp_f32_e32 v71, v102
	v_exp_f32_e32 v72, v103
	v_exp_f32_e32 v75, v106
	v_exp_f32_e32 v76, v107
	v_exp_f32_e32 v77, v108
	v_exp_f32_e32 v78, v109
	v_exp_f32_e32 v73, v104
	v_exp_f32_e32 v74, v105
	v_cvt_pk_bf16_f32 v102, v0, v14
	v_cvt_pk_bf16_f32 v103, v15, v68
	v_cvt_pk_bf16_f32 v104, v69, v70
	v_cvt_pk_bf16_f32 v105, v71, v72
	v_exp_f32_e32 v96, v80
	v_exp_f32_e32 v79, v110
	s_waitcnt lgkmcnt(0)
	s_waitcnt lgkmcnt(0)
	v_mfma_f32_32x32x16_bf16 v[32:47], v[196:199], v[102:105], v[32:47]
	v_exp_f32_e32 v80, v111
	v_cvt_pk_bf16_f32 v98, v73, v74
	v_cvt_pk_bf16_f32 v99, v75, v76
	v_cvt_pk_bf16_f32 v100, v77, v78
	v_cvt_pk_bf16_f32 v101, v79, v80
	v_exp_f32_e32 v81, v81
	v_exp_f32_e32 v82, v82
	v_mfma_f32_32x32x16_bf16 v[32:47], v[200:203], v[98:101], v[32:47]
	v_exp_f32_e32 v83, v83
	v_exp_f32_e32 v84, v84
	v_exp_f32_e32 v85, v85
	v_exp_f32_e32 v86, v86
	v_exp_f32_e32 v87, v87
	v_cvt_pk_bf16_f32 v64, v96, v81
	v_cvt_pk_bf16_f32 v65, v82, v83
	v_cvt_pk_bf16_f32 v66, v84, v85
	v_cvt_pk_bf16_f32 v67, v86, v87
	v_exp_f32_e32 v88, v88
	v_exp_f32_e32 v89, v89
	v_mfma_f32_32x32x16_bf16 v[32:47], v[204:207], v[64:67], v[32:47]
	v_exp_f32_e32 v90, v90
	v_exp_f32_e32 v91, v91
	v_exp_f32_e32 v92, v92
	v_exp_f32_e32 v93, v93
	v_exp_f32_e32 v94, v94
	v_exp_f32_e32 v95, v95
	v_cvt_pk_bf16_f32 v10, v88, v89
	v_cvt_pk_bf16_f32 v11, v90, v91
	v_cvt_pk_bf16_f32 v12, v92, v93
	v_cvt_pk_bf16_f32 v13, v94, v95
	s_andn2_b64 vcc, exec, s[42:43]
	s_nop 1
	v_mfma_f32_32x32x16_bf16 v[32:47], v[208:211], v[10:13], v[32:47]
	v_mfma_f32_32x32x16_bf16 v[16:31], v[238:241], v[102:105], v[16:31]
	v_mfma_f32_32x32x16_bf16 v[16:31], v[242:245], v[98:101], v[16:31]
	v_mfma_f32_32x32x16_bf16 v[16:31], v[246:249], v[64:67], v[16:31]
	v_mfma_f32_32x32x16_bf16 v[16:31], v[234:237], v[10:13], v[16:31]
	s_cbranch_vccnz .LBB0_341
	s_waitcnt vmcnt(1)
	ds_write_b128 v184, v[6:9]
	s_waitcnt vmcnt(0)
	ds_write_b128 v185, v[2:5] offset:18432
	s_branch .LBB0_341

;     __device__ __forceinline__ void operator()(const f32x4 (&acc)[2][2][4][2], const Unit& u, int wr, int wc, int fr, int fq) const {
;         const int row0 = u.pm * 256 + wr * 64 + fr, col0 = u.pn * 256 + wc * 32 + 8 * fq;
; #pragma unroll
;         for (int bj = 0; bj < 2; ++bj) {
;             const int c = col0 + bj * 128;
;             f32x4 g0 = {1.f, 1.f, 1.f, 1.f}, g1 = g0, b0 = {0.f, 0.f, 0.f, 0.f}, b1 = b0;
;             if (lng) { g0 = *(const f32x4*)(lng + c); g1 = *(const f32x4*)(lng + c + 4); b0 = *(const f32x4*)(lnb + c); b1 = *(const f32x4*)(lnb + c + 4); }
;             g0 = g0 * ca; g1 = g1 * ca; b0 = b0 * ca; b1 = b1 * ca;
; #pragma unroll
;             for (int ai = 0; ai < 2; ++ai)
; #pragma unroll
;                 for (int m = 0; m < 4; ++m) {
;                     const int row = row0 + ai * 128 + m * 16;
;                     float mean = 0.f, rstd = 1.f;
;                     if (lng) { const float2 st = *(const float2*)(stats + 2 * (size_t)row); mean = st.x; rstd = st.y; }
;                     float* p = X + (size_t)row * DM + c;
;                     f32x4 x0 = *(const f32x4*)p, x1 = *(const f32x4*)(p + 4);
;                     x0 = (x0 - mean) * rstd * g0 + b0 + acc[ai][bj][m][0] * cb; x1 = (x1 - mean) * rstd * g1 + b1 + acc[ai][bj][m][1] * cb;
;                     *(f32x4*)p = x0; *(f32x4*)(p + 4) = x1;
.LBB0_820:
	v_lshl_or_b32 v154, s13, 8, v186
	v_lshl_add_u32 v178, s18, 8, v167
	s_add_u32 s98, s94, 0x80000
	s_addc_u32 s99, s95, 0
	v_lshlrev_b32_e32 v155, 2, v154
	v_lshlrev_b32_e32 v179, 3, v178
	v_lshlrev_b32_e32 v180, 12, v178
	v_add_u32_e32 v180, v180, v155
	v_add_u32_e32 v182, 0x10000, v180
	v_add_u32_e32 v183, 0x20000, v180
	v_add_u32_e32 v184, 0x30000, v180
	s_andn2_b64 vcc, exec, s[46:47]
	s_cbranch_vccnz .Lres_nolng
	global_load_dwordx4 v[144:147], v155, s[30:31]
	global_load_dwordx4 v[148:151], v155, s[30:31] offset:16
	global_load_dwordx4 v[156:159], v155, s[42:43]
	global_load_dwordx4 v[170:173], v155, s[42:43] offset:16
	global_load_dwordx4 v[174:177], v155, s[30:31] offset:512
	global_load_dwordx4 v[188:191], v155, s[30:31] offset:528
	global_load_dwordx4 v[194:197], v155, s[42:43] offset:512
	global_load_dwordx4 v[198:201], v155, s[42:43] offset:528
	s_branch .Lres_gbdone
.Lres_nolng:
	v_mov_b32_e32 v144, s4
	v_mov_b32_e32 v145, s4
	v_mov_b32_e32 v146, s4
	v_mov_b32_e32 v147, s4
	v_mov_b32_e32 v156, 0
	v_mov_b32_e32 v157, 0
	v_mov_b32_e32 v158, 0
	v_mov_b32_e32 v159, 0
	v_mov_b32_e32 v148, s4
	v_mov_b32_e32 v149, s4
	v_mov_b32_e32 v150, s4
	v_mov_b32_e32 v151, s4
	v_mov_b32_e32 v170, 0
	v_mov_b32_e32 v171, 0
	v_mov_b32_e32 v172, 0
	v_mov_b32_e32 v173, 0
	v_mov_b32_e32 v174, s4
	v_mov_b32_e32 v175, s4
	v_mov_b32_e32 v176, s4
	v_mov_b32_e32 v177, s4
	v_mov_b32_e32 v194, 0
	v_mov_b32_e32 v195, 0
	v_mov_b32_e32 v196, 0
	v_mov_b32_e32 v197, 0
	v_mov_b32_e32 v188, s4
	v_mov_b32_e32 v189, s4
	v_mov_b32_e32 v190, s4
	v_mov_b32_e32 v191, s4
	v_mov_b32_e32 v198, 0
	v_mov_b32_e32 v199, 0
	v_mov_b32_e32 v200, 0
	v_mov_b32_e32 v201, 0
.Lres_gbdone:
	global_load_dwordx2 v[152:153], v179, s[96:97]
	global_load_dwordx4 v[202:205], v180, s[94:95]
	global_load_dwordx4 v[206:209], v180, s[94:95] offset:16
	global_load_dwordx2 v[160:161], v179, s[96:97] offset:128
	global_load_dwordx4 v[210:213], v182, s[94:95]
	global_load_dwordx4 v[226:229], v182, s[94:95] offset:16
	global_load_dwordx2 v[216:217], v179, s[96:97] offset:256
	global_load_dwordx4 v[230:233], v183, s[94:95]
	global_load_dwordx4 v[234:237], v183, s[94:95] offset:16
	global_load_dwordx2 v[246:247], v179, s[96:97] offset:384
	global_load_dwordx4 v[238:241], v184, s[94:95]
	global_load_dwordx4 v[242:245], v184, s[94:95] offset:16
	s_waitcnt vmcnt(9)
	s_andn2_b64 vcc, exec, s[46:47]
	s_cbranch_vccnz .Lres_noscale
	v_pk_mul_f32 v[156:157], v[156:157], s[4:5] op_sel_hi:[1,0]
	v_pk_mul_f32 v[158:159], v[158:159], s[4:5] op_sel_hi:[1,0]
	v_pk_mul_f32 v[170:171], v[170:171], s[4:5] op_sel_hi:[1,0]
	v_pk_mul_f32 v[172:173], v[172:173], s[4:5] op_sel_hi:[1,0]
	v_pk_mul_f32 v[144:145], v[144:145], s[4:5] op_sel_hi:[1,0]
	v_pk_mul_f32 v[146:147], v[146:147], s[4:5] op_sel_hi:[1,0]
	v_pk_mul_f32 v[148:149], v[148:149], s[4:5] op_sel_hi:[1,0]
	v_pk_mul_f32 v[150:151], v[150:151], s[4:5] op_sel_hi:[1,0]
	v_pk_mul_f32 v[194:195], v[194:195], s[4:5] op_sel_hi:[1,0]
	v_pk_mul_f32 v[196:197], v[196:197], s[4:5] op_sel_hi:[1,0]
	v_pk_mul_f32 v[198:199], v[198:199], s[4:5] op_sel_hi:[1,0]
	v_pk_mul_f32 v[200:201], v[200:201], s[4:5] op_sel_hi:[1,0]
	v_pk_mul_f32 v[174:175], v[174:175], s[4:5] op_sel_hi:[1,0]
	v_pk_mul_f32 v[176:177], v[176:177], s[4:5] op_sel_hi:[1,0]
	v_pk_mul_f32 v[188:189], v[188:189], s[4:5] op_sel_hi:[1,0]
	v_pk_mul_f32 v[190:191], v[190:191], s[4:5] op_sel_hi:[1,0]
.Lres_noscale:
	v_cndmask_b32_e64 v152, 0, v152, s[46:47]
	v_pk_add_f32 v[202:203], v[202:203], v[152:153] op_sel_hi:[1,0] neg_lo:[0,1] neg_hi:[0,1]
	v_pk_add_f32 v[204:205], v[204:205], v[152:153] op_sel_hi:[1,0] neg_lo:[0,1] neg_hi:[0,1]
	v_pk_add_f32 v[206:207], v[206:207], v[152:153] op_sel_hi:[1,0] neg_lo:[0,1] neg_hi:[0,1]
	v_pk_add_f32 v[208:209], v[208:209], v[152:153] op_sel_hi:[1,0] neg_lo:[0,1] neg_hi:[0,1]
	v_cndmask_b32_e64 v152, 1.0, v153, s[46:47]
	v_pk_mul_f32 v[202:203], v[152:153], v[202:203] op_sel_hi:[0,1]
	v_pk_mul_f32 v[204:205], v[152:153], v[204:205] op_sel_hi:[0,1]
	v_pk_mul_f32 v[206:207], v[152:153], v[206:207] op_sel_hi:[0,1]
	v_pk_mul_f32 v[208:209], v[152:153], v[208:209] op_sel_hi:[0,1]
	v_pk_fma_f32 v[202:203], v[144:145], v[202:203], v[156:157]
	v_pk_fma_f32 v[204:205], v[146:147], v[204:205], v[158:159]
	v_pk_fma_f32 v[206:207], v[148:149], v[206:207], v[170:171]
	v_pk_fma_f32 v[208:209], v[150:151], v[208:209], v[172:173]
	v_pk_fma_f32 v[126:127], v[138:139], v[126:127], v[202:203]
	v_pk_fma_f32 v[128:129], v[138:139], v[128:129], v[204:205]
	v_pk_fma_f32 v[122:123], v[138:139], v[122:123], v[206:207]
	v_pk_fma_f32 v[124:125], v[138:139], v[124:125], v[208:209]
	global_store_dwordx4 v180, v[126:129], s[94:95]
	global_store_dwordx4 v180, v[122:125], s[94:95] offset:16
	global_load_dwordx2 v[152:153], v179, s[96:97] offset:1024
	global_load_dwordx4 v[202:205], v180, s[98:99]
	global_load_dwordx4 v[206:209], v180, s[98:99] offset:16
	s_waitcnt vmcnt(11)
;     __device__ __forceinline__ void operator()(const f32x4 (&acc)[2][2][4][2], const Unit& u, int wr, int wc, int fr, int fq) const {
;     ...
;             for (int ai = 0; ai < 2; ++ai)
; #pragma unroll
;                 for (int m = 0; m < 4; ++m) {
;                     const int row = row0 + ai * 128 + m * 16;
;                     float mean = 0.f, rstd = 1.f;
;                     if (lng) { const float2 st = *(const float2*)(stats + 2 * (size_t)row); mean = st.x; rstd = st.y; }
;                     float* p = X + (size_t)row * DM + c;
;                     f32x4 x0 = *(const f32x4*)p, x1 = *(const f32x4*)(p + 4);
;                     x0 = (x0 - mean) * rstd * g0 + b0 + acc[ai][bj][m][0] * cb; x1 = (x1 - mean) * rstd * g1 + b1 + acc[ai][bj][m][1] * cb;
;                     *(f32x4*)p = x0; *(f32x4*)(p + 4) = x1;
	v_cndmask_b32_e64 v160, 0, v160, s[46:47]
	v_pk_add_f32 v[210:211], v[210:211], v[160:161] op_sel_hi:[1,0] neg_lo:[0,1] neg_hi:[0,1]
	v_pk_add_f32 v[212:213], v[212:213], v[160:161] op_sel_hi:[1,0] neg_lo:[0,1] neg_hi:[0,1]
	v_pk_add_f32 v[226:227], v[226:227], v[160:161] op_sel_hi:[1,0] neg_lo:[0,1] neg_hi:[0,1]
	v_pk_add_f32 v[228:229], v[228:229], v[160:161] op_sel_hi:[1,0] neg_lo:[0,1] neg_hi:[0,1]
	v_cndmask_b32_e64 v160, 1.0, v161, s[46:47]
	v_pk_mul_f32 v[210:211], v[160:161], v[210:211] op_sel_hi:[0,1]
	v_pk_mul_f32 v[212:213], v[160:161], v[212:213] op_sel_hi:[0,1]
	v_pk_mul_f32 v[226:227], v[160:161], v[226:227] op_sel_hi:[0,1]
	v_pk_mul_f32 v[228:229], v[160:161], v[228:229] op_sel_hi:[0,1]
	v_pk_fma_f32 v[210:211], v[144:145], v[210:211], v[156:157]
	v_pk_fma_f32 v[212:213], v[146:147], v[212:213], v[158:159]
	v_pk_fma_f32 v[226:227], v[148:149], v[226:227], v[170:171]
	v_pk_fma_f32 v[228:229], v[150:151], v[228:229], v[172:173]
	v_pk_fma_f32 v[118:119], v[138:139], v[118:119], v[210:211]
	v_pk_fma_f32 v[120:121], v[138:139], v[120:121], v[212:213]
	v_pk_fma_f32 v[114:115], v[138:139], v[114:115], v[226:227]
	v_pk_fma_f32 v[116:117], v[138:139], v[116:117], v[228:229]
	global_store_dwordx4 v182, v[118:121], s[94:95]
	global_store_dwordx4 v182, v[114:117], s[94:95] offset:16
	global_load_dwordx2 v[160:161], v179, s[96:97] offset:1152
	global_load_dwordx4 v[210:213], v182, s[98:99]
	global_load_dwordx4 v[226:229], v182, s[98:99] offset:16
	s_waitcnt vmcnt(13)
	v_cndmask_b32_e64 v216, 0, v216, s[46:47]
	v_pk_add_f32 v[230:231], v[230:231], v[216:217] op_sel_hi:[1,0] neg_lo:[0,1] neg_hi:[0,1]
	v_pk_add_f32 v[232:233], v[232:233], v[216:217] op_sel_hi:[1,0] neg_lo:[0,1] neg_hi:[0,1]
	v_pk_add_f32 v[234:235], v[234:235], v[216:217] op_sel_hi:[1,0] neg_lo:[0,1] neg_hi:[0,1]
	v_pk_add_f32 v[236:237], v[236:237], v[216:217] op_sel_hi:[1,0] neg_lo:[0,1] neg_hi:[0,1]
	v_cndmask_b32_e64 v216, 1.0, v217, s[46:47]
	v_pk_mul_f32 v[230:231], v[216:217], v[230:231] op_sel_hi:[0,1]
	v_pk_mul_f32 v[232:233], v[216:217], v[232:233] op_sel_hi:[0,1]
	v_pk_mul_f32 v[234:235], v[216:217], v[234:235] op_sel_hi:[0,1]
	v_pk_mul_f32 v[236:237], v[216:217], v[236:237] op_sel_hi:[0,1]
	v_pk_fma_f32 v[230:231], v[144:145], v[230:231], v[156:157]
	v_pk_fma_f32 v[232:233], v[146:147], v[232:233], v[158:159]
	v_pk_fma_f32 v[234:235], v[148:149], v[234:235], v[170:171]
	v_pk_fma_f32 v[236:237], v[150:151], v[236:237], v[172:173]
	v_pk_fma_f32 v[110:111], v[138:139], v[110:111], v[230:231]
	v_pk_fma_f32 v[112:113], v[138:139], v[112:113], v[232:233]
	v_pk_fma_f32 v[106:107], v[138:139], v[106:107], v[234:235]
	v_pk_fma_f32 v[108:109], v[138:139], v[108:109], v[236:237]
	global_store_dwordx4 v183, v[110:113], s[94:95]
	global_store_dwordx4 v183, v[106:109], s[94:95] offset:16
	global_load_dwordx2 v[216:217], v179, s[96:97] offset:1280
	global_load_dwordx4 v[230:233], v183, s[98:99]
	global_load_dwordx4 v[234:237], v183, s[98:99] offset:16
	s_waitcnt vmcnt(15)
	v_cndmask_b32_e64 v246, 0, v246, s[46:47]
	v_pk_add_f32 v[238:239], v[238:239], v[246:247] op_sel_hi:[1,0] neg_lo:[0,1] neg_hi:[0,1]
	v_pk_add_f32 v[240:241], v[240:241], v[246:247] op_sel_hi:[1,0] neg_lo:[0,1] neg_hi:[0,1]
	v_pk_add_f32 v[242:243], v[242:243], v[246:247] op_sel_hi:[1,0] neg_lo:[0,1] neg_hi:[0,1]
	v_pk_add_f32 v[244:245], v[244:245], v[246:247] op_sel_hi:[1,0] neg_lo:[0,1] neg_hi:[0,1]
	v_cndmask_b32_e64 v246, 1.0, v247, s[46:47]
	v_pk_mul_f32 v[238:239], v[246:247], v[238:239] op_sel_hi:[0,1]
	v_pk_mul_f32 v[240:241], v[246:247], v[240:241] op_sel_hi:[0,1]
	v_pk_mul_f32 v[242:243], v[246:247], v[242:243] op_sel_hi:[0,1]
	v_pk_mul_f32 v[244:245], v[246:247], v[244:245] op_sel_hi:[0,1]
	v_pk_fma_f32 v[238:239], v[144:145], v[238:239], v[156:157]
	v_pk_fma_f32 v[240:241], v[146:147], v[240:241], v[158:159]
	v_pk_fma_f32 v[242:243], v[148:149], v[242:243], v[170:171]
	v_pk_fma_f32 v[244:245], v[150:151], v[244:245], v[172:173]
	v_pk_fma_f32 v[102:103], v[138:139], v[102:103], v[238:239]
	v_pk_fma_f32 v[104:105], v[138:139], v[104:105], v[240:241]
	v_pk_fma_f32 v[98:99], v[138:139], v[98:99], v[242:243]
	v_pk_fma_f32 v[100:101], v[138:139], v[100:101], v[244:245]
	global_store_dwordx4 v184, v[102:105], s[94:95]
	global_store_dwordx4 v184, v[98:101], s[94:95] offset:16
	global_load_dwordx2 v[246:247], v179, s[96:97] offset:1408
	global_load_dwordx4 v[238:241], v184, s[98:99]
	global_load_dwordx4 v[242:245], v184, s[98:99] offset:16
	s_waitcnt vmcnt(15)
	v_cndmask_b32_e64 v152, 0, v152, s[46:47]
	v_pk_add_f32 v[202:203], v[202:203], v[152:153] op_sel_hi:[1,0] neg_lo:[0,1] neg_hi:[0,1]
	v_pk_add_f32 v[204:205], v[204:205], v[152:153] op_sel_hi:[1,0] neg_lo:[0,1] neg_hi:[0,1]
	v_pk_add_f32 v[206:207], v[206:207], v[152:153] op_sel_hi:[1,0] neg_lo:[0,1] neg_hi:[0,1]
	v_pk_add_f32 v[208:209], v[208:209], v[152:153] op_sel_hi:[1,0] neg_lo:[0,1] neg_hi:[0,1]
	v_cndmask_b32_e64 v152, 1.0, v153, s[46:47]
	v_pk_mul_f32 v[202:203], v[152:153], v[202:203] op_sel_hi:[0,1]
	v_pk_mul_f32 v[204:205], v[152:153], v[204:205] op_sel_hi:[0,1]
	v_pk_mul_f32 v[206:207], v[152:153], v[206:207] op_sel_hi:[0,1]
	v_pk_mul_f32 v[208:209], v[152:153], v[208:209] op_sel_hi:[0,1]
	v_pk_fma_f32 v[202:203], v[144:145], v[202:203], v[156:157]
	v_pk_fma_f32 v[204:205], v[146:147], v[204:205], v[158:159]
	v_pk_fma_f32 v[206:207], v[148:149], v[206:207], v[170:171]
	v_pk_fma_f32 v[208:209], v[150:151], v[208:209], v[172:173]
	v_pk_fma_f32 v[94:95], v[138:139], v[94:95], v[202:203]
	v_pk_fma_f32 v[96:97], v[138:139], v[96:97], v[204:205]
	v_pk_fma_f32 v[90:91], v[138:139], v[90:91], v[206:207]
	v_pk_fma_f32 v[92:93], v[138:139], v[92:93], v[208:209]
	global_store_dwordx4 v180, v[94:97], s[98:99]
	global_store_dwordx4 v180, v[90:93], s[98:99] offset:16
	global_load_dwordx2 v[152:153], v179, s[96:97]
	global_load_dwordx4 v[202:205], v180, s[94:95] offset:512
	global_load_dwordx4 v[206:209], v180, s[94:95] offset:528
	s_waitcnt vmcnt(15)
;     __device__ __forceinline__ void operator()(const f32x4 (&acc)[2][2][4][2], const Unit& u, int wr, int wc, int fr, int fq) const {
;     ...
;             for (int ai = 0; ai < 2; ++ai)
; #pragma unroll
;                 for (int m = 0; m < 4; ++m) {
;                     const int row = row0 + ai * 128 + m * 16;
;                     float mean = 0.f, rstd = 1.f;
;                     if (lng) { const float2 st = *(const float2*)(stats + 2 * (size_t)row); mean = st.x; rstd = st.y; }
;                     float* p = X + (size_t)row * DM + c;
;                     f32x4 x0 = *(const f32x4*)p, x1 = *(const f32x4*)(p + 4);
;                     x0 = (x0 - mean) * rstd * g0 + b0 + acc[ai][bj][m][0] * cb; x1 = (x1 - mean) * rstd * g1 + b1 + acc[ai][bj][m][1] * cb;
;                     *(f32x4*)p = x0; *(f32x4*)(p + 4) = x1;
	v_cndmask_b32_e64 v160, 0, v160, s[46:47]
	v_pk_add_f32 v[210:211], v[210:211], v[160:161] op_sel_hi:[1,0] neg_lo:[0,1] neg_hi:[0,1]
	v_pk_add_f32 v[212:213], v[212:213], v[160:161] op_sel_hi:[1,0] neg_lo:[0,1] neg_hi:[0,1]
	v_pk_add_f32 v[226:227], v[226:227], v[160:161] op_sel_hi:[1,0] neg_lo:[0,1] neg_hi:[0,1]
	v_pk_add_f32 v[228:229], v[228:229], v[160:161] op_sel_hi:[1,0] neg_lo:[0,1] neg_hi:[0,1]
	v_cndmask_b32_e64 v160, 1.0, v161, s[46:47]
	v_pk_mul_f32 v[210:211], v[160:161], v[210:211] op_sel_hi:[0,1]
	v_pk_mul_f32 v[212:213], v[160:161], v[212:213] op_sel_hi:[0,1]
	v_pk_mul_f32 v[226:227], v[160:161], v[226:227] op_sel_hi:[0,1]
	v_pk_mul_f32 v[228:229], v[160:161], v[228:229] op_sel_hi:[0,1]
	v_pk_fma_f32 v[210:211], v[144:145], v[210:211], v[156:157]
	v_pk_fma_f32 v[212:213], v[146:147], v[212:213], v[158:159]
	v_pk_fma_f32 v[226:227], v[148:149], v[226:227], v[170:171]
	v_pk_fma_f32 v[228:229], v[150:151], v[228:229], v[172:173]
	v_pk_fma_f32 v[86:87], v[138:139], v[86:87], v[210:211]
	v_pk_fma_f32 v[88:89], v[138:139], v[88:89], v[212:213]
	v_pk_fma_f32 v[82:83], v[138:139], v[82:83], v[226:227]
	v_pk_fma_f32 v[84:85], v[138:139], v[84:85], v[228:229]
	global_store_dwordx4 v182, v[86:89], s[98:99]
	global_store_dwordx4 v182, v[82:85], s[98:99] offset:16
	global_load_dwordx2 v[160:161], v179, s[96:97] offset:128
	global_load_dwordx4 v[210:213], v182, s[94:95] offset:512
	global_load_dwordx4 v[226:229], v182, s[94:95] offset:528
	s_waitcnt vmcnt(15)
	v_cndmask_b32_e64 v216, 0, v216, s[46:47]
	v_pk_add_f32 v[230:231], v[230:231], v[216:217] op_sel_hi:[1,0] neg_lo:[0,1] neg_hi:[0,1]
	v_pk_add_f32 v[232:233], v[232:233], v[216:217] op_sel_hi:[1,0] neg_lo:[0,1] neg_hi:[0,1]
	v_pk_add_f32 v[234:235], v[234:235], v[216:217] op_sel_hi:[1,0] neg_lo:[0,1] neg_hi:[0,1]
	v_pk_add_f32 v[236:237], v[236:237], v[216:217] op_sel_hi:[1,0] neg_lo:[0,1] neg_hi:[0,1]
	v_cndmask_b32_e64 v216, 1.0, v217, s[46:47]
	v_pk_mul_f32 v[230:231], v[216:217], v[230:231] op_sel_hi:[0,1]
	v_pk_mul_f32 v[232:233], v[216:217], v[232:233] op_sel_hi:[0,1]
	v_pk_mul_f32 v[234:235], v[216:217], v[234:235] op_sel_hi:[0,1]
	v_pk_mul_f32 v[236:237], v[216:217], v[236:237] op_sel_hi:[0,1]
	v_pk_fma_f32 v[230:231], v[144:145], v[230:231], v[156:157]
	v_pk_fma_f32 v[232:233], v[146:147], v[232:233], v[158:159]
	v_pk_fma_f32 v[234:235], v[148:149], v[234:235], v[170:171]
	v_pk_fma_f32 v[236:237], v[150:151], v[236:237], v[172:173]
	v_pk_fma_f32 v[78:79], v[138:139], v[78:79], v[230:231]
	v_pk_fma_f32 v[80:81], v[138:139], v[80:81], v[232:233]
	v_pk_fma_f32 v[74:75], v[138:139], v[74:75], v[234:235]
	v_pk_fma_f32 v[76:77], v[138:139], v[76:77], v[236:237]
	global_store_dwordx4 v183, v[78:81], s[98:99]
	global_store_dwordx4 v183, v[74:77], s[98:99] offset:16
	global_load_dwordx2 v[216:217], v179, s[96:97] offset:256
	global_load_dwordx4 v[230:233], v183, s[94:95] offset:512
	global_load_dwordx4 v[234:237], v183, s[94:95] offset:528
	s_waitcnt vmcnt(15)
	v_cndmask_b32_e64 v246, 0, v246, s[46:47]
	v_pk_add_f32 v[238:239], v[238:239], v[246:247] op_sel_hi:[1,0] neg_lo:[0,1] neg_hi:[0,1]
	v_pk_add_f32 v[240:241], v[240:241], v[246:247] op_sel_hi:[1,0] neg_lo:[0,1] neg_hi:[0,1]
	v_pk_add_f32 v[242:243], v[242:243], v[246:247] op_sel_hi:[1,0] neg_lo:[0,1] neg_hi:[0,1]
	v_pk_add_f32 v[244:245], v[244:245], v[246:247] op_sel_hi:[1,0] neg_lo:[0,1] neg_hi:[0,1]
	v_cndmask_b32_e64 v246, 1.0, v247, s[46:47]
	v_pk_mul_f32 v[238:239], v[246:247], v[238:239] op_sel_hi:[0,1]
	v_pk_mul_f32 v[240:241], v[246:247], v[240:241] op_sel_hi:[0,1]
	v_pk_mul_f32 v[242:243], v[246:247], v[242:243] op_sel_hi:[0,1]
	v_pk_mul_f32 v[244:245], v[246:247], v[244:245] op_sel_hi:[0,1]
	v_pk_fma_f32 v[238:239], v[144:145], v[238:239], v[156:157]
	v_pk_fma_f32 v[240:241], v[146:147], v[240:241], v[158:159]
	v_pk_fma_f32 v[242:243], v[148:149], v[242:243], v[170:171]
	v_pk_fma_f32 v[244:245], v[150:151], v[244:245], v[172:173]
	v_pk_fma_f32 v[70:71], v[138:139], v[70:71], v[238:239]
	v_pk_fma_f32 v[72:73], v[138:139], v[72:73], v[240:241]
	v_pk_fma_f32 v[66:67], v[138:139], v[66:67], v[242:243]
	v_pk_fma_f32 v[68:69], v[138:139], v[68:69], v[244:245]
	global_store_dwordx4 v184, v[70:73], s[98:99]
	global_store_dwordx4 v184, v[66:69], s[98:99] offset:16
	global_load_dwordx2 v[246:247], v179, s[96:97] offset:384
	global_load_dwordx4 v[238:241], v184, s[94:95] offset:512
	global_load_dwordx4 v[242:245], v184, s[94:95] offset:528
	s_waitcnt vmcnt(15)
	v_cndmask_b32_e64 v152, 0, v152, s[46:47]
	v_pk_add_f32 v[202:203], v[202:203], v[152:153] op_sel_hi:[1,0] neg_lo:[0,1] neg_hi:[0,1]
	v_pk_add_f32 v[204:205], v[204:205], v[152:153] op_sel_hi:[1,0] neg_lo:[0,1] neg_hi:[0,1]
	v_pk_add_f32 v[206:207], v[206:207], v[152:153] op_sel_hi:[1,0] neg_lo:[0,1] neg_hi:[0,1]
	v_pk_add_f32 v[208:209], v[208:209], v[152:153] op_sel_hi:[1,0] neg_lo:[0,1] neg_hi:[0,1]
	v_cndmask_b32_e64 v152, 1.0, v153, s[46:47]
	v_pk_mul_f32 v[202:203], v[152:153], v[202:203] op_sel_hi:[0,1]
	v_pk_mul_f32 v[204:205], v[152:153], v[204:205] op_sel_hi:[0,1]
	v_pk_mul_f32 v[206:207], v[152:153], v[206:207] op_sel_hi:[0,1]
	v_pk_mul_f32 v[208:209], v[152:153], v[208:209] op_sel_hi:[0,1]
	v_pk_fma_f32 v[202:203], v[174:175], v[202:203], v[194:195]
	v_pk_fma_f32 v[204:205], v[176:177], v[204:205], v[196:197]
	v_pk_fma_f32 v[206:207], v[188:189], v[206:207], v[198:199]
	v_pk_fma_f32 v[208:209], v[190:191], v[208:209], v[200:201]
	v_pk_fma_f32 v[62:63], v[138:139], v[62:63], v[202:203]
	v_pk_fma_f32 v[64:65], v[138:139], v[64:65], v[204:205]
	v_pk_fma_f32 v[58:59], v[138:139], v[58:59], v[206:207]
	v_pk_fma_f32 v[60:61], v[138:139], v[60:61], v[208:209]
	global_store_dwordx4 v180, v[62:65], s[94:95] offset:512
	global_store_dwordx4 v180, v[58:61], s[94:95] offset:528
	global_load_dwordx2 v[152:153], v179, s[96:97] offset:1024
	global_load_dwordx4 v[202:205], v180, s[98:99] offset:512
	global_load_dwordx4 v[206:209], v180, s[98:99] offset:528
	s_waitcnt vmcnt(15)
;     __device__ __forceinline__ void operator()(const f32x4 (&acc)[2][2][4][2], const Unit& u, int wr, int wc, int fr, int fq) const {
;     ...
;             for (int ai = 0; ai < 2; ++ai)
; #pragma unroll
;                 for (int m = 0; m < 4; ++m) {
;                     const int row = row0 + ai * 128 + m * 16;
;                     float mean = 0.f, rstd = 1.f;
;                     if (lng) { const float2 st = *(const float2*)(stats + 2 * (size_t)row); mean = st.x; rstd = st.y; }
;                     float* p = X + (size_t)row * DM + c;
;                     f32x4 x0 = *(const f32x4*)p, x1 = *(const f32x4*)(p + 4);
;                     x0 = (x0 - mean) * rstd * g0 + b0 + acc[ai][bj][m][0] * cb; x1 = (x1 - mean) * rstd * g1 + b1 + acc[ai][bj][m][1] * cb;
;                     *(f32x4*)p = x0; *(f32x4*)(p + 4) = x1;
	v_cndmask_b32_e64 v160, 0, v160, s[46:47]
	v_pk_add_f32 v[210:211], v[210:211], v[160:161] op_sel_hi:[1,0] neg_lo:[0,1] neg_hi:[0,1]
	v_pk_add_f32 v[212:213], v[212:213], v[160:161] op_sel_hi:[1,0] neg_lo:[0,1] neg_hi:[0,1]
	v_pk_add_f32 v[226:227], v[226:227], v[160:161] op_sel_hi:[1,0] neg_lo:[0,1] neg_hi:[0,1]
	v_pk_add_f32 v[228:229], v[228:229], v[160:161] op_sel_hi:[1,0] neg_lo:[0,1] neg_hi:[0,1]
	v_cndmask_b32_e64 v160, 1.0, v161, s[46:47]
	v_pk_mul_f32 v[210:211], v[160:161], v[210:211] op_sel_hi:[0,1]
	v_pk_mul_f32 v[212:213], v[160:161], v[212:213] op_sel_hi:[0,1]
	v_pk_mul_f32 v[226:227], v[160:161], v[226:227] op_sel_hi:[0,1]
	v_pk_mul_f32 v[228:229], v[160:161], v[228:229] op_sel_hi:[0,1]
	v_pk_fma_f32 v[210:211], v[174:175], v[210:211], v[194:195]
	v_pk_fma_f32 v[212:213], v[176:177], v[212:213], v[196:197]
	v_pk_fma_f32 v[226:227], v[188:189], v[226:227], v[198:199]
	v_pk_fma_f32 v[228:229], v[190:191], v[228:229], v[200:201]
	v_pk_fma_f32 v[54:55], v[138:139], v[54:55], v[210:211]
	v_pk_fma_f32 v[56:57], v[138:139], v[56:57], v[212:213]
	v_pk_fma_f32 v[50:51], v[138:139], v[50:51], v[226:227]
	v_pk_fma_f32 v[52:53], v[138:139], v[52:53], v[228:229]
	global_store_dwordx4 v182, v[54:57], s[94:95] offset:512
	global_store_dwordx4 v182, v[50:53], s[94:95] offset:528
	global_load_dwordx2 v[160:161], v179, s[96:97] offset:1152
	global_load_dwordx4 v[210:213], v182, s[98:99] offset:512
	global_load_dwordx4 v[226:229], v182, s[98:99] offset:528
	s_waitcnt vmcnt(15)
	v_cndmask_b32_e64 v216, 0, v216, s[46:47]
	v_pk_add_f32 v[230:231], v[230:231], v[216:217] op_sel_hi:[1,0] neg_lo:[0,1] neg_hi:[0,1]
	v_pk_add_f32 v[232:233], v[232:233], v[216:217] op_sel_hi:[1,0] neg_lo:[0,1] neg_hi:[0,1]
	v_pk_add_f32 v[234:235], v[234:235], v[216:217] op_sel_hi:[1,0] neg_lo:[0,1] neg_hi:[0,1]
	v_pk_add_f32 v[236:237], v[236:237], v[216:217] op_sel_hi:[1,0] neg_lo:[0,1] neg_hi:[0,1]
	v_cndmask_b32_e64 v216, 1.0, v217, s[46:47]
	v_pk_mul_f32 v[230:231], v[216:217], v[230:231] op_sel_hi:[0,1]
	v_pk_mul_f32 v[232:233], v[216:217], v[232:233] op_sel_hi:[0,1]
	v_pk_mul_f32 v[234:235], v[216:217], v[234:235] op_sel_hi:[0,1]
	v_pk_mul_f32 v[236:237], v[216:217], v[236:237] op_sel_hi:[0,1]
	v_pk_fma_f32 v[230:231], v[174:175], v[230:231], v[194:195]
	v_pk_fma_f32 v[232:233], v[176:177], v[232:233], v[196:197]
	v_pk_fma_f32 v[234:235], v[188:189], v[234:235], v[198:199]
	v_pk_fma_f32 v[236:237], v[190:191], v[236:237], v[200:201]
	v_pk_fma_f32 v[46:47], v[138:139], v[46:47], v[230:231]
	v_pk_fma_f32 v[48:49], v[138:139], v[48:49], v[232:233]
	v_pk_fma_f32 v[42:43], v[138:139], v[42:43], v[234:235]
	v_pk_fma_f32 v[44:45], v[138:139], v[44:45], v[236:237]
	global_store_dwordx4 v183, v[46:49], s[94:95] offset:512
	global_store_dwordx4 v183, v[42:45], s[94:95] offset:528
	global_load_dwordx2 v[216:217], v179, s[96:97] offset:1280
	global_load_dwordx4 v[230:233], v183, s[98:99] offset:512
	global_load_dwordx4 v[234:237], v183, s[98:99] offset:528
	s_waitcnt vmcnt(15)
	v_cndmask_b32_e64 v246, 0, v246, s[46:47]
	v_pk_add_f32 v[238:239], v[238:239], v[246:247] op_sel_hi:[1,0] neg_lo:[0,1] neg_hi:[0,1]
	v_pk_add_f32 v[240:241], v[240:241], v[246:247] op_sel_hi:[1,0] neg_lo:[0,1] neg_hi:[0,1]
	v_pk_add_f32 v[242:243], v[242:243], v[246:247] op_sel_hi:[1,0] neg_lo:[0,1] neg_hi:[0,1]
	v_pk_add_f32 v[244:245], v[244:245], v[246:247] op_sel_hi:[1,0] neg_lo:[0,1] neg_hi:[0,1]
	v_cndmask_b32_e64 v246, 1.0, v247, s[46:47]
	v_pk_mul_f32 v[238:239], v[246:247], v[238:239] op_sel_hi:[0,1]
	v_pk_mul_f32 v[240:241], v[246:247], v[240:241] op_sel_hi:[0,1]
	v_pk_mul_f32 v[242:243], v[246:247], v[242:243] op_sel_hi:[0,1]
	v_pk_mul_f32 v[244:245], v[246:247], v[244:245] op_sel_hi:[0,1]
	v_pk_fma_f32 v[238:239], v[174:175], v[238:239], v[194:195]
	v_pk_fma_f32 v[240:241], v[176:177], v[240:241], v[196:197]
	v_pk_fma_f32 v[242:243], v[188:189], v[242:243], v[198:199]
	v_pk_fma_f32 v[244:245], v[190:191], v[244:245], v[200:201]
	v_pk_fma_f32 v[38:39], v[138:139], v[38:39], v[238:239]
	v_pk_fma_f32 v[40:41], v[138:139], v[40:41], v[240:241]
	v_pk_fma_f32 v[34:35], v[138:139], v[34:35], v[242:243]
	v_pk_fma_f32 v[36:37], v[138:139], v[36:37], v[244:245]
	global_store_dwordx4 v184, v[38:41], s[94:95] offset:512
	global_store_dwordx4 v184, v[34:37], s[94:95] offset:528
	global_load_dwordx2 v[246:247], v179, s[96:97] offset:1408
	global_load_dwordx4 v[238:241], v184, s[98:99] offset:512
	global_load_dwordx4 v[242:245], v184, s[98:99] offset:528
	s_waitcnt vmcnt(15)
;     __device__ __forceinline__ void operator()(const f32x4 (&acc)[2][2][4][2], const Unit& u, int wr, int wc, int fr, int fq) const {
;     ...
;             for (int ai = 0; ai < 2; ++ai)
; #pragma unroll
;                 for (int m = 0; m < 4; ++m) {
;                     const int row = row0 + ai * 128 + m * 16;
;                     float mean = 0.f, rstd = 1.f;
;                     if (lng) { const float2 st = *(const float2*)(stats + 2 * (size_t)row); mean = st.x; rstd = st.y; }
;                     float* p = X + (size_t)row * DM + c;
;                     f32x4 x0 = *(const f32x4*)p, x1 = *(const f32x4*)(p + 4);
;                     x0 = (x0 - mean) * rstd * g0 + b0 + acc[ai][bj][m][0] * cb; x1 = (x1 - mean) * rstd * g1 + b1 + acc[ai][bj][m][1] * cb;
;                     *(f32x4*)p = x0; *(f32x4*)(p + 4) = x1;
	v_cndmask_b32_e64 v152, 0, v152, s[46:47]
	v_pk_add_f32 v[202:203], v[202:203], v[152:153] op_sel_hi:[1,0] neg_lo:[0,1] neg_hi:[0,1]
	v_pk_add_f32 v[204:205], v[204:205], v[152:153] op_sel_hi:[1,0] neg_lo:[0,1] neg_hi:[0,1]
	v_pk_add_f32 v[206:207], v[206:207], v[152:153] op_sel_hi:[1,0] neg_lo:[0,1] neg_hi:[0,1]
	v_pk_add_f32 v[208:209], v[208:209], v[152:153] op_sel_hi:[1,0] neg_lo:[0,1] neg_hi:[0,1]
	v_cndmask_b32_e64 v152, 1.0, v153, s[46:47]
	v_pk_mul_f32 v[202:203], v[152:153], v[202:203] op_sel_hi:[0,1]
	v_pk_mul_f32 v[204:205], v[152:153], v[204:205] op_sel_hi:[0,1]
	v_pk_mul_f32 v[206:207], v[152:153], v[206:207] op_sel_hi:[0,1]
	v_pk_mul_f32 v[208:209], v[152:153], v[208:209] op_sel_hi:[0,1]
	v_pk_fma_f32 v[202:203], v[174:175], v[202:203], v[194:195]
	v_pk_fma_f32 v[204:205], v[176:177], v[204:205], v[196:197]
	v_pk_fma_f32 v[206:207], v[188:189], v[206:207], v[198:199]
	v_pk_fma_f32 v[208:209], v[190:191], v[208:209], v[200:201]
	v_pk_fma_f32 v[30:31], v[138:139], v[30:31], v[202:203]
	v_pk_fma_f32 v[32:33], v[138:139], v[32:33], v[204:205]
	v_pk_fma_f32 v[26:27], v[138:139], v[26:27], v[206:207]
	v_pk_fma_f32 v[28:29], v[138:139], v[28:29], v[208:209]
	global_store_dwordx4 v180, v[30:33], s[98:99] offset:512
	global_store_dwordx4 v180, v[26:29], s[98:99] offset:528
	s_waitcnt vmcnt(12)
	v_cndmask_b32_e64 v160, 0, v160, s[46:47]
	v_pk_add_f32 v[210:211], v[210:211], v[160:161] op_sel_hi:[1,0] neg_lo:[0,1] neg_hi:[0,1]
	v_pk_add_f32 v[212:213], v[212:213], v[160:161] op_sel_hi:[1,0] neg_lo:[0,1] neg_hi:[0,1]
	v_pk_add_f32 v[226:227], v[226:227], v[160:161] op_sel_hi:[1,0] neg_lo:[0,1] neg_hi:[0,1]
	v_pk_add_f32 v[228:229], v[228:229], v[160:161] op_sel_hi:[1,0] neg_lo:[0,1] neg_hi:[0,1]
	v_cndmask_b32_e64 v160, 1.0, v161, s[46:47]
	v_pk_mul_f32 v[210:211], v[160:161], v[210:211] op_sel_hi:[0,1]
	v_pk_mul_f32 v[212:213], v[160:161], v[212:213] op_sel_hi:[0,1]
	v_pk_mul_f32 v[226:227], v[160:161], v[226:227] op_sel_hi:[0,1]
	v_pk_mul_f32 v[228:229], v[160:161], v[228:229] op_sel_hi:[0,1]
	v_pk_fma_f32 v[210:211], v[174:175], v[210:211], v[194:195]
	v_pk_fma_f32 v[212:213], v[176:177], v[212:213], v[196:197]
	v_pk_fma_f32 v[226:227], v[188:189], v[226:227], v[198:199]
	v_pk_fma_f32 v[228:229], v[190:191], v[228:229], v[200:201]
	v_pk_fma_f32 v[22:23], v[138:139], v[22:23], v[210:211]
	v_pk_fma_f32 v[24:25], v[138:139], v[24:25], v[212:213]
	v_pk_fma_f32 v[18:19], v[138:139], v[18:19], v[226:227]
	v_pk_fma_f32 v[20:21], v[138:139], v[20:21], v[228:229]
	global_store_dwordx4 v182, v[22:25], s[98:99] offset:512
	global_store_dwordx4 v182, v[18:21], s[98:99] offset:528
	s_waitcnt vmcnt(9)
	v_cndmask_b32_e64 v216, 0, v216, s[46:47]
	v_pk_add_f32 v[230:231], v[230:231], v[216:217] op_sel_hi:[1,0] neg_lo:[0,1] neg_hi:[0,1]
	v_pk_add_f32 v[232:233], v[232:233], v[216:217] op_sel_hi:[1,0] neg_lo:[0,1] neg_hi:[0,1]
	v_pk_add_f32 v[234:235], v[234:235], v[216:217] op_sel_hi:[1,0] neg_lo:[0,1] neg_hi:[0,1]
	v_pk_add_f32 v[236:237], v[236:237], v[216:217] op_sel_hi:[1,0] neg_lo:[0,1] neg_hi:[0,1]
	v_cndmask_b32_e64 v216, 1.0, v217, s[46:47]
	v_pk_mul_f32 v[230:231], v[216:217], v[230:231] op_sel_hi:[0,1]
	v_pk_mul_f32 v[232:233], v[216:217], v[232:233] op_sel_hi:[0,1]
	v_pk_mul_f32 v[234:235], v[216:217], v[234:235] op_sel_hi:[0,1]
	v_pk_mul_f32 v[236:237], v[216:217], v[236:237] op_sel_hi:[0,1]
	v_pk_fma_f32 v[230:231], v[174:175], v[230:231], v[194:195]
	v_pk_fma_f32 v[232:233], v[176:177], v[232:233], v[196:197]
	v_pk_fma_f32 v[234:235], v[188:189], v[234:235], v[198:199]
	v_pk_fma_f32 v[236:237], v[190:191], v[236:237], v[200:201]
	v_pk_fma_f32 v[14:15], v[138:139], v[14:15], v[230:231]
	v_pk_fma_f32 v[16:17], v[138:139], v[16:17], v[232:233]
	v_pk_fma_f32 v[10:11], v[138:139], v[10:11], v[234:235]
	v_pk_fma_f32 v[12:13], v[138:139], v[12:13], v[236:237]
	global_store_dwordx4 v183, v[14:17], s[98:99] offset:512
	global_store_dwordx4 v183, v[10:13], s[98:99] offset:528
	s_waitcnt vmcnt(6)
	v_cndmask_b32_e64 v246, 0, v246, s[46:47]
	v_pk_add_f32 v[238:239], v[238:239], v[246:247] op_sel_hi:[1,0] neg_lo:[0,1] neg_hi:[0,1]
	v_pk_add_f32 v[240:241], v[240:241], v[246:247] op_sel_hi:[1,0] neg_lo:[0,1] neg_hi:[0,1]
	v_pk_add_f32 v[242:243], v[242:243], v[246:247] op_sel_hi:[1,0] neg_lo:[0,1] neg_hi:[0,1]
	v_pk_add_f32 v[244:245], v[244:245], v[246:247] op_sel_hi:[1,0] neg_lo:[0,1] neg_hi:[0,1]
	v_cndmask_b32_e64 v246, 1.0, v247, s[46:47]
	v_pk_mul_f32 v[238:239], v[246:247], v[238:239] op_sel_hi:[0,1]
	v_pk_mul_f32 v[240:241], v[246:247], v[240:241] op_sel_hi:[0,1]
	v_pk_mul_f32 v[242:243], v[246:247], v[242:243] op_sel_hi:[0,1]
	v_pk_mul_f32 v[244:245], v[246:247], v[244:245] op_sel_hi:[0,1]
	v_pk_fma_f32 v[238:239], v[174:175], v[238:239], v[194:195]
	v_pk_fma_f32 v[240:241], v[176:177], v[240:241], v[196:197]
	v_pk_fma_f32 v[242:243], v[188:189], v[242:243], v[198:199]
	v_pk_fma_f32 v[244:245], v[190:191], v[244:245], v[200:201]
	v_pk_fma_f32 v[6:7], v[138:139], v[6:7], v[238:239]
	v_pk_fma_f32 v[8:9], v[138:139], v[8:9], v[240:241]
	v_pk_fma_f32 v[2:3], v[138:139], v[2:3], v[242:243]
	v_pk_fma_f32 v[4:5], v[138:139], v[4:5], v[244:245]
	global_store_dwordx4 v184, v[6:9], s[98:99] offset:512
	global_store_dwordx4 v184, v[2:5], s[98:99] offset:528
	s_and_b64 vcc, exec, s[38:39]
	s_mov_b64 s[6:7], -1
	s_cbranch_vccnz .LBB0_805
	s_andn2_b64 vcc, exec, s[26:27]
	s_cbranch_vccnz .LBB0_804
	s_barrier
	s_branch .LBB0_804

; __global__ void __launch_bounds__(NT, 2) mk_fwd(Params P) {
;     __shared__ __attribute__((aligned(16))) unsigned char lds_raw[LDS_BYTES];
	.amdhsa_kernel _ZN2mk6mk_fwdENS_6ParamsE
		.amdhsa_group_segment_fixed_size 147456
		.amdhsa_private_segment_fixed_size 0
		.amdhsa_kernarg_size 488
		.amdhsa_user_sgpr_count 2
		.amdhsa_user_sgpr_dispatch_ptr 0
		.amdhsa_user_sgpr_queue_ptr 0
		.amdhsa_user_sgpr_kernarg_segment_ptr 1
		.amdhsa_user_sgpr_dispatch_id 0
		.amdhsa_user_sgpr_kernarg_preload_length 0
		.amdhsa_user_sgpr_kernarg_preload_offset 0
		.amdhsa_user_sgpr_private_segment_size 0
		.amdhsa_uses_dynamic_stack 0
		.amdhsa_enable_private_segment 0
		.amdhsa_system_sgpr_workgroup_id_x 1
		.amdhsa_system_sgpr_workgroup_id_y 0
		.amdhsa_system_sgpr_workgroup_id_z 0
		.amdhsa_system_sgpr_workgroup_info 0
		.amdhsa_system_vgpr_workitem_id 2
		.amdhsa_next_free_vgpr 256
		.amdhsa_next_free_sgpr 100
		.amdhsa_accum_offset 256
		.amdhsa_reserve_vcc 1
		.amdhsa_float_round_mode_32 0
		.amdhsa_float_round_mode_16_64 0
		.amdhsa_float_denorm_mode_32 3
		.amdhsa_float_denorm_mode_16_64 3
		.amdhsa_dx10_clamp 1
		.amdhsa_ieee_mode 1
		.amdhsa_fp16_overflow 0
		.amdhsa_tg_split 0
		.amdhsa_exception_fp_ieee_invalid_op 0
		.amdhsa_exception_fp_denorm_src 0
		.amdhsa_exception_fp_ieee_div_zero 0
		.amdhsa_exception_fp_ieee_overflow 0
		.amdhsa_exception_fp_ieee_underflow 0
		.amdhsa_exception_fp_ieee_inexact 0
		.amdhsa_exception_int_div_zero 0
	.end_amdhsa_kernel

; __global__ void __launch_bounds__(NT, 2) mk_fwd(Params P) {
;     __shared__ __attribute__((aligned(16))) unsigned char lds_raw[LDS_BYTES];
amdhsa.kernels:
  - .agpr_count:     0
    .args:
      - .offset:         0
        .size:           232
        .value_kind:     by_value
      - .offset:         232
        .size:           4
        .value_kind:     hidden_block_count_x
      - .offset:         236
        .size:           4
        .value_kind:     hidden_block_count_y
      - .offset:         240
        .size:           4
        .value_kind:     hidden_block_count_z
      - .offset:         244
        .size:           2
        .value_kind:     hidden_group_size_x
      - .offset:         246
        .size:           2
        .value_kind:     hidden_group_size_y
      - .offset:         248
        .size:           2
        .value_kind:     hidden_group_size_z
      - .offset:         250
        .size:           2
        .value_kind:     hidden_remainder_x
      - .offset:         252
        .size:           2
        .value_kind:     hidden_remainder_y
      - .offset:         254
        .size:           2
        .value_kind:     hidden_remainder_z
      - .offset:         272
        .size:           8
        .value_kind:     hidden_global_offset_x
      - .offset:         280
        .size:           8
        .value_kind:     hidden_global_offset_y
      - .offset:         288
        .size:           8
        .value_kind:     hidden_global_offset_z
      - .offset:         296
        .size:           2
        .value_kind:     hidden_grid_dims
      - .offset:         320
        .size:           8
        .value_kind:     hidden_multigrid_sync_arg
    .group_segment_fixed_size: 147456
    .kernarg_segment_align: 8
    .kernarg_segment_size: 488
    .language:       OpenCL C
    .language_version:
      - 2
      - 0
    .max_flat_workgroup_size: 512
    .name:           _ZN2mk6mk_fwdENS_6ParamsE
    .private_segment_fixed_size: 0
    .sgpr_count:     106
    .sgpr_spill_count: 261
    .symbol:         _ZN2mk6mk_fwdENS_6ParamsE.kd
    .uniform_work_group_size: 1
    .uses_dynamic_stack: false
    .vgpr_count:     256
    .vgpr_spill_count: 0
    .wavefront_size: 64
